# P10: cross-lane max via permlane16/32 swap instead of ds_bpermute; hierarchical u/v grid barrier; next-item q-fragment prefetch in P10
# speedup vs baseline: 1.1461x; 1.0053x over previous
; DI void peer_topk_wave(const Params& p, int item, unsigned* lds  ) {
;   const int lane = threadIdx.x & 63, r = lane & 15, kg = lane >> 4;
;   const int h = item & 7, row0 = (item >> 3) * 16;
;   unsigned win[2][16];
; #pragma unroll
;   for (int pp = 0; pp < 2; ++pp) {
;     bf16x8 qf[4];
; #pragma unroll
;     for (int ks = 0; ks < 4; ++ks) qf[ks] = *(const bf16x8*)&p.pq[(size_t)(row0 + r) * 2048 + h * 256 + pp * 128 + ks * 32 + kg * 8];
;     unsigned kk[32];
;     const u16* sk = p.subkb + (size_t)(h * 2 + pp) * 16384;
; #pragma unroll
;     ...
;   CAND(0, 0, 0, 0, 13, 2, 0, 6, 1)
;   CAND(1, 0, 1, 0, 14, 2, 1, 7, 0)
;   CAND(2, 0, 2, 0, 15, 2, 2, 7, 1)
;   CAND(3, 0, 3, 1, 0, 2, 3, 8, 0)
;   CAND(4, 0, 4, 1, 1, 2, 4, 9, 0)
;   CAND(5, 0, 5, 1, 2, 3, 0, 10, 0)
;   CAND(6, 0, 6, 1, 3, 3, 1, 11, 0)
;   CAND(7, 0, 7, 1, 4, 3, 2, 12, 0)
;   CAND(8, 0, 8, 1, 5, 3, 3, 13, 0)
;   CAND(9, 0, 9, 1, 6, 4, 2, 14, 0)
;   CAND(10, 0, 10, 1, 7, 5, 0, 15, 0)
;   CAND(11, 0, 11, 4, 0, 5, 1, -1, -1)
;   CAND(12, 0, 12, 4, 1, 6, 0, -1, -1)
.LBB0_1087:
	s_or_b64 exec, exec, s[2:3]
	s_movk_i32 s0, 0x4040
	v_cmp_gt_i32_e32 vcc, s0, v163
	s_waitcnt lgkmcnt(0)
	s_barrier
	s_and_saveexec_b64 s[72:73], vcc
	s_cbranch_execz .LBB0_1304
	v_mov_b32_e32 v3, 0x61
	v_cmp_eq_u32_e64 s[10:11], 2, v175
	v_mov_b32_e32 v5, 0x42
	v_lshlrev_b32_e32 v1, 7, v134
	v_cndmask_b32_e64 v97, v3, 32, s[10:11]
	v_mov_b32_e32 v3, 0x70
	v_cndmask_b32_e64 v98, v3, 33, s[10:11]
	v_mov_b32_e32 v3, 0x71
	v_cndmask_b32_e64 v99, v3, 34, s[10:11]
	v_mov_b32_e32 v3, 0x80
	v_cndmask_b32_e64 v100, v3, 35, s[10:11]
	v_mov_b32_e32 v3, 0x90
	v_cndmask_b32_e64 v101, v3, 36, s[10:11]
	v_mov_b32_e32 v3, 0xa0
	v_cndmask_b32_e64 v102, v3, 48, s[10:11]
	v_mov_b32_e32 v3, 0xb0
	v_cndmask_b32_e64 v103, v3, 49, s[10:11]
	v_mov_b32_e32 v3, 0xc0
	v_cndmask_b32_e64 v104, v3, 50, s[10:11]
	v_mov_b32_e32 v3, 0xd0
	v_cndmask_b32_e64 v105, v3, 51, s[10:11]
	v_mov_b32_e32 v3, 0xe0
	v_cndmask_b32_e64 v106, v3, v5, s[10:11]
	v_mov_b32_e32 v3, 0xf0
	v_mov_b32_e32 v5, 0x50
	v_cndmask_b32_e64 v107, v3, v5, s[10:11]
	v_mov_b32_e32 v3, 0x51
	v_cndmask_b32_e64 v108, 0, v3, s[10:11]
	v_mov_b32_e32 v3, 0x60
	v_cndmask_b32_e64 v109, 0, v3, s[10:11]
	v_lshlrev_b32_e32 v3, 11, v174
	v_add_u32_e32 v110, v3, v1
	v_and_b32_e32 v3, 64, v128
	v_or_b32_e32 v0, v171, v1
	v_xor_b32_e32 v1, 16, v128
	v_add_u32_e32 v3, 64, v3
	v_cmp_lt_i32_e32 vcc, v1, v3
	v_mov_b32_e32 v17, 0
	v_or_b32_e32 v2, 32, v0
	v_cndmask_b32_e32 v1, v128, v1, vcc
	v_lshlrev_b32_e32 v111, 2, v1
	v_xor_b32_e32 v1, 32, v128
	v_cmp_lt_i32_e32 vcc, v1, v3
	v_or_b32_e32 v4, 64, v0
	v_or_b32_e32 v6, 0x60, v0
	v_cndmask_b32_e32 v1, v128, v1, vcc
	v_or_b32_e32 v8, 0x800, v0
	v_or_b32_e32 v10, 0x820, v0
	v_or_b32_e32 v12, 0x840, v0
	v_or_b32_e32 v14, 0x860, v0
	v_or_b32_e32 v16, 0x1000, v0
	v_or_b32_e32 v32, 0x1020, v0
	v_or_b32_e32 v34, 0x1040, v0
	v_or_b32_e32 v36, 0x1060, v0
	v_or_b32_e32 v38, 0x1800, v0
	v_or_b32_e32 v40, 0x1820, v0
	v_or_b32_e32 v42, 0x1840, v0
	v_or_b32_e32 v44, 0x1860, v0
	v_or_b32_e32 v46, 0x2000, v0
	v_or_b32_e32 v48, 0x2020, v0
	v_or_b32_e32 v50, 0x2040, v0
	v_or_b32_e32 v52, 0x2060, v0
	v_or_b32_e32 v54, 0x2800, v0
	v_or_b32_e32 v56, 0x2820, v0
	v_or_b32_e32 v58, 0x2840, v0
	v_or_b32_e32 v60, 0x2860, v0
	v_or_b32_e32 v62, 0x3000, v0
	v_or_b32_e32 v64, 0x3020, v0
	v_or_b32_e32 v66, 0x3040, v0
	v_or_b32_e32 v68, 0x3060, v0
	v_or_b32_e32 v70, 0x3800, v0
	v_or_b32_e32 v72, 0x3820, v0
	v_or_b32_e32 v74, 0x3840, v0
	v_or_b32_e32 v76, 0x3860, v0
	v_lshlrev_b32_e32 v112, 2, v1
	v_lshlrev_b32_e32 v1, 1, v174
	v_or_b32_e32 v90, 16, v170
	v_or_b32_e32 v91, 32, v170
	v_or_b32_e32 v92, 48, v170
	v_or_b32_e32 v93, 64, v170
	v_or_b32_e32 v94, 0x50, v170
	v_or_b32_e32 v95, 0x60, v170
	v_or_b32_e32 v96, 0x70, v170
	v_cmp_gt_u32_e64 s[4:5], 2, v175
	v_cmp_eq_u32_e64 s[12:13], 3, v175
	v_or_b32_e32 v113, 1, v170
	v_or_b32_e32 v114, 2, v170
	v_or_b32_e32 v115, 3, v170
	v_or_b32_e32 v116, 17, v170
	v_or_b32_e32 v117, 18, v170
	v_or_b32_e32 v118, 19, v170
	v_or_b32_e32 v119, 33, v170
	v_or_b32_e32 v120, 34, v170
	v_or_b32_e32 v121, 35, v170
	v_or_b32_e32 v122, 49, v170
	v_or_b32_e32 v123, 50, v170
	v_or_b32_e32 v124, 51, v170
	v_or_b32_e32 v125, 0x41, v170
	v_or_b32_e32 v126, 0x42, v170
	v_or_b32_e32 v127, 0x43, v170
	v_or_b32_e32 v129, 0x51, v170
	v_or_b32_e32 v130, 0x52, v170
	v_or_b32_e32 v131, 0x53, v170
	v_or_b32_e32 v135, 0x61, v170
	v_or_b32_e32 v136, 0x62, v170
	v_or_b32_e32 v137, 0x63, v170
	v_or_b32_e32 v138, 0x71, v170
	v_or_b32_e32 v139, 0x72, v170
	v_or_b32_e32 v140, 0x73, v170
	v_lshl_add_u32 v141, s86, 3, v1
	s_lshl_b32 s79, s84, 3
	s_mov_b64 s[74:75], 0
	s_mov_b32 s88, 0
	s_mov_b64 s[90:91], 0x1000000
	v_mov_b32_e32 v142, 0x10178
	v_lshlrev_b32_e32 v18, 1, v171
	v_mov_b32_e32 v19, v17
	v_mov_b32_e32 v143, 0x10110
	v_lshlrev_b32_e32 v20, 1, v0
	v_mov_b32_e32 v21, v17
	s_movk_i32 s80, 0xff80
	v_lshlrev_b32_e32 v22, 1, v8
	v_mov_b32_e32 v23, v17
	v_lshlrev_b32_e32 v24, 1, v10
	v_mov_b32_e32 v25, v17
	v_lshlrev_b32_e32 v26, 1, v12
	v_mov_b32_e32 v27, v17
	v_lshlrev_b32_e32 v28, 1, v14
	v_mov_b32_e32 v29, v17
	v_lshlrev_b32_e32 v30, 1, v16
	v_mov_b32_e32 v31, v17
	v_lshlrev_b32_e32 v32, 1, v32
	v_mov_b32_e32 v33, v17
	v_lshlrev_b32_e32 v34, 1, v34
	v_mov_b32_e32 v35, v17
	v_lshlrev_b32_e32 v36, 1, v36
	v_mov_b32_e32 v37, v17
	v_lshlrev_b32_e32 v38, 1, v38
	v_mov_b32_e32 v39, v17
	v_lshlrev_b32_e32 v40, 1, v40
	v_mov_b32_e32 v41, v17
	v_lshlrev_b32_e32 v42, 1, v42
	v_mov_b32_e32 v43, v17
	v_lshlrev_b32_e32 v44, 1, v44
	v_mov_b32_e32 v45, v17
	v_lshlrev_b32_e32 v46, 1, v46
	v_mov_b32_e32 v47, v17
	v_lshlrev_b32_e32 v48, 1, v48
	v_mov_b32_e32 v49, v17
	v_lshlrev_b32_e32 v50, 1, v50
	v_mov_b32_e32 v51, v17
	v_lshlrev_b32_e32 v52, 1, v52
	v_mov_b32_e32 v53, v17
	v_lshlrev_b32_e32 v54, 1, v54
	v_mov_b32_e32 v55, v17
	v_lshlrev_b32_e32 v56, 1, v56
	v_mov_b32_e32 v57, v17
	v_lshlrev_b32_e32 v58, 1, v58
	v_mov_b32_e32 v59, v17
	v_lshlrev_b32_e32 v60, 1, v60
	v_mov_b32_e32 v61, v17
	v_lshlrev_b32_e32 v62, 1, v62
	v_mov_b32_e32 v63, v17
	v_lshlrev_b32_e32 v64, 1, v64
	v_mov_b32_e32 v65, v17
	v_lshlrev_b32_e32 v66, 1, v66
	v_mov_b32_e32 v67, v17
	v_lshlrev_b32_e32 v68, 1, v68
	v_mov_b32_e32 v69, v17
	v_lshlrev_b32_e32 v70, 1, v70
	v_mov_b32_e32 v71, v17
	v_lshlrev_b32_e32 v72, 1, v72
	v_mov_b32_e32 v73, v17
	v_lshlrev_b32_e32 v74, 1, v74
	v_mov_b32_e32 v75, v17
	v_lshlrev_b32_e32 v76, 1, v76
	v_mov_b32_e32 v77, v17
	s_mov_b64 s[76:77], 0x8000
	v_lshlrev_b32_e32 v78, 1, v2
	v_mov_b32_e32 v79, v17
	v_lshlrev_b32_e32 v80, 1, v4
	v_mov_b32_e32 v81, v17
	v_lshlrev_b32_e32 v82, 1, v6
	v_mov_b32_e32 v83, v17
	s_movk_i32 s81, 0x7f
	s_movk_i32 s82, 0xff00
	s_movk_i32 s83, 0xff
	v_mov_b32_e32 v144, 0x101b0
	s_movk_i32 s86, 0x403f
	v_mov_b32_e32 v145, v163
	s_branch .LBB0_1091

; #define MFMA(a, b, c) __builtin_amdgcn_mfma_f32_16x16x32_bf16((a), (b), (c), 0, 0, 0)
; DI unsigned ordf(float f) { unsigned u = __float_as_uint(f); return (u & 0x80000000u) ? ~u : (u | 0x80000000u); }
; DI void peer_topk_wave(const Params& p, int item, unsigned* lds  ) {
;     ...
;   for (int pp = 0; pp < 2; ++pp) {
;     bf16x8 qf[4];
; #pragma unroll
;     for (int ks = 0; ks < 4; ++ks) qf[ks] = *(const bf16x8*)&p.pq[(size_t)(row0 + r) * 2048 + h * 256 + pp * 128 + ks * 32 + kg * 8];
;     unsigned kk[32];
;     const u16* sk = p.subkb + (size_t)(h * 2 + pp) * 16384;
; #pragma unroll
;     for (int mt = 0; mt < 8; ++mt) {
;       f32x4 a = (f32x4){0.f, 0.f, 0.f, 0.f};
; #pragma unroll
;       for (int ks = 0; ks < 4; ++ks) {
;         bf16x8 kf = *(const bf16x8*)&sk[(mt * 16 + r) * 128 + ks * 32 + kg * 8];
;         a = MFMA(kf, qf[ks], a);
;       }
; #pragma unroll
;       for (int j = 0; j < 4; ++j) kk[mt * 4 + j] = (ordf(a[j]) & ~127u) | (unsigned)(mt * 16 + kg * 4 + j);
.LBB0_1091:
	ds_read_b64 v[0:1], v142
	ds_read_b64 v[86:87], v143
	v_and_or_b32 v84, v141, -16, v134
	v_ashrrev_i32_e32 v85, 31, v84
	v_and_b32_e32 v146, 7, v145
	v_lshlrev_b64 v[2:3], 12, v[84:85]
	s_waitcnt lgkmcnt(0)
	v_lshl_add_u64 v[0:1], v[0:1], 0, v[2:3]
	v_lshlrev_b32_e32 v16, 9, v146
	v_lshl_add_u64 v[0:1], v[0:1], 0, v[16:17]
	v_lshlrev_b32_e32 v16, 16, v146
	v_lshl_add_u64 v[86:87], v[86:87], 0, v[16:17]
	v_lshl_add_u64 v[88:89], v[0:1], 0, v[18:19]
	v_lshl_add_u64 v[156:157], v[86:87], 0, v[20:21]
	s_cmp_lg_u32 s88, 0
	s_cbranch_scc1 .Lp10q_mov0
	flat_load_dwordx4 v[12:15], v[88:89]
	flat_load_dwordx4 v[8:11], v[88:89] offset:64
	flat_load_dwordx4 v[4:7], v[88:89] offset:128
	flat_load_dwordx4 v[0:3], v[88:89] offset:192
	s_branch .Lp10q_done0
.Lp10q_mov0:
	v_mov_b32_e32 v12, v204
	v_mov_b32_e32 v13, v205
	v_mov_b32_e32 v14, v206
	v_mov_b32_e32 v15, v207
	v_mov_b32_e32 v8, v208
	v_mov_b32_e32 v9, v209
	v_mov_b32_e32 v10, v210
	v_mov_b32_e32 v11, v211
	v_mov_b32_e32 v4, v212
	v_mov_b32_e32 v5, v213
	v_mov_b32_e32 v6, v214
	v_mov_b32_e32 v7, v215
	v_mov_b32_e32 v0, v216
	v_mov_b32_e32 v1, v217
	v_mov_b32_e32 v2, v218
	v_mov_b32_e32 v3, v219
.Lp10q_done0:
	v_readfirstlane_b32 s0, v86
	v_readfirstlane_b32 s1, v87
	s_nop 3
	s_add_u32 s2, s0, 0x0
	s_addc_u32 s3, s1, 0
	global_load_dwordx4 v[24:27], v20, s[2:3]
	global_load_dwordx4 v[28:31], v20, s[2:3] offset:64
	global_load_dwordx4 v[32:35], v20, s[2:3] offset:128
	global_load_dwordx4 v[36:39], v20, s[2:3] offset:192
	s_add_u32 s2, s0, 0x1000
	s_addc_u32 s3, s1, 0
	global_load_dwordx4 v[40:43], v20, s[2:3]
	global_load_dwordx4 v[44:47], v20, s[2:3] offset:64
	global_load_dwordx4 v[48:51], v20, s[2:3] offset:128
	global_load_dwordx4 v[52:55], v20, s[2:3] offset:192
	s_add_u32 s2, s0, 0x2000
	s_addc_u32 s3, s1, 0
	global_load_dwordx4 v[56:59], v20, s[2:3]
	global_load_dwordx4 v[60:63], v20, s[2:3] offset:64
	global_load_dwordx4 v[64:67], v20, s[2:3] offset:128
	global_load_dwordx4 v[68:71], v20, s[2:3] offset:192
	s_add_u32 s2, s0, 0x3000
	s_addc_u32 s3, s1, 0
	global_load_dwordx4 v[72:75], v20, s[2:3]
	global_load_dwordx4 v[76:79], v20, s[2:3] offset:64
	global_load_dwordx4 v[80:83], v20, s[2:3] offset:128
	s_waitcnt vmcnt(11) lgkmcnt(0)
	v_mfma_f32_16x16x32_bf16 v[190:193], v[24:27], v[12:15], 0
	v_mfma_f32_16x16x32_bf16 v[190:193], v[28:31], v[8:11], v[190:193]
	v_mfma_f32_16x16x32_bf16 v[190:193], v[32:35], v[4:7], v[190:193]
	v_mfma_f32_16x16x32_bf16 v[190:193], v[36:39], v[0:3], v[190:193]
	global_load_dwordx4 v[24:27], v20, s[2:3] offset:192
	s_add_u32 s2, s0, 0x4000
	s_addc_u32 s3, s1, 0
	global_load_dwordx4 v[28:31], v20, s[2:3]
	global_load_dwordx4 v[32:35], v20, s[2:3] offset:64
	global_load_dwordx4 v[36:39], v20, s[2:3] offset:128
	s_waitcnt vmcnt(11)
	v_mfma_f32_16x16x32_bf16 v[198:201], v[40:43], v[12:15], 0
	v_mfma_f32_16x16x32_bf16 v[198:201], v[44:47], v[8:11], v[198:201]
	v_mfma_f32_16x16x32_bf16 v[198:201], v[48:51], v[4:7], v[198:201]
	v_mfma_f32_16x16x32_bf16 v[198:201], v[52:55], v[0:3], v[198:201]
	global_load_dwordx4 v[40:43], v20, s[2:3] offset:192
	s_add_u32 s2, s0, 0x5000
	s_addc_u32 s3, s1, 0
	global_load_dwordx4 v[44:47], v20, s[2:3]
	global_load_dwordx4 v[48:51], v20, s[2:3] offset:64
	global_load_dwordx4 v[52:55], v20, s[2:3] offset:128
	s_nop 7
	s_nop 3
	v_ashrrev_i32_e32 v197, 31, v190
	v_or_b32_e32 v197, 0x80000000, v197
	v_xor_b32_e32 v197, v190, v197
	v_and_or_b32 v147, v197, s80, v170
	v_ashrrev_i32_e32 v202, 31, v191
	v_or_b32_e32 v202, 0x80000000, v202
	v_xor_b32_e32 v202, v191, v202
	v_and_or_b32 v148, v202, s80, v113
	v_ashrrev_i32_e32 v197, 31, v192
	v_or_b32_e32 v197, 0x80000000, v197
	v_xor_b32_e32 v197, v192, v197
	v_and_or_b32 v149, v197, s80, v114
	v_ashrrev_i32_e32 v202, 31, v193
	v_or_b32_e32 v202, 0x80000000, v202
	v_xor_b32_e32 v202, v193, v202
	v_and_or_b32 v150, v202, s80, v115
	s_waitcnt vmcnt(11)
	v_mfma_f32_16x16x32_bf16 v[190:193], v[56:59], v[12:15], 0
	v_mfma_f32_16x16x32_bf16 v[190:193], v[60:63], v[8:11], v[190:193]
	v_mfma_f32_16x16x32_bf16 v[190:193], v[64:67], v[4:7], v[190:193]
	v_mfma_f32_16x16x32_bf16 v[190:193], v[68:71], v[0:3], v[190:193]
	global_load_dwordx4 v[56:59], v20, s[2:3] offset:192
	s_add_u32 s2, s0, 0x6000
	s_addc_u32 s3, s1, 0
	global_load_dwordx4 v[60:63], v20, s[2:3]
	global_load_dwordx4 v[64:67], v20, s[2:3] offset:64
	global_load_dwordx4 v[68:71], v20, s[2:3] offset:128
	s_nop 7
	s_nop 3
	v_ashrrev_i32_e32 v197, 31, v198
	v_or_b32_e32 v197, 0x80000000, v197
	v_xor_b32_e32 v197, v198, v197
	v_and_or_b32 v151, v197, s80, v90
	v_ashrrev_i32_e32 v202, 31, v199
	v_or_b32_e32 v202, 0x80000000, v202
	v_xor_b32_e32 v202, v199, v202
	v_and_or_b32 v152, v202, s80, v116
	v_ashrrev_i32_e32 v197, 31, v200
	v_or_b32_e32 v197, 0x80000000, v197
	v_xor_b32_e32 v197, v200, v197
	v_and_or_b32 v153, v197, s80, v117
	v_ashrrev_i32_e32 v202, 31, v201
	v_or_b32_e32 v202, 0x80000000, v202
	v_xor_b32_e32 v202, v201, v202
	v_and_or_b32 v154, v202, s80, v118
	s_waitcnt vmcnt(11)
	v_mfma_f32_16x16x32_bf16 v[198:201], v[72:75], v[12:15], 0
	v_mfma_f32_16x16x32_bf16 v[198:201], v[76:79], v[8:11], v[198:201]
	v_mfma_f32_16x16x32_bf16 v[198:201], v[80:83], v[4:7], v[198:201]
	v_mfma_f32_16x16x32_bf16 v[198:201], v[24:27], v[0:3], v[198:201]
	global_load_dwordx4 v[72:75], v20, s[2:3] offset:192
	s_add_u32 s2, s0, 0x7000
	s_addc_u32 s3, s1, 0
	global_load_dwordx4 v[76:79], v20, s[2:3]
	global_load_dwordx4 v[80:83], v20, s[2:3] offset:64
	global_load_dwordx4 v[24:27], v20, s[2:3] offset:128
	s_nop 7
	s_nop 3
	v_ashrrev_i32_e32 v197, 31, v190
	v_or_b32_e32 v197, 0x80000000, v197
	v_xor_b32_e32 v197, v190, v197
	v_and_or_b32 v155, v197, s80, v91
	v_ashrrev_i32_e32 v202, 31, v191
	v_or_b32_e32 v202, 0x80000000, v202
	v_xor_b32_e32 v202, v191, v202
	v_and_or_b32 v156, v202, s80, v119
	v_ashrrev_i32_e32 v197, 31, v192
	v_or_b32_e32 v197, 0x80000000, v197
	v_xor_b32_e32 v197, v192, v197
	v_and_or_b32 v157, v197, s80, v120
	v_ashrrev_i32_e32 v202, 31, v193
	v_or_b32_e32 v202, 0x80000000, v202
	v_xor_b32_e32 v202, v193, v202
	v_and_or_b32 v158, v202, s80, v121
	s_waitcnt vmcnt(11)
; #define MFMA(a, b, c) __builtin_amdgcn_mfma_f32_16x16x32_bf16((a), (b), (c), 0, 0, 0)
; DI unsigned ordf(float f) { unsigned u = __float_as_uint(f); return (u & 0x80000000u) ? ~u : (u | 0x80000000u); }
; DI void peer_topk_wave(const Params& p, int item, unsigned* lds  ) {
;     ...
;     for (int mt = 0; mt < 8; ++mt) {
;       f32x4 a = (f32x4){0.f, 0.f, 0.f, 0.f};
; #pragma unroll
;       for (int ks = 0; ks < 4; ++ks) {
;         bf16x8 kf = *(const bf16x8*)&sk[(mt * 16 + r) * 128 + ks * 32 + kg * 8];
;         a = MFMA(kf, qf[ks], a);
;       }
; #pragma unroll
;       for (int j = 0; j < 4; ++j) kk[mt * 4 + j] = (ordf(a[j]) & ~127u) | (unsigned)(mt * 16 + kg * 4 + j);
;     }
; #pragma unroll
;     for (int rr = 0; rr < 16; ++rr) {
;       unsigned m = 0;
; #pragma unroll
;       for (int i = 0; i < 32; ++i) m = umax(m, kk[i]);
;       m = umax(m, (unsigned)__shfl_xor((int)m, 16));
;       m = umax(m, (unsigned)__shfl_xor((int)m, 32));
	v_mfma_f32_16x16x32_bf16 v[190:193], v[28:31], v[12:15], 0
	v_mfma_f32_16x16x32_bf16 v[190:193], v[32:35], v[8:11], v[190:193]
	v_mfma_f32_16x16x32_bf16 v[190:193], v[36:39], v[4:7], v[190:193]
	v_mfma_f32_16x16x32_bf16 v[190:193], v[40:43], v[0:3], v[190:193]
	global_load_dwordx4 v[28:31], v20, s[2:3] offset:192
	s_nop 7
	s_nop 3
	v_ashrrev_i32_e32 v197, 31, v198
	v_or_b32_e32 v197, 0x80000000, v197
	v_xor_b32_e32 v197, v198, v197
	v_and_or_b32 v159, v197, s80, v92
	v_ashrrev_i32_e32 v202, 31, v199
	v_or_b32_e32 v202, 0x80000000, v202
	v_xor_b32_e32 v202, v199, v202
	v_and_or_b32 v160, v202, s80, v122
	v_ashrrev_i32_e32 v197, 31, v200
	v_or_b32_e32 v197, 0x80000000, v197
	v_xor_b32_e32 v197, v200, v197
	v_and_or_b32 v161, v197, s80, v123
	v_ashrrev_i32_e32 v202, 31, v201
	v_or_b32_e32 v202, 0x80000000, v202
	v_xor_b32_e32 v202, v201, v202
	v_and_or_b32 v162, v202, s80, v124
	s_waitcnt vmcnt(8)
	v_mfma_f32_16x16x32_bf16 v[198:201], v[44:47], v[12:15], 0
	v_mfma_f32_16x16x32_bf16 v[198:201], v[48:51], v[8:11], v[198:201]
	v_mfma_f32_16x16x32_bf16 v[198:201], v[52:55], v[4:7], v[198:201]
	v_mfma_f32_16x16x32_bf16 v[198:201], v[56:59], v[0:3], v[198:201]
	s_nop 7
	s_nop 3
	v_ashrrev_i32_e32 v197, 31, v190
	v_or_b32_e32 v197, 0x80000000, v197
	v_xor_b32_e32 v197, v190, v197
	v_and_or_b32 v164, v197, s80, v93
	v_ashrrev_i32_e32 v202, 31, v191
	v_or_b32_e32 v202, 0x80000000, v202
	v_xor_b32_e32 v202, v191, v202
	v_and_or_b32 v165, v202, s80, v125
	v_ashrrev_i32_e32 v197, 31, v192
	v_or_b32_e32 v197, 0x80000000, v197
	v_xor_b32_e32 v197, v192, v197
	v_and_or_b32 v166, v197, s80, v126
	v_ashrrev_i32_e32 v202, 31, v193
	v_or_b32_e32 v202, 0x80000000, v202
	v_xor_b32_e32 v202, v193, v202
	v_and_or_b32 v167, v202, s80, v127
	s_waitcnt vmcnt(4)
	v_mfma_f32_16x16x32_bf16 v[190:193], v[60:63], v[12:15], 0
	v_mfma_f32_16x16x32_bf16 v[190:193], v[64:67], v[8:11], v[190:193]
	v_mfma_f32_16x16x32_bf16 v[190:193], v[68:71], v[4:7], v[190:193]
	v_mfma_f32_16x16x32_bf16 v[190:193], v[72:75], v[0:3], v[190:193]
	s_nop 7
	s_nop 3
	v_ashrrev_i32_e32 v197, 31, v198
	v_or_b32_e32 v197, 0x80000000, v197
	v_xor_b32_e32 v197, v198, v197
	v_and_or_b32 v168, v197, s80, v94
	v_ashrrev_i32_e32 v202, 31, v199
	v_or_b32_e32 v202, 0x80000000, v202
	v_xor_b32_e32 v202, v199, v202
	v_and_or_b32 v169, v202, s80, v129
	v_ashrrev_i32_e32 v197, 31, v200
	v_or_b32_e32 v197, 0x80000000, v197
	v_xor_b32_e32 v197, v200, v197
	v_and_or_b32 v171, v197, s80, v130
	v_ashrrev_i32_e32 v202, 31, v201
	v_or_b32_e32 v202, 0x80000000, v202
	v_xor_b32_e32 v202, v201, v202
	v_and_or_b32 v172, v202, s80, v131
	s_waitcnt vmcnt(0)
	v_mfma_f32_16x16x32_bf16 v[198:201], v[76:79], v[12:15], 0
	v_mfma_f32_16x16x32_bf16 v[198:201], v[80:83], v[8:11], v[198:201]
	v_mfma_f32_16x16x32_bf16 v[198:201], v[24:27], v[4:7], v[198:201]
	v_mfma_f32_16x16x32_bf16 v[198:201], v[28:31], v[0:3], v[198:201]
	s_nop 7
	s_nop 3
	v_ashrrev_i32_e32 v197, 31, v190
	v_or_b32_e32 v197, 0x80000000, v197
	v_xor_b32_e32 v197, v190, v197
	v_and_or_b32 v173, v197, s80, v95
	v_ashrrev_i32_e32 v202, 31, v191
	v_or_b32_e32 v202, 0x80000000, v202
	v_xor_b32_e32 v202, v191, v202
	v_and_or_b32 v180, v202, s80, v135
	v_ashrrev_i32_e32 v197, 31, v192
	v_or_b32_e32 v197, 0x80000000, v197
	v_xor_b32_e32 v197, v192, v197
	v_and_or_b32 v181, v197, s80, v136
	v_ashrrev_i32_e32 v202, 31, v193
	v_or_b32_e32 v202, 0x80000000, v202
	v_xor_b32_e32 v202, v193, v202
	v_and_or_b32 v182, v202, s80, v137
	s_nop 7
	s_nop 3
	v_ashrrev_i32_e32 v197, 31, v198
	v_or_b32_e32 v197, 0x80000000, v197
	v_xor_b32_e32 v197, v198, v197
	v_and_or_b32 v0, v197, s80, v96
	v_ashrrev_i32_e32 v202, 31, v199
	v_or_b32_e32 v202, 0x80000000, v202
	v_xor_b32_e32 v202, v199, v202
	v_and_or_b32 v1, v202, s80, v138
	v_ashrrev_i32_e32 v197, 31, v200
	v_or_b32_e32 v197, 0x80000000, v197
	v_xor_b32_e32 v197, v200, v197
	v_and_or_b32 v2, v197, s80, v139
	v_ashrrev_i32_e32 v202, 31, v201
	v_or_b32_e32 v202, 0x80000000, v202
	v_xor_b32_e32 v202, v201, v202
	v_and_or_b32 v3, v202, s80, v140
	v_max_u32_e32 v4, v147, v148
	v_max3_u32 v4, v4, v149, v150
	v_max3_u32 v4, v4, v151, v152
	v_max3_u32 v4, v4, v153, v154
	v_max3_u32 v4, v4, v155, v156
	v_max3_u32 v4, v4, v157, v158
	v_max3_u32 v4, v4, v159, v160
	v_max3_u32 v4, v4, v161, v162
	v_max3_u32 v4, v4, v164, v165
	v_max3_u32 v4, v4, v166, v167
	v_max3_u32 v4, v4, v168, v169
	v_max3_u32 v4, v4, v171, v172
	v_max3_u32 v4, v4, v173, v180
	v_max3_u32 v4, v4, v181, v182
	v_and_or_b32 v3, v3, s80, v140
	v_max3_u32 v4, v4, v0, v1
	v_max3_u32 v4, v4, v2, v3
	v_mov_b32_e32 v5, v4
	s_nop 1
	v_permlane16_swap_b32 v4, v5
	s_nop 1
	s_waitcnt lgkmcnt(0)
	v_max_u32_e32 v4, v4, v5
	v_mov_b32_e32 v5, v4
	s_nop 1
	v_permlane32_swap_b32 v4, v5
	s_nop 1
	s_waitcnt lgkmcnt(0)
; DI void peer_topk_wave(const Params& p, int item, unsigned* lds  ) {
;     ...
; #pragma unroll
;     for (int rr = 0; rr < 16; ++rr) {
;       unsigned m = 0;
; #pragma unroll
;       for (int i = 0; i < 32; ++i) m = umax(m, kk[i]);
;       m = umax(m, (unsigned)__shfl_xor((int)m, 16));
;       m = umax(m, (unsigned)__shfl_xor((int)m, 32));
;       win[pp][rr] = m;
; #pragma unroll
;       for (int i = 0; i < 32; ++i) kk[i] = (kk[i] == m) ? 0u : kk[i];
;     }
	v_max_u32_e32 v16, v4, v5
	v_cmp_ne_u32_e32 vcc, v147, v16
	v_cmp_ne_u32_e64 s[98:99], v148, v16
	v_cmp_ne_u32_e64 s[100:101], v149, v16
	v_cndmask_b32_e32 v4, 0, v147, vcc
	v_cndmask_b32_e64 v5, 0, v148, s[98:99]
	v_max_u32_e32 v147, v4, v5
	v_cndmask_b32_e64 v6, 0, v149, s[100:101]
	v_cmp_ne_u32_e32 vcc, v150, v16
	v_cmp_ne_u32_e64 s[98:99], v151, v16
	v_cmp_ne_u32_e64 s[100:101], v152, v16
	v_cndmask_b32_e32 v7, 0, v150, vcc
	v_max3_u32 v147, v147, v6, v7
	v_cndmask_b32_e64 v8, 0, v151, s[98:99]
	v_cndmask_b32_e64 v9, 0, v152, s[100:101]
	v_cmp_ne_u32_e32 vcc, v153, v16
	v_max3_u32 v147, v147, v8, v9
	v_cmp_ne_u32_e64 s[98:99], v154, v16
	v_cndmask_b32_e32 v10, 0, v153, vcc
	v_cmp_ne_u32_e64 s[100:101], v155, v16
	v_cndmask_b32_e64 v11, 0, v154, s[98:99]
	v_max3_u32 v147, v147, v10, v11
	v_cndmask_b32_e64 v12, 0, v155, s[100:101]
	v_cmp_ne_u32_e32 vcc, v156, v16
	v_cmp_ne_u32_e64 s[98:99], v157, v16
	v_cmp_ne_u32_e64 s[100:101], v158, v16
	v_cndmask_b32_e32 v13, 0, v156, vcc
	v_max3_u32 v147, v147, v12, v13
	v_cndmask_b32_e64 v14, 0, v157, s[98:99]
	v_cndmask_b32_e64 v15, 0, v158, s[100:101]
	v_cmp_ne_u32_e32 vcc, v159, v16
	v_max3_u32 v147, v147, v14, v15
	v_cmp_ne_u32_e64 s[98:99], v160, v16
	v_cndmask_b32_e32 v148, 0, v159, vcc
	v_cmp_ne_u32_e64 s[100:101], v161, v16
	v_cndmask_b32_e64 v149, 0, v160, s[98:99]
	v_max3_u32 v147, v147, v148, v149
	v_cndmask_b32_e64 v150, 0, v161, s[100:101]
	v_cmp_ne_u32_e32 vcc, v162, v16
	v_cmp_ne_u32_e64 s[98:99], v164, v16
	v_cmp_ne_u32_e64 s[100:101], v165, v16
	v_cndmask_b32_e32 v151, 0, v162, vcc
	v_max3_u32 v147, v147, v150, v151
	v_cndmask_b32_e64 v152, 0, v164, s[98:99]
	v_cndmask_b32_e64 v153, 0, v165, s[100:101]
	v_cmp_ne_u32_e32 vcc, v166, v16
	v_max3_u32 v147, v147, v152, v153
	v_cmp_ne_u32_e64 s[98:99], v167, v16
	v_cndmask_b32_e32 v154, 0, v166, vcc
	v_cmp_ne_u32_e64 s[100:101], v168, v16
	v_cndmask_b32_e64 v155, 0, v167, s[98:99]
	v_max3_u32 v147, v147, v154, v155
	v_cndmask_b32_e64 v156, 0, v168, s[100:101]
	v_cmp_ne_u32_e32 vcc, v169, v16
	v_cmp_ne_u32_e64 s[98:99], v171, v16
	v_cmp_ne_u32_e64 s[100:101], v172, v16
	v_cndmask_b32_e32 v157, 0, v169, vcc
	v_max3_u32 v147, v147, v156, v157
	v_cndmask_b32_e64 v158, 0, v171, s[98:99]
	v_cndmask_b32_e64 v159, 0, v172, s[100:101]
	v_cmp_ne_u32_e32 vcc, v173, v16
	v_max3_u32 v147, v147, v158, v159
	v_cmp_ne_u32_e64 s[98:99], v180, v16
	v_cndmask_b32_e32 v160, 0, v173, vcc
	v_cmp_ne_u32_e64 s[100:101], v181, v16
	v_cndmask_b32_e64 v161, 0, v180, s[98:99]
	v_max3_u32 v147, v147, v160, v161
	v_cndmask_b32_e64 v162, 0, v181, s[100:101]
	v_cmp_ne_u32_e32 vcc, v182, v16
	v_cmp_ne_u32_e64 s[98:99], v0, v16
	v_cmp_ne_u32_e64 s[100:101], v1, v16
	v_cndmask_b32_e32 v164, 0, v182, vcc
	v_max3_u32 v147, v147, v162, v164
	v_cndmask_b32_e64 v0, 0, v0, s[98:99]
	v_cndmask_b32_e64 v1, 0, v1, s[100:101]
	v_cmp_ne_u32_e32 vcc, v2, v16
	v_max3_u32 v147, v147, v0, v1
	v_cmp_ne_u32_e64 s[98:99], v3, v16
	v_cndmask_b32_e32 v2, 0, v2, vcc
	s_nop 0
	v_cndmask_b32_e64 v3, 0, v3, s[98:99]
	v_max3_u32 v147, v147, v2, v3
	v_mov_b32_e32 v165, v147
	s_nop 1
	v_permlane16_swap_b32 v147, v165
	s_nop 1
	s_waitcnt lgkmcnt(0)
	v_max_u32_e32 v147, v147, v165
	v_mov_b32_e32 v165, v147
	s_nop 1
	v_permlane32_swap_b32 v147, v165
	s_nop 1
	s_waitcnt lgkmcnt(0)
	v_max_u32_e32 v147, v147, v165
	v_cmp_ne_u32_e32 vcc, v4, v147
	v_cmp_ne_u32_e64 s[98:99], v5, v147
	v_cmp_ne_u32_e64 s[100:101], v6, v147
	v_cndmask_b32_e32 v4, 0, v4, vcc
	v_cndmask_b32_e64 v5, 0, v5, s[98:99]
	v_cndmask_b32_e64 v6, 0, v6, s[100:101]
	v_cmp_ne_u32_e32 vcc, v7, v147
	v_cmp_ne_u32_e64 s[98:99], v8, v147
	v_cmp_ne_u32_e64 s[100:101], v9, v147
	v_cndmask_b32_e32 v7, 0, v7, vcc
	v_cndmask_b32_e64 v8, 0, v8, s[98:99]
	v_cndmask_b32_e64 v9, 0, v9, s[100:101]
	v_cmp_ne_u32_e32 vcc, v10, v147
	v_cmp_ne_u32_e64 s[98:99], v11, v147
	v_cmp_ne_u32_e64 s[100:101], v12, v147
	v_cndmask_b32_e32 v10, 0, v10, vcc
	v_cndmask_b32_e64 v11, 0, v11, s[98:99]
	v_cndmask_b32_e64 v12, 0, v12, s[100:101]
	v_cmp_ne_u32_e32 vcc, v13, v147
	v_cmp_ne_u32_e64 s[98:99], v14, v147
	v_cmp_ne_u32_e64 s[100:101], v15, v147
	v_cndmask_b32_e32 v13, 0, v13, vcc
	v_cndmask_b32_e64 v14, 0, v14, s[98:99]
	v_cndmask_b32_e64 v15, 0, v15, s[100:101]
	v_cmp_ne_u32_e32 vcc, v148, v147
	v_cmp_ne_u32_e64 s[98:99], v149, v147
	v_cmp_ne_u32_e64 s[100:101], v150, v147
	v_cndmask_b32_e32 v165, 0, v148, vcc
	v_max_u32_e32 v148, v4, v5
	v_max3_u32 v148, v148, v6, v7
	v_cndmask_b32_e64 v149, 0, v149, s[98:99]
	v_max3_u32 v148, v148, v8, v9
	v_max3_u32 v148, v148, v10, v11
	v_cndmask_b32_e64 v150, 0, v150, s[100:101]
	v_cmp_ne_u32_e32 vcc, v151, v147
	v_max3_u32 v148, v148, v12, v13
	v_max3_u32 v148, v148, v14, v15
	v_cndmask_b32_e32 v151, 0, v151, vcc
	v_cmp_ne_u32_e64 s[98:99], v152, v147
	v_max3_u32 v148, v148, v165, v149
	v_max3_u32 v148, v148, v150, v151
	v_cndmask_b32_e64 v152, 0, v152, s[98:99]
	v_cmp_ne_u32_e64 s[100:101], v153, v147
	v_cmp_ne_u32_e32 vcc, v154, v147
	v_cmp_ne_u32_e64 s[98:99], v155, v147
	v_cndmask_b32_e64 v153, 0, v153, s[100:101]
	v_max3_u32 v148, v148, v152, v153
	v_cndmask_b32_e32 v154, 0, v154, vcc
	v_cndmask_b32_e64 v155, 0, v155, s[98:99]
	v_cmp_ne_u32_e64 s[100:101], v156, v147
	v_max3_u32 v148, v148, v154, v155
	v_cmp_ne_u32_e32 vcc, v157, v147
	v_cndmask_b32_e64 v156, 0, v156, s[100:101]
	v_cmp_ne_u32_e64 s[98:99], v158, v147
	v_cndmask_b32_e32 v157, 0, v157, vcc
	v_max3_u32 v148, v148, v156, v157
	v_cndmask_b32_e64 v158, 0, v158, s[98:99]
	v_cmp_ne_u32_e64 s[100:101], v159, v147
	v_cmp_ne_u32_e32 vcc, v160, v147
	v_cmp_ne_u32_e64 s[98:99], v161, v147
	v_cndmask_b32_e64 v159, 0, v159, s[100:101]
	v_max3_u32 v148, v148, v158, v159
	v_cndmask_b32_e32 v160, 0, v160, vcc
	v_cndmask_b32_e64 v161, 0, v161, s[98:99]
	v_cmp_ne_u32_e64 s[100:101], v162, v147
	v_max3_u32 v148, v148, v160, v161
	v_cmp_ne_u32_e32 vcc, v164, v147
	v_cndmask_b32_e64 v162, 0, v162, s[100:101]
	v_cmp_ne_u32_e64 s[98:99], v0, v147
	v_cndmask_b32_e32 v164, 0, v164, vcc
	v_max3_u32 v148, v148, v162, v164
	v_cndmask_b32_e64 v0, 0, v0, s[98:99]
	v_cmp_ne_u32_e64 s[100:101], v1, v147
	v_cmp_ne_u32_e32 vcc, v2, v147
	v_cmp_ne_u32_e64 s[98:99], v3, v147
	v_cndmask_b32_e64 v1, 0, v1, s[100:101]
	v_max3_u32 v148, v148, v0, v1
	v_cndmask_b32_e32 v2, 0, v2, vcc
	v_cndmask_b32_e64 v3, 0, v3, s[98:99]
	v_max3_u32 v148, v148, v2, v3
	v_mov_b32_e32 v166, v148
	s_nop 1
	v_permlane16_swap_b32 v148, v166
	s_nop 1
	s_waitcnt lgkmcnt(0)
; DI void peer_topk_wave(const Params& p, int item, unsigned* lds  ) {
;     ...
; #pragma unroll
;     for (int rr = 0; rr < 16; ++rr) {
;       unsigned m = 0;
; #pragma unroll
;       for (int i = 0; i < 32; ++i) m = umax(m, kk[i]);
;       m = umax(m, (unsigned)__shfl_xor((int)m, 16));
;       m = umax(m, (unsigned)__shfl_xor((int)m, 32));
;       win[pp][rr] = m;
; #pragma unroll
;       for (int i = 0; i < 32; ++i) kk[i] = (kk[i] == m) ? 0u : kk[i];
;     }
	v_max_u32_e32 v148, v148, v166
	v_mov_b32_e32 v166, v148
	s_nop 1
	v_permlane32_swap_b32 v148, v166
	s_nop 1
	s_waitcnt lgkmcnt(0)
	v_max_u32_e32 v148, v148, v166
	v_cmp_ne_u32_e32 vcc, v4, v148
	v_cmp_ne_u32_e64 s[98:99], v5, v148
	v_cmp_ne_u32_e64 s[100:101], v6, v148
	v_cndmask_b32_e32 v4, 0, v4, vcc
	v_cndmask_b32_e64 v5, 0, v5, s[98:99]
	v_cndmask_b32_e64 v6, 0, v6, s[100:101]
	v_cmp_ne_u32_e32 vcc, v7, v148
	v_cmp_ne_u32_e64 s[98:99], v8, v148
	v_cmp_ne_u32_e64 s[100:101], v9, v148
	v_cndmask_b32_e32 v7, 0, v7, vcc
	v_cndmask_b32_e64 v8, 0, v8, s[98:99]
	v_cndmask_b32_e64 v9, 0, v9, s[100:101]
	v_cmp_ne_u32_e32 vcc, v10, v148
	v_cmp_ne_u32_e64 s[98:99], v11, v148
	v_cmp_ne_u32_e64 s[100:101], v12, v148
	v_cndmask_b32_e32 v10, 0, v10, vcc
	v_cndmask_b32_e64 v11, 0, v11, s[98:99]
	v_cndmask_b32_e64 v12, 0, v12, s[100:101]
	v_cmp_ne_u32_e32 vcc, v13, v148
	v_cmp_ne_u32_e64 s[98:99], v14, v148
	v_cmp_ne_u32_e64 s[100:101], v15, v148
	v_cndmask_b32_e32 v13, 0, v13, vcc
	v_cndmask_b32_e64 v14, 0, v14, s[98:99]
	v_cndmask_b32_e64 v15, 0, v15, s[100:101]
	v_cmp_ne_u32_e32 vcc, v165, v148
	v_cmp_ne_u32_e64 s[98:99], v149, v148
	v_cmp_ne_u32_e64 s[100:101], v150, v148
	v_cndmask_b32_e32 v165, 0, v165, vcc
	v_cndmask_b32_e64 v166, 0, v149, s[98:99]
	v_max_u32_e32 v149, v4, v5
	v_max3_u32 v149, v149, v6, v7
	v_cndmask_b32_e64 v150, 0, v150, s[100:101]
	v_cmp_ne_u32_e32 vcc, v151, v148
	v_max3_u32 v149, v149, v8, v9
	v_max3_u32 v149, v149, v10, v11
	v_cndmask_b32_e32 v151, 0, v151, vcc
	v_cmp_ne_u32_e64 s[98:99], v152, v148
	v_max3_u32 v149, v149, v12, v13
	v_max3_u32 v149, v149, v14, v15
	v_cndmask_b32_e64 v152, 0, v152, s[98:99]
	v_cmp_ne_u32_e64 s[100:101], v153, v148
	v_max3_u32 v149, v149, v165, v166
	v_max3_u32 v149, v149, v150, v151
	v_cndmask_b32_e64 v153, 0, v153, s[100:101]
	v_cmp_ne_u32_e32 vcc, v154, v148
	v_max3_u32 v149, v149, v152, v153
	v_cmp_ne_u32_e64 s[98:99], v155, v148
	v_cndmask_b32_e32 v154, 0, v154, vcc
	v_cmp_ne_u32_e64 s[100:101], v156, v148
	v_cndmask_b32_e64 v155, 0, v155, s[98:99]
	v_max3_u32 v149, v149, v154, v155
	v_cndmask_b32_e64 v156, 0, v156, s[100:101]
	v_cmp_ne_u32_e32 vcc, v157, v148
	v_cmp_ne_u32_e64 s[98:99], v158, v148
	v_cmp_ne_u32_e64 s[100:101], v159, v148
	v_cndmask_b32_e32 v157, 0, v157, vcc
	v_max3_u32 v149, v149, v156, v157
	v_cndmask_b32_e64 v158, 0, v158, s[98:99]
	v_cndmask_b32_e64 v159, 0, v159, s[100:101]
	v_cmp_ne_u32_e32 vcc, v160, v148
	v_max3_u32 v149, v149, v158, v159
	v_cmp_ne_u32_e64 s[98:99], v161, v148
	v_cndmask_b32_e32 v160, 0, v160, vcc
	v_cmp_ne_u32_e64 s[100:101], v162, v148
	v_cndmask_b32_e64 v161, 0, v161, s[98:99]
	v_max3_u32 v149, v149, v160, v161
	v_cndmask_b32_e64 v162, 0, v162, s[100:101]
	v_cmp_ne_u32_e32 vcc, v164, v148
	v_cmp_ne_u32_e64 s[98:99], v0, v148
	v_cmp_ne_u32_e64 s[100:101], v1, v148
	v_cndmask_b32_e32 v164, 0, v164, vcc
	v_max3_u32 v149, v149, v162, v164
	v_cndmask_b32_e64 v0, 0, v0, s[98:99]
	v_cndmask_b32_e64 v1, 0, v1, s[100:101]
	v_cmp_ne_u32_e32 vcc, v2, v148
	v_max3_u32 v149, v149, v0, v1
	v_cmp_ne_u32_e64 s[98:99], v3, v148
	v_cndmask_b32_e32 v2, 0, v2, vcc
	s_nop 0
	v_cndmask_b32_e64 v3, 0, v3, s[98:99]
	v_max3_u32 v149, v149, v2, v3
	v_mov_b32_e32 v167, v149
	s_nop 1
	v_permlane16_swap_b32 v149, v167
	s_nop 1
	s_waitcnt lgkmcnt(0)
	v_max_u32_e32 v149, v149, v167
	v_mov_b32_e32 v167, v149
	s_nop 1
	v_permlane32_swap_b32 v149, v167
	s_nop 1
	s_waitcnt lgkmcnt(0)
	v_max_u32_e32 v149, v149, v167
	v_cmp_ne_u32_e32 vcc, v4, v149
	v_cmp_ne_u32_e64 s[98:99], v5, v149
	v_cmp_ne_u32_e64 s[100:101], v6, v149
	v_cndmask_b32_e32 v4, 0, v4, vcc
	v_cndmask_b32_e64 v5, 0, v5, s[98:99]
	v_cndmask_b32_e64 v6, 0, v6, s[100:101]
	v_cmp_ne_u32_e32 vcc, v7, v149
	v_cmp_ne_u32_e64 s[98:99], v8, v149
	v_cmp_ne_u32_e64 s[100:101], v9, v149
	v_cndmask_b32_e32 v7, 0, v7, vcc
	v_cndmask_b32_e64 v8, 0, v8, s[98:99]
	v_cndmask_b32_e64 v9, 0, v9, s[100:101]
	v_cmp_ne_u32_e32 vcc, v10, v149
	v_cmp_ne_u32_e64 s[98:99], v11, v149
	v_cmp_ne_u32_e64 s[100:101], v12, v149
	v_cndmask_b32_e32 v10, 0, v10, vcc
	v_cndmask_b32_e64 v11, 0, v11, s[98:99]
	v_cndmask_b32_e64 v12, 0, v12, s[100:101]
	v_cmp_ne_u32_e32 vcc, v13, v149
	v_cmp_ne_u32_e64 s[98:99], v14, v149
	v_cmp_ne_u32_e64 s[100:101], v15, v149
	v_cndmask_b32_e32 v13, 0, v13, vcc
	v_cndmask_b32_e64 v14, 0, v14, s[98:99]
	v_cndmask_b32_e64 v15, 0, v15, s[100:101]
	v_cmp_ne_u32_e32 vcc, v165, v149
	v_cmp_ne_u32_e64 s[98:99], v166, v149
	v_cmp_ne_u32_e64 s[100:101], v150, v149
	v_cndmask_b32_e32 v165, 0, v165, vcc
	v_cndmask_b32_e64 v166, 0, v166, s[98:99]
	v_cndmask_b32_e64 v167, 0, v150, s[100:101]
	v_cmp_ne_u32_e32 vcc, v151, v149
	v_max_u32_e32 v150, v4, v5
	v_max3_u32 v150, v150, v6, v7
	v_cndmask_b32_e32 v151, 0, v151, vcc
	v_cmp_ne_u32_e64 s[98:99], v152, v149
	v_max3_u32 v150, v150, v8, v9
	v_max3_u32 v150, v150, v10, v11
	v_cndmask_b32_e64 v152, 0, v152, s[98:99]
	v_cmp_ne_u32_e64 s[100:101], v153, v149
	v_max3_u32 v150, v150, v12, v13
	v_max3_u32 v150, v150, v14, v15
	v_cndmask_b32_e64 v153, 0, v153, s[100:101]
	v_cmp_ne_u32_e32 vcc, v154, v149
	v_max3_u32 v150, v150, v165, v166
	v_max3_u32 v150, v150, v167, v151
	v_cndmask_b32_e32 v154, 0, v154, vcc
	v_cmp_ne_u32_e64 s[98:99], v155, v149
	v_max3_u32 v150, v150, v152, v153
	v_cmp_ne_u32_e64 s[100:101], v156, v149
	v_cndmask_b32_e64 v155, 0, v155, s[98:99]
	v_max3_u32 v150, v150, v154, v155
	v_cndmask_b32_e64 v156, 0, v156, s[100:101]
	v_cmp_ne_u32_e32 vcc, v157, v149
	v_cmp_ne_u32_e64 s[98:99], v158, v149
	v_cmp_ne_u32_e64 s[100:101], v159, v149
	v_cndmask_b32_e32 v157, 0, v157, vcc
	v_max3_u32 v150, v150, v156, v157
	v_cndmask_b32_e64 v158, 0, v158, s[98:99]
	v_cndmask_b32_e64 v159, 0, v159, s[100:101]
	v_cmp_ne_u32_e32 vcc, v160, v149
	v_max3_u32 v150, v150, v158, v159
	v_cmp_ne_u32_e64 s[98:99], v161, v149
	v_cndmask_b32_e32 v160, 0, v160, vcc
	v_cmp_ne_u32_e64 s[100:101], v162, v149
	v_cndmask_b32_e64 v161, 0, v161, s[98:99]
	v_max3_u32 v150, v150, v160, v161
	v_cndmask_b32_e64 v162, 0, v162, s[100:101]
	v_cmp_ne_u32_e32 vcc, v164, v149
	v_cmp_ne_u32_e64 s[98:99], v0, v149
	v_cmp_ne_u32_e64 s[100:101], v1, v149
	v_cndmask_b32_e32 v164, 0, v164, vcc
	v_max3_u32 v150, v150, v162, v164
	v_cndmask_b32_e64 v0, 0, v0, s[98:99]
	v_cndmask_b32_e64 v1, 0, v1, s[100:101]
	v_cmp_ne_u32_e32 vcc, v2, v149
	v_max3_u32 v150, v150, v0, v1
	v_cmp_ne_u32_e64 s[98:99], v3, v149
	v_cndmask_b32_e32 v2, 0, v2, vcc
	s_nop 0
	v_cndmask_b32_e64 v3, 0, v3, s[98:99]
	v_max3_u32 v150, v150, v2, v3
	v_mov_b32_e32 v168, v150
	s_nop 1
	v_permlane16_swap_b32 v150, v168
	s_nop 1
	s_waitcnt lgkmcnt(0)
; DI void peer_topk_wave(const Params& p, int item, unsigned* lds  ) {
;     ...
; #pragma unroll
;     for (int rr = 0; rr < 16; ++rr) {
;       unsigned m = 0;
; #pragma unroll
;       for (int i = 0; i < 32; ++i) m = umax(m, kk[i]);
;       m = umax(m, (unsigned)__shfl_xor((int)m, 16));
;       m = umax(m, (unsigned)__shfl_xor((int)m, 32));
;       win[pp][rr] = m;
; #pragma unroll
;       for (int i = 0; i < 32; ++i) kk[i] = (kk[i] == m) ? 0u : kk[i];
;     }
	v_max_u32_e32 v150, v150, v168
	v_mov_b32_e32 v168, v150
	s_nop 1
	v_permlane32_swap_b32 v150, v168
	s_nop 1
	s_waitcnt lgkmcnt(0)
	v_max_u32_e32 v150, v150, v168
	v_cmp_ne_u32_e32 vcc, v4, v150
	v_cmp_ne_u32_e64 s[98:99], v5, v150
	v_cmp_ne_u32_e64 s[100:101], v6, v150
	v_cndmask_b32_e32 v4, 0, v4, vcc
	v_cndmask_b32_e64 v5, 0, v5, s[98:99]
	v_cndmask_b32_e64 v6, 0, v6, s[100:101]
	v_cmp_ne_u32_e32 vcc, v7, v150
	v_cmp_ne_u32_e64 s[98:99], v8, v150
	v_cmp_ne_u32_e64 s[100:101], v9, v150
	v_cndmask_b32_e32 v7, 0, v7, vcc
	v_cndmask_b32_e64 v8, 0, v8, s[98:99]
	v_cndmask_b32_e64 v9, 0, v9, s[100:101]
	v_cmp_ne_u32_e32 vcc, v10, v150
	v_cmp_ne_u32_e64 s[98:99], v11, v150
	v_cmp_ne_u32_e64 s[100:101], v12, v150
	v_cndmask_b32_e32 v10, 0, v10, vcc
	v_cndmask_b32_e64 v11, 0, v11, s[98:99]
	v_cndmask_b32_e64 v12, 0, v12, s[100:101]
	v_cmp_ne_u32_e32 vcc, v13, v150
	v_cmp_ne_u32_e64 s[98:99], v14, v150
	v_cmp_ne_u32_e64 s[100:101], v15, v150
	v_cndmask_b32_e32 v13, 0, v13, vcc
	v_cndmask_b32_e64 v14, 0, v14, s[98:99]
	v_cndmask_b32_e64 v15, 0, v15, s[100:101]
	v_cmp_ne_u32_e32 vcc, v165, v150
	v_cmp_ne_u32_e64 s[98:99], v166, v150
	v_cmp_ne_u32_e64 s[100:101], v167, v150
	v_cndmask_b32_e32 v165, 0, v165, vcc
	v_cndmask_b32_e64 v166, 0, v166, s[98:99]
	v_cndmask_b32_e64 v167, 0, v167, s[100:101]
	v_cmp_ne_u32_e32 vcc, v151, v150
	v_cmp_ne_u32_e64 s[98:99], v152, v150
	v_cmp_ne_u32_e64 s[100:101], v153, v150
	v_cndmask_b32_e32 v168, 0, v151, vcc
	v_max_u32_e32 v151, v4, v5
	v_max3_u32 v151, v151, v6, v7
	v_cndmask_b32_e64 v152, 0, v152, s[98:99]
	v_max3_u32 v151, v151, v8, v9
	v_max3_u32 v151, v151, v10, v11
	v_cndmask_b32_e64 v153, 0, v153, s[100:101]
	v_cmp_ne_u32_e32 vcc, v154, v150
	v_max3_u32 v151, v151, v12, v13
	v_max3_u32 v151, v151, v14, v15
	v_cndmask_b32_e32 v154, 0, v154, vcc
	v_cmp_ne_u32_e64 s[98:99], v155, v150
	v_max3_u32 v151, v151, v165, v166
	v_max3_u32 v151, v151, v167, v168
	v_cndmask_b32_e64 v155, 0, v155, s[98:99]
	v_cmp_ne_u32_e64 s[100:101], v156, v150
	v_max3_u32 v151, v151, v152, v153
	v_max3_u32 v151, v151, v154, v155
	v_cndmask_b32_e64 v156, 0, v156, s[100:101]
	v_cmp_ne_u32_e32 vcc, v157, v150
	v_cmp_ne_u32_e64 s[98:99], v158, v150
	v_cmp_ne_u32_e64 s[100:101], v159, v150
	v_cndmask_b32_e32 v157, 0, v157, vcc
	v_max3_u32 v151, v151, v156, v157
	v_cndmask_b32_e64 v158, 0, v158, s[98:99]
	v_cndmask_b32_e64 v159, 0, v159, s[100:101]
	v_cmp_ne_u32_e32 vcc, v160, v150
	v_max3_u32 v151, v151, v158, v159
	v_cmp_ne_u32_e64 s[98:99], v161, v150
	v_cndmask_b32_e32 v160, 0, v160, vcc
	v_cmp_ne_u32_e64 s[100:101], v162, v150
	v_cndmask_b32_e64 v161, 0, v161, s[98:99]
	v_max3_u32 v151, v151, v160, v161
	v_cndmask_b32_e64 v162, 0, v162, s[100:101]
	v_cmp_ne_u32_e32 vcc, v164, v150
	v_cmp_ne_u32_e64 s[98:99], v0, v150
	v_cmp_ne_u32_e64 s[100:101], v1, v150
	v_cndmask_b32_e32 v164, 0, v164, vcc
	v_max3_u32 v151, v151, v162, v164
	v_cndmask_b32_e64 v0, 0, v0, s[98:99]
	v_cndmask_b32_e64 v1, 0, v1, s[100:101]
	v_cmp_ne_u32_e32 vcc, v2, v150
	v_max3_u32 v151, v151, v0, v1
	v_cmp_ne_u32_e64 s[98:99], v3, v150
	v_cndmask_b32_e32 v2, 0, v2, vcc
	s_nop 0
	v_cndmask_b32_e64 v3, 0, v3, s[98:99]
	v_max3_u32 v151, v151, v2, v3
	v_mov_b32_e32 v169, v151
	s_nop 1
	v_permlane16_swap_b32 v151, v169
	s_nop 1
	s_waitcnt lgkmcnt(0)
	v_max_u32_e32 v151, v151, v169
	v_mov_b32_e32 v169, v151
	s_nop 1
	v_permlane32_swap_b32 v151, v169
	s_nop 1
	s_waitcnt lgkmcnt(0)
	v_max_u32_e32 v151, v151, v169
	v_cmp_ne_u32_e32 vcc, v4, v151
	v_cmp_ne_u32_e64 s[98:99], v5, v151
	v_cmp_ne_u32_e64 s[100:101], v6, v151
	v_cndmask_b32_e32 v4, 0, v4, vcc
	v_cndmask_b32_e64 v5, 0, v5, s[98:99]
	v_cndmask_b32_e64 v6, 0, v6, s[100:101]
	v_cmp_ne_u32_e32 vcc, v7, v151
	v_cmp_ne_u32_e64 s[98:99], v8, v151
	v_cmp_ne_u32_e64 s[100:101], v9, v151
	v_cndmask_b32_e32 v7, 0, v7, vcc
	v_cndmask_b32_e64 v8, 0, v8, s[98:99]
	v_cndmask_b32_e64 v9, 0, v9, s[100:101]
	v_cmp_ne_u32_e32 vcc, v10, v151
	v_cmp_ne_u32_e64 s[98:99], v11, v151
	v_cmp_ne_u32_e64 s[100:101], v12, v151
	v_cndmask_b32_e32 v10, 0, v10, vcc
	v_cndmask_b32_e64 v11, 0, v11, s[98:99]
	v_cndmask_b32_e64 v12, 0, v12, s[100:101]
	v_cmp_ne_u32_e32 vcc, v13, v151
	v_cmp_ne_u32_e64 s[98:99], v14, v151
	v_cmp_ne_u32_e64 s[100:101], v15, v151
	v_cndmask_b32_e32 v13, 0, v13, vcc
	v_cndmask_b32_e64 v14, 0, v14, s[98:99]
	v_cndmask_b32_e64 v15, 0, v15, s[100:101]
	v_cmp_ne_u32_e32 vcc, v165, v151
	v_cmp_ne_u32_e64 s[98:99], v166, v151
	v_cmp_ne_u32_e64 s[100:101], v167, v151
	v_cndmask_b32_e32 v165, 0, v165, vcc
	v_cndmask_b32_e64 v166, 0, v166, s[98:99]
	v_cndmask_b32_e64 v167, 0, v167, s[100:101]
	v_cmp_ne_u32_e32 vcc, v168, v151
	v_cmp_ne_u32_e64 s[98:99], v152, v151
	v_cmp_ne_u32_e64 s[100:101], v153, v151
	v_cndmask_b32_e32 v168, 0, v168, vcc
	v_cndmask_b32_e64 v169, 0, v152, s[98:99]
	v_max_u32_e32 v152, v4, v5
	v_max3_u32 v152, v152, v6, v7
	v_cndmask_b32_e64 v153, 0, v153, s[100:101]
	v_cmp_ne_u32_e32 vcc, v154, v151
	v_max3_u32 v152, v152, v8, v9
	v_max3_u32 v152, v152, v10, v11
	v_cndmask_b32_e32 v154, 0, v154, vcc
	v_cmp_ne_u32_e64 s[98:99], v155, v151
	v_max3_u32 v152, v152, v12, v13
	v_max3_u32 v152, v152, v14, v15
	v_cndmask_b32_e64 v155, 0, v155, s[98:99]
	v_cmp_ne_u32_e64 s[100:101], v156, v151
	v_max3_u32 v152, v152, v165, v166
	v_max3_u32 v152, v152, v167, v168
	v_cndmask_b32_e64 v156, 0, v156, s[100:101]
	v_cmp_ne_u32_e32 vcc, v157, v151
	v_max3_u32 v152, v152, v169, v153
	v_max3_u32 v152, v152, v154, v155
	v_cndmask_b32_e32 v157, 0, v157, vcc
	v_cmp_ne_u32_e64 s[98:99], v158, v151
	v_max3_u32 v152, v152, v156, v157
	v_cmp_ne_u32_e64 s[100:101], v159, v151
	v_cndmask_b32_e64 v158, 0, v158, s[98:99]
	v_cmp_ne_u32_e32 vcc, v160, v151
	v_cndmask_b32_e64 v159, 0, v159, s[100:101]
	v_max3_u32 v152, v152, v158, v159
	v_cndmask_b32_e32 v160, 0, v160, vcc
	v_cmp_ne_u32_e64 s[98:99], v161, v151
	v_cmp_ne_u32_e64 s[100:101], v162, v151
	v_cmp_ne_u32_e32 vcc, v164, v151
	v_cndmask_b32_e64 v161, 0, v161, s[98:99]
	v_max3_u32 v152, v152, v160, v161
	v_cndmask_b32_e64 v162, 0, v162, s[100:101]
	v_cndmask_b32_e32 v164, 0, v164, vcc
	v_cmp_ne_u32_e64 s[98:99], v0, v151
	v_max3_u32 v152, v152, v162, v164
	v_cmp_ne_u32_e64 s[100:101], v1, v151
	v_cndmask_b32_e64 v0, 0, v0, s[98:99]
	v_cmp_ne_u32_e32 vcc, v2, v151
	v_cndmask_b32_e64 v1, 0, v1, s[100:101]
	v_max3_u32 v152, v152, v0, v1
	v_cndmask_b32_e32 v2, 0, v2, vcc
	v_cmp_ne_u32_e64 s[98:99], v3, v151
	s_nop 0
	s_nop 0
	v_cndmask_b32_e64 v3, 0, v3, s[98:99]
	v_max3_u32 v152, v152, v2, v3
	v_mov_b32_e32 v171, v152
	s_nop 1
	v_permlane16_swap_b32 v152, v171
	s_nop 1
	s_waitcnt lgkmcnt(0)
; DI void peer_topk_wave(const Params& p, int item, unsigned* lds  ) {
;     ...
; #pragma unroll
;     for (int rr = 0; rr < 16; ++rr) {
;       unsigned m = 0;
; #pragma unroll
;       for (int i = 0; i < 32; ++i) m = umax(m, kk[i]);
;       m = umax(m, (unsigned)__shfl_xor((int)m, 16));
;       m = umax(m, (unsigned)__shfl_xor((int)m, 32));
;       win[pp][rr] = m;
; #pragma unroll
;       for (int i = 0; i < 32; ++i) kk[i] = (kk[i] == m) ? 0u : kk[i];
;     }
	v_max_u32_e32 v152, v152, v171
	v_mov_b32_e32 v171, v152
	s_nop 1
	v_permlane32_swap_b32 v152, v171
	s_nop 1
	s_waitcnt lgkmcnt(0)
	v_max_u32_e32 v152, v152, v171
	v_cmp_ne_u32_e32 vcc, v4, v152
	v_cmp_ne_u32_e64 s[98:99], v5, v152
	v_cmp_ne_u32_e64 s[100:101], v6, v152
	v_cndmask_b32_e32 v4, 0, v4, vcc
	v_cndmask_b32_e64 v5, 0, v5, s[98:99]
	v_cndmask_b32_e64 v6, 0, v6, s[100:101]
	v_cmp_ne_u32_e32 vcc, v7, v152
	v_cmp_ne_u32_e64 s[98:99], v8, v152
	v_cmp_ne_u32_e64 s[100:101], v9, v152
	v_cndmask_b32_e32 v7, 0, v7, vcc
	v_cndmask_b32_e64 v8, 0, v8, s[98:99]
	v_cndmask_b32_e64 v9, 0, v9, s[100:101]
	v_cmp_ne_u32_e32 vcc, v10, v152
	v_cmp_ne_u32_e64 s[98:99], v11, v152
	v_cmp_ne_u32_e64 s[100:101], v12, v152
	v_cndmask_b32_e32 v10, 0, v10, vcc
	v_cndmask_b32_e64 v11, 0, v11, s[98:99]
	v_cndmask_b32_e64 v12, 0, v12, s[100:101]
	v_cmp_ne_u32_e32 vcc, v13, v152
	v_cmp_ne_u32_e64 s[98:99], v14, v152
	v_cmp_ne_u32_e64 s[100:101], v15, v152
	v_cndmask_b32_e32 v13, 0, v13, vcc
	v_cndmask_b32_e64 v14, 0, v14, s[98:99]
	v_cndmask_b32_e64 v15, 0, v15, s[100:101]
	v_cmp_ne_u32_e32 vcc, v165, v152
	v_cmp_ne_u32_e64 s[98:99], v166, v152
	v_cmp_ne_u32_e64 s[100:101], v167, v152
	v_cndmask_b32_e32 v165, 0, v165, vcc
	v_cndmask_b32_e64 v166, 0, v166, s[98:99]
	v_cndmask_b32_e64 v167, 0, v167, s[100:101]
	v_cmp_ne_u32_e32 vcc, v168, v152
	v_cmp_ne_u32_e64 s[98:99], v169, v152
	v_cmp_ne_u32_e64 s[100:101], v153, v152
	v_cndmask_b32_e32 v168, 0, v168, vcc
	v_cndmask_b32_e64 v169, 0, v169, s[98:99]
	v_cndmask_b32_e64 v171, 0, v153, s[100:101]
	v_cmp_ne_u32_e32 vcc, v154, v152
	v_max_u32_e32 v153, v4, v5
	v_max3_u32 v153, v153, v6, v7
	v_cndmask_b32_e32 v154, 0, v154, vcc
	v_cmp_ne_u32_e64 s[98:99], v155, v152
	v_max3_u32 v153, v153, v8, v9
	v_max3_u32 v153, v153, v10, v11
	v_cndmask_b32_e64 v155, 0, v155, s[98:99]
	v_cmp_ne_u32_e64 s[100:101], v156, v152
	v_max3_u32 v153, v153, v12, v13
	v_max3_u32 v153, v153, v14, v15
	v_cndmask_b32_e64 v156, 0, v156, s[100:101]
	v_cmp_ne_u32_e32 vcc, v157, v152
	v_max3_u32 v153, v153, v165, v166
	v_max3_u32 v153, v153, v167, v168
	v_cndmask_b32_e32 v157, 0, v157, vcc
	v_cmp_ne_u32_e64 s[98:99], v158, v152
	v_max3_u32 v153, v153, v169, v171
	v_max3_u32 v153, v153, v154, v155
	v_cndmask_b32_e64 v158, 0, v158, s[98:99]
	v_cmp_ne_u32_e64 s[100:101], v159, v152
	v_max3_u32 v153, v153, v156, v157
	v_cmp_ne_u32_e32 vcc, v160, v152
	v_cndmask_b32_e64 v159, 0, v159, s[100:101]
	v_max3_u32 v153, v153, v158, v159
	v_cndmask_b32_e32 v160, 0, v160, vcc
	v_cmp_ne_u32_e64 s[98:99], v161, v152
	v_cmp_ne_u32_e64 s[100:101], v162, v152
	v_cmp_ne_u32_e32 vcc, v164, v152
	v_cndmask_b32_e64 v161, 0, v161, s[98:99]
	v_max3_u32 v153, v153, v160, v161
	v_cndmask_b32_e64 v162, 0, v162, s[100:101]
	v_cndmask_b32_e32 v164, 0, v164, vcc
	v_cmp_ne_u32_e64 s[98:99], v0, v152
	v_max3_u32 v153, v153, v162, v164
	v_cmp_ne_u32_e64 s[100:101], v1, v152
	v_cndmask_b32_e64 v0, 0, v0, s[98:99]
	v_cmp_ne_u32_e32 vcc, v2, v152
	v_cndmask_b32_e64 v1, 0, v1, s[100:101]
	v_max3_u32 v153, v153, v0, v1
	v_cndmask_b32_e32 v2, 0, v2, vcc
	v_cmp_ne_u32_e64 s[98:99], v3, v152
	s_nop 0
	s_nop 0
	v_cndmask_b32_e64 v3, 0, v3, s[98:99]
	v_max3_u32 v153, v153, v2, v3
	v_mov_b32_e32 v172, v153
	s_nop 1
	v_permlane16_swap_b32 v153, v172
	s_nop 1
	s_waitcnt lgkmcnt(0)
	v_max_u32_e32 v153, v153, v172
	v_mov_b32_e32 v172, v153
	s_nop 1
	v_permlane32_swap_b32 v153, v172
	s_nop 1
	s_waitcnt lgkmcnt(0)
	v_max_u32_e32 v153, v153, v172
	v_cmp_ne_u32_e32 vcc, v4, v153
	v_cmp_ne_u32_e64 s[98:99], v5, v153
	v_cmp_ne_u32_e64 s[100:101], v6, v153
	v_cndmask_b32_e32 v4, 0, v4, vcc
	v_cndmask_b32_e64 v5, 0, v5, s[98:99]
	v_cndmask_b32_e64 v6, 0, v6, s[100:101]
	v_cmp_ne_u32_e32 vcc, v7, v153
	v_cmp_ne_u32_e64 s[98:99], v8, v153
	v_cmp_ne_u32_e64 s[100:101], v9, v153
	v_cndmask_b32_e32 v7, 0, v7, vcc
	v_cndmask_b32_e64 v8, 0, v8, s[98:99]
	v_cndmask_b32_e64 v9, 0, v9, s[100:101]
	v_cmp_ne_u32_e32 vcc, v10, v153
	v_cmp_ne_u32_e64 s[98:99], v11, v153
	v_cmp_ne_u32_e64 s[100:101], v12, v153
	v_cndmask_b32_e32 v10, 0, v10, vcc
	v_cndmask_b32_e64 v11, 0, v11, s[98:99]
	v_cndmask_b32_e64 v12, 0, v12, s[100:101]
	v_cmp_ne_u32_e32 vcc, v13, v153
	v_cmp_ne_u32_e64 s[98:99], v14, v153
	v_cmp_ne_u32_e64 s[100:101], v15, v153
	v_cndmask_b32_e32 v13, 0, v13, vcc
	v_cndmask_b32_e64 v14, 0, v14, s[98:99]
	v_cndmask_b32_e64 v15, 0, v15, s[100:101]
	v_cmp_ne_u32_e32 vcc, v165, v153
	v_cmp_ne_u32_e64 s[98:99], v166, v153
	v_cmp_ne_u32_e64 s[100:101], v167, v153
	v_cndmask_b32_e32 v165, 0, v165, vcc
	v_cndmask_b32_e64 v166, 0, v166, s[98:99]
	v_cndmask_b32_e64 v167, 0, v167, s[100:101]
	v_cmp_ne_u32_e32 vcc, v168, v153
	v_cmp_ne_u32_e64 s[98:99], v169, v153
	v_cmp_ne_u32_e64 s[100:101], v171, v153
	v_cndmask_b32_e32 v168, 0, v168, vcc
	v_cndmask_b32_e64 v169, 0, v169, s[98:99]
	v_cndmask_b32_e64 v171, 0, v171, s[100:101]
	v_cmp_ne_u32_e32 vcc, v154, v153
	v_cmp_ne_u32_e64 s[98:99], v155, v153
	v_cmp_ne_u32_e64 s[100:101], v156, v153
	v_cndmask_b32_e32 v172, 0, v154, vcc
	v_max_u32_e32 v154, v4, v5
	v_max3_u32 v154, v154, v6, v7
	v_max3_u32 v154, v154, v8, v9
	v_cndmask_b32_e64 v155, 0, v155, s[98:99]
	v_max3_u32 v154, v154, v10, v11
	v_max3_u32 v154, v154, v12, v13
	v_cndmask_b32_e64 v156, 0, v156, s[100:101]
	v_cmp_ne_u32_e32 vcc, v157, v153
	v_max3_u32 v154, v154, v14, v15
	v_max3_u32 v154, v154, v165, v166
	v_cndmask_b32_e32 v157, 0, v157, vcc
	v_cmp_ne_u32_e64 s[98:99], v158, v153
	v_max3_u32 v154, v154, v167, v168
	v_max3_u32 v154, v154, v169, v171
	v_cndmask_b32_e64 v158, 0, v158, s[98:99]
	v_cmp_ne_u32_e64 s[100:101], v159, v153
	v_max3_u32 v154, v154, v172, v155
	v_max3_u32 v154, v154, v156, v157
	v_cndmask_b32_e64 v159, 0, v159, s[100:101]
	v_cmp_ne_u32_e32 vcc, v160, v153
	v_max3_u32 v154, v154, v158, v159
	v_cmp_ne_u32_e64 s[98:99], v161, v153
	v_cndmask_b32_e32 v160, 0, v160, vcc
	v_cmp_ne_u32_e64 s[100:101], v162, v153
	v_cndmask_b32_e64 v161, 0, v161, s[98:99]
	v_max3_u32 v154, v154, v160, v161
	v_cndmask_b32_e64 v162, 0, v162, s[100:101]
	v_cmp_ne_u32_e32 vcc, v164, v153
	v_cmp_ne_u32_e64 s[98:99], v0, v153
	v_cmp_ne_u32_e64 s[100:101], v1, v153
	v_cndmask_b32_e32 v164, 0, v164, vcc
	v_max3_u32 v154, v154, v162, v164
	v_cndmask_b32_e64 v0, 0, v0, s[98:99]
	v_cndmask_b32_e64 v1, 0, v1, s[100:101]
	v_cmp_ne_u32_e32 vcc, v2, v153
	v_max3_u32 v154, v154, v0, v1
	v_cmp_ne_u32_e64 s[98:99], v3, v153
	v_cndmask_b32_e32 v2, 0, v2, vcc
	s_nop 0
	v_cndmask_b32_e64 v3, 0, v3, s[98:99]
	v_max3_u32 v154, v154, v2, v3
	v_mov_b32_e32 v173, v154
	s_nop 1
	v_permlane16_swap_b32 v154, v173
	s_nop 1
	s_waitcnt lgkmcnt(0)
; DI void peer_topk_wave(const Params& p, int item, unsigned* lds  ) {
;     ...
; #pragma unroll
;     for (int rr = 0; rr < 16; ++rr) {
;       unsigned m = 0;
; #pragma unroll
;       for (int i = 0; i < 32; ++i) m = umax(m, kk[i]);
;       m = umax(m, (unsigned)__shfl_xor((int)m, 16));
;       m = umax(m, (unsigned)__shfl_xor((int)m, 32));
;       win[pp][rr] = m;
; #pragma unroll
;       for (int i = 0; i < 32; ++i) kk[i] = (kk[i] == m) ? 0u : kk[i];
;     }
	v_max_u32_e32 v154, v154, v173
	v_mov_b32_e32 v173, v154
	s_nop 1
	v_permlane32_swap_b32 v154, v173
	s_nop 1
	s_waitcnt lgkmcnt(0)
	v_max_u32_e32 v154, v154, v173
	v_cmp_ne_u32_e32 vcc, v4, v154
	v_cmp_ne_u32_e64 s[98:99], v5, v154
	v_cmp_ne_u32_e64 s[100:101], v6, v154
	v_cndmask_b32_e32 v4, 0, v4, vcc
	v_cndmask_b32_e64 v5, 0, v5, s[98:99]
	v_cndmask_b32_e64 v6, 0, v6, s[100:101]
	v_cmp_ne_u32_e32 vcc, v7, v154
	v_cmp_ne_u32_e64 s[98:99], v8, v154
	v_cmp_ne_u32_e64 s[100:101], v9, v154
	v_cndmask_b32_e32 v7, 0, v7, vcc
	v_cndmask_b32_e64 v8, 0, v8, s[98:99]
	v_cndmask_b32_e64 v9, 0, v9, s[100:101]
	v_cmp_ne_u32_e32 vcc, v10, v154
	v_cmp_ne_u32_e64 s[98:99], v11, v154
	v_cmp_ne_u32_e64 s[100:101], v12, v154
	v_cndmask_b32_e32 v10, 0, v10, vcc
	v_cndmask_b32_e64 v11, 0, v11, s[98:99]
	v_cndmask_b32_e64 v12, 0, v12, s[100:101]
	v_cmp_ne_u32_e32 vcc, v13, v154
	v_cmp_ne_u32_e64 s[98:99], v14, v154
	v_cmp_ne_u32_e64 s[100:101], v15, v154
	v_cndmask_b32_e32 v13, 0, v13, vcc
	v_cndmask_b32_e64 v14, 0, v14, s[98:99]
	v_cndmask_b32_e64 v15, 0, v15, s[100:101]
	v_cmp_ne_u32_e32 vcc, v165, v154
	v_cmp_ne_u32_e64 s[98:99], v166, v154
	v_cmp_ne_u32_e64 s[100:101], v167, v154
	v_cndmask_b32_e32 v165, 0, v165, vcc
	v_cndmask_b32_e64 v166, 0, v166, s[98:99]
	v_cndmask_b32_e64 v167, 0, v167, s[100:101]
	v_cmp_ne_u32_e32 vcc, v168, v154
	v_cmp_ne_u32_e64 s[98:99], v169, v154
	v_cmp_ne_u32_e64 s[100:101], v171, v154
	v_cndmask_b32_e32 v168, 0, v168, vcc
	v_cndmask_b32_e64 v169, 0, v169, s[98:99]
	v_cndmask_b32_e64 v171, 0, v171, s[100:101]
	v_cmp_ne_u32_e32 vcc, v172, v154
	v_cmp_ne_u32_e64 s[98:99], v155, v154
	v_cmp_ne_u32_e64 s[100:101], v156, v154
	v_cndmask_b32_e32 v172, 0, v172, vcc
	v_cndmask_b32_e64 v173, 0, v155, s[98:99]
	v_max_u32_e32 v155, v4, v5
	v_max3_u32 v155, v155, v6, v7
	v_max3_u32 v155, v155, v8, v9
	v_max3_u32 v155, v155, v10, v11
	v_cndmask_b32_e64 v156, 0, v156, s[100:101]
	v_cmp_ne_u32_e32 vcc, v157, v154
	v_max3_u32 v155, v155, v12, v13
	v_max3_u32 v155, v155, v14, v15
	v_cndmask_b32_e32 v157, 0, v157, vcc
	v_cmp_ne_u32_e64 s[98:99], v158, v154
	v_max3_u32 v155, v155, v165, v166
	v_max3_u32 v155, v155, v167, v168
	v_cndmask_b32_e64 v158, 0, v158, s[98:99]
	v_cmp_ne_u32_e64 s[100:101], v159, v154
	v_max3_u32 v155, v155, v169, v171
	v_max3_u32 v155, v155, v172, v173
	v_cndmask_b32_e64 v159, 0, v159, s[100:101]
	v_cmp_ne_u32_e32 vcc, v160, v154
	v_max3_u32 v155, v155, v156, v157
	v_max3_u32 v155, v155, v158, v159
	v_cndmask_b32_e32 v160, 0, v160, vcc
	v_cmp_ne_u32_e64 s[98:99], v161, v154
	v_cmp_ne_u32_e64 s[100:101], v162, v154
	v_cmp_ne_u32_e32 vcc, v164, v154
	v_cndmask_b32_e64 v161, 0, v161, s[98:99]
	v_max3_u32 v155, v155, v160, v161
	v_cndmask_b32_e64 v162, 0, v162, s[100:101]
	v_cndmask_b32_e32 v164, 0, v164, vcc
	v_cmp_ne_u32_e64 s[98:99], v0, v154
	v_max3_u32 v155, v155, v162, v164
	v_cmp_ne_u32_e64 s[100:101], v1, v154
	v_cndmask_b32_e64 v0, 0, v0, s[98:99]
	v_cmp_ne_u32_e32 vcc, v2, v154
	v_cndmask_b32_e64 v1, 0, v1, s[100:101]
	v_max3_u32 v155, v155, v0, v1
	v_cndmask_b32_e32 v2, 0, v2, vcc
	v_cmp_ne_u32_e64 s[98:99], v3, v154
	s_nop 0
	s_nop 0
	v_cndmask_b32_e64 v3, 0, v3, s[98:99]
	v_max3_u32 v155, v155, v2, v3
	v_mov_b32_e32 v176, v155
	s_nop 1
	v_permlane16_swap_b32 v155, v176
	s_nop 1
	s_waitcnt lgkmcnt(0)
	v_max_u32_e32 v155, v155, v176
	v_mov_b32_e32 v176, v155
	s_nop 1
	v_permlane32_swap_b32 v155, v176
	s_nop 1
	s_waitcnt lgkmcnt(0)
	v_max_u32_e32 v155, v155, v176
	v_cmp_ne_u32_e32 vcc, v4, v155
	v_cmp_ne_u32_e64 s[98:99], v5, v155
	v_cmp_ne_u32_e64 s[100:101], v6, v155
	v_cndmask_b32_e32 v4, 0, v4, vcc
	v_cndmask_b32_e64 v5, 0, v5, s[98:99]
	v_cndmask_b32_e64 v6, 0, v6, s[100:101]
	v_cmp_ne_u32_e32 vcc, v7, v155
	v_cmp_ne_u32_e64 s[98:99], v8, v155
	v_cmp_ne_u32_e64 s[100:101], v9, v155
	v_cndmask_b32_e32 v7, 0, v7, vcc
	v_cndmask_b32_e64 v8, 0, v8, s[98:99]
	v_cndmask_b32_e64 v9, 0, v9, s[100:101]
	v_cmp_ne_u32_e32 vcc, v10, v155
	v_cmp_ne_u32_e64 s[98:99], v11, v155
	v_cmp_ne_u32_e64 s[100:101], v12, v155
	v_cndmask_b32_e32 v10, 0, v10, vcc
	v_cndmask_b32_e64 v11, 0, v11, s[98:99]
	v_cndmask_b32_e64 v12, 0, v12, s[100:101]
	v_cmp_ne_u32_e32 vcc, v13, v155
	v_cmp_ne_u32_e64 s[98:99], v14, v155
	v_cmp_ne_u32_e64 s[100:101], v15, v155
	v_cndmask_b32_e32 v13, 0, v13, vcc
	v_cndmask_b32_e64 v14, 0, v14, s[98:99]
	v_cndmask_b32_e64 v15, 0, v15, s[100:101]
	v_cmp_ne_u32_e32 vcc, v165, v155
	v_cmp_ne_u32_e64 s[98:99], v166, v155
	v_cmp_ne_u32_e64 s[100:101], v167, v155
	v_cndmask_b32_e32 v165, 0, v165, vcc
	v_cndmask_b32_e64 v166, 0, v166, s[98:99]
	v_cndmask_b32_e64 v167, 0, v167, s[100:101]
	v_cmp_ne_u32_e32 vcc, v168, v155
	v_cmp_ne_u32_e64 s[98:99], v169, v155
	v_cmp_ne_u32_e64 s[100:101], v171, v155
	v_cndmask_b32_e32 v168, 0, v168, vcc
	v_cndmask_b32_e64 v169, 0, v169, s[98:99]
	v_cndmask_b32_e64 v171, 0, v171, s[100:101]
	v_cmp_ne_u32_e32 vcc, v172, v155
	v_cmp_ne_u32_e64 s[98:99], v173, v155
	v_cmp_ne_u32_e64 s[100:101], v156, v155
	v_cndmask_b32_e32 v172, 0, v172, vcc
	v_cndmask_b32_e64 v173, 0, v173, s[98:99]
	v_cndmask_b32_e64 v176, 0, v156, s[100:101]
	v_max_u32_e32 v156, v4, v5
	v_max3_u32 v156, v156, v6, v7
	v_max3_u32 v156, v156, v8, v9
	v_cmp_ne_u32_e32 vcc, v157, v155
	v_max3_u32 v156, v156, v10, v11
	v_max3_u32 v156, v156, v12, v13
	v_cndmask_b32_e32 v157, 0, v157, vcc
	v_cmp_ne_u32_e64 s[98:99], v158, v155
	v_max3_u32 v156, v156, v14, v15
	v_max3_u32 v156, v156, v165, v166
	v_cndmask_b32_e64 v158, 0, v158, s[98:99]
	v_cmp_ne_u32_e64 s[100:101], v159, v155
	v_max3_u32 v156, v156, v167, v168
	v_max3_u32 v156, v156, v169, v171
	v_cndmask_b32_e64 v159, 0, v159, s[100:101]
	v_cmp_ne_u32_e32 vcc, v160, v155
	v_max3_u32 v156, v156, v172, v173
	v_max3_u32 v156, v156, v176, v157
	v_cndmask_b32_e32 v160, 0, v160, vcc
	v_cmp_ne_u32_e64 s[98:99], v161, v155
	v_max3_u32 v156, v156, v158, v159
	v_cmp_ne_u32_e64 s[100:101], v162, v155
	v_cndmask_b32_e64 v161, 0, v161, s[98:99]
	v_max3_u32 v156, v156, v160, v161
	v_cndmask_b32_e64 v162, 0, v162, s[100:101]
	v_cmp_ne_u32_e32 vcc, v164, v155
	v_cmp_ne_u32_e64 s[98:99], v0, v155
	v_cmp_ne_u32_e64 s[100:101], v1, v155
	v_cndmask_b32_e32 v164, 0, v164, vcc
	v_max3_u32 v156, v156, v162, v164
	v_cndmask_b32_e64 v0, 0, v0, s[98:99]
	v_cndmask_b32_e64 v1, 0, v1, s[100:101]
	v_cmp_ne_u32_e32 vcc, v2, v155
	v_max3_u32 v156, v156, v0, v1
	v_cmp_ne_u32_e64 s[98:99], v3, v155
	v_cndmask_b32_e32 v2, 0, v2, vcc
	s_nop 0
	v_cndmask_b32_e64 v3, 0, v3, s[98:99]
	v_max3_u32 v156, v156, v2, v3
	v_mov_b32_e32 v177, v156
	s_nop 1
	v_permlane16_swap_b32 v156, v177
	s_nop 1
	s_waitcnt lgkmcnt(0)
; DI void peer_topk_wave(const Params& p, int item, unsigned* lds  ) {
;     ...
; #pragma unroll
;     for (int rr = 0; rr < 16; ++rr) {
;       unsigned m = 0;
; #pragma unroll
;       for (int i = 0; i < 32; ++i) m = umax(m, kk[i]);
;       m = umax(m, (unsigned)__shfl_xor((int)m, 16));
;       m = umax(m, (unsigned)__shfl_xor((int)m, 32));
;       win[pp][rr] = m;
; #pragma unroll
;       for (int i = 0; i < 32; ++i) kk[i] = (kk[i] == m) ? 0u : kk[i];
;     }
	v_max_u32_e32 v156, v156, v177
	v_mov_b32_e32 v177, v156
	s_nop 1
	v_permlane32_swap_b32 v156, v177
	s_nop 1
	s_waitcnt lgkmcnt(0)
	v_max_u32_e32 v156, v156, v177
	v_cmp_ne_u32_e32 vcc, v4, v156
	v_cmp_ne_u32_e64 s[98:99], v5, v156
	v_cmp_ne_u32_e64 s[100:101], v6, v156
	v_cndmask_b32_e32 v4, 0, v4, vcc
	v_cndmask_b32_e64 v5, 0, v5, s[98:99]
	v_cndmask_b32_e64 v6, 0, v6, s[100:101]
	v_cmp_ne_u32_e32 vcc, v7, v156
	v_cmp_ne_u32_e64 s[98:99], v8, v156
	v_cmp_ne_u32_e64 s[100:101], v9, v156
	v_cndmask_b32_e32 v7, 0, v7, vcc
	v_cndmask_b32_e64 v8, 0, v8, s[98:99]
	v_cndmask_b32_e64 v9, 0, v9, s[100:101]
	v_cmp_ne_u32_e32 vcc, v10, v156
	v_cmp_ne_u32_e64 s[98:99], v11, v156
	v_cmp_ne_u32_e64 s[100:101], v12, v156
	v_cndmask_b32_e32 v10, 0, v10, vcc
	v_cndmask_b32_e64 v11, 0, v11, s[98:99]
	v_cndmask_b32_e64 v12, 0, v12, s[100:101]
	v_cmp_ne_u32_e32 vcc, v13, v156
	v_cmp_ne_u32_e64 s[98:99], v14, v156
	v_cmp_ne_u32_e64 s[100:101], v15, v156
	v_cndmask_b32_e32 v13, 0, v13, vcc
	v_cndmask_b32_e64 v14, 0, v14, s[98:99]
	v_cndmask_b32_e64 v15, 0, v15, s[100:101]
	v_cmp_ne_u32_e32 vcc, v165, v156
	v_cmp_ne_u32_e64 s[98:99], v166, v156
	v_cmp_ne_u32_e64 s[100:101], v167, v156
	v_cndmask_b32_e32 v165, 0, v165, vcc
	v_cndmask_b32_e64 v166, 0, v166, s[98:99]
	v_cndmask_b32_e64 v167, 0, v167, s[100:101]
	v_cmp_ne_u32_e32 vcc, v168, v156
	v_cmp_ne_u32_e64 s[98:99], v169, v156
	v_cmp_ne_u32_e64 s[100:101], v171, v156
	v_cndmask_b32_e32 v168, 0, v168, vcc
	v_cndmask_b32_e64 v169, 0, v169, s[98:99]
	v_cndmask_b32_e64 v171, 0, v171, s[100:101]
	v_cmp_ne_u32_e32 vcc, v172, v156
	v_cmp_ne_u32_e64 s[98:99], v173, v156
	v_cmp_ne_u32_e64 s[100:101], v176, v156
	v_cndmask_b32_e32 v172, 0, v172, vcc
	v_cndmask_b32_e64 v173, 0, v173, s[98:99]
	v_cndmask_b32_e64 v176, 0, v176, s[100:101]
	v_cmp_ne_u32_e32 vcc, v157, v156
	v_cmp_ne_u32_e64 s[98:99], v158, v156
	v_cmp_ne_u32_e64 s[100:101], v159, v156
	v_cndmask_b32_e32 v177, 0, v157, vcc
	v_max_u32_e32 v157, v4, v5
	v_max3_u32 v157, v157, v6, v7
	v_max3_u32 v157, v157, v8, v9
	v_max3_u32 v157, v157, v10, v11
	v_max3_u32 v157, v157, v12, v13
	v_max3_u32 v157, v157, v14, v15
	v_cndmask_b32_e64 v158, 0, v158, s[98:99]
	v_max3_u32 v157, v157, v165, v166
	v_max3_u32 v157, v157, v167, v168
	v_cndmask_b32_e64 v159, 0, v159, s[100:101]
	v_cmp_ne_u32_e32 vcc, v160, v156
	v_max3_u32 v157, v157, v169, v171
	v_max3_u32 v157, v157, v172, v173
	v_cndmask_b32_e32 v160, 0, v160, vcc
	v_cmp_ne_u32_e64 s[98:99], v161, v156
	v_max3_u32 v157, v157, v176, v177
	v_max3_u32 v157, v157, v158, v159
	v_cndmask_b32_e64 v161, 0, v161, s[98:99]
	v_cmp_ne_u32_e64 s[100:101], v162, v156
	v_max3_u32 v157, v157, v160, v161
	v_cmp_ne_u32_e32 vcc, v164, v156
	v_cndmask_b32_e64 v162, 0, v162, s[100:101]
	v_cmp_ne_u32_e64 s[98:99], v0, v156
	v_cndmask_b32_e32 v164, 0, v164, vcc
	v_max3_u32 v157, v157, v162, v164
	v_cndmask_b32_e64 v0, 0, v0, s[98:99]
	v_cmp_ne_u32_e64 s[100:101], v1, v156
	v_cmp_ne_u32_e32 vcc, v2, v156
	v_cmp_ne_u32_e64 s[98:99], v3, v156
	v_cndmask_b32_e64 v1, 0, v1, s[100:101]
	v_max3_u32 v157, v157, v0, v1
	v_cndmask_b32_e32 v2, 0, v2, vcc
	v_cndmask_b32_e64 v3, 0, v3, s[98:99]
	v_max3_u32 v157, v157, v2, v3
	v_mov_b32_e32 v178, v157
	s_nop 1
	v_permlane16_swap_b32 v157, v178
	s_nop 1
	s_waitcnt lgkmcnt(0)
	v_max_u32_e32 v157, v157, v178
	v_mov_b32_e32 v178, v157
	s_nop 1
	v_permlane32_swap_b32 v157, v178
	s_nop 1
	s_waitcnt lgkmcnt(0)
	v_max_u32_e32 v157, v157, v178
	v_cmp_ne_u32_e32 vcc, v4, v157
	v_cmp_ne_u32_e64 s[98:99], v5, v157
	v_cmp_ne_u32_e64 s[100:101], v6, v157
	v_cndmask_b32_e32 v4, 0, v4, vcc
	v_cndmask_b32_e64 v5, 0, v5, s[98:99]
	v_cndmask_b32_e64 v6, 0, v6, s[100:101]
	v_cmp_ne_u32_e32 vcc, v7, v157
	v_cmp_ne_u32_e64 s[98:99], v8, v157
	v_cmp_ne_u32_e64 s[100:101], v9, v157
	v_cndmask_b32_e32 v7, 0, v7, vcc
	v_cndmask_b32_e64 v8, 0, v8, s[98:99]
	v_cndmask_b32_e64 v9, 0, v9, s[100:101]
	v_cmp_ne_u32_e32 vcc, v10, v157
	v_cmp_ne_u32_e64 s[98:99], v11, v157
	v_cmp_ne_u32_e64 s[100:101], v12, v157
	v_cndmask_b32_e32 v10, 0, v10, vcc
	v_cndmask_b32_e64 v11, 0, v11, s[98:99]
	v_cndmask_b32_e64 v12, 0, v12, s[100:101]
	v_cmp_ne_u32_e32 vcc, v13, v157
	v_cmp_ne_u32_e64 s[98:99], v14, v157
	v_cmp_ne_u32_e64 s[100:101], v15, v157
	v_cndmask_b32_e32 v13, 0, v13, vcc
	v_cndmask_b32_e64 v14, 0, v14, s[98:99]
	v_cndmask_b32_e64 v15, 0, v15, s[100:101]
	v_cmp_ne_u32_e32 vcc, v165, v157
	v_cmp_ne_u32_e64 s[98:99], v166, v157
	v_cmp_ne_u32_e64 s[100:101], v167, v157
	v_cndmask_b32_e32 v165, 0, v165, vcc
	v_cndmask_b32_e64 v166, 0, v166, s[98:99]
	v_cndmask_b32_e64 v167, 0, v167, s[100:101]
	v_cmp_ne_u32_e32 vcc, v168, v157
	v_cmp_ne_u32_e64 s[98:99], v169, v157
	v_cmp_ne_u32_e64 s[100:101], v171, v157
	v_cndmask_b32_e32 v168, 0, v168, vcc
	v_cndmask_b32_e64 v169, 0, v169, s[98:99]
	v_cndmask_b32_e64 v171, 0, v171, s[100:101]
	v_cmp_ne_u32_e32 vcc, v172, v157
	v_cmp_ne_u32_e64 s[98:99], v173, v157
	v_cmp_ne_u32_e64 s[100:101], v176, v157
	v_cndmask_b32_e32 v172, 0, v172, vcc
	v_cndmask_b32_e64 v173, 0, v173, s[98:99]
	v_cndmask_b32_e64 v176, 0, v176, s[100:101]
	v_cmp_ne_u32_e32 vcc, v177, v157
	v_cmp_ne_u32_e64 s[98:99], v158, v157
	v_cmp_ne_u32_e64 s[100:101], v159, v157
	v_cndmask_b32_e32 v177, 0, v177, vcc
	v_cndmask_b32_e64 v178, 0, v158, s[98:99]
	v_max_u32_e32 v158, v4, v5
	v_max3_u32 v158, v158, v6, v7
	v_max3_u32 v158, v158, v8, v9
	v_max3_u32 v158, v158, v10, v11
	v_max3_u32 v158, v158, v12, v13
	v_max3_u32 v158, v158, v14, v15
	v_max3_u32 v158, v158, v165, v166
	v_cndmask_b32_e64 v159, 0, v159, s[100:101]
	v_cmp_ne_u32_e32 vcc, v160, v157
	v_max3_u32 v158, v158, v167, v168
	v_max3_u32 v158, v158, v169, v171
	v_cndmask_b32_e32 v160, 0, v160, vcc
	v_cmp_ne_u32_e64 s[98:99], v161, v157
	v_max3_u32 v158, v158, v172, v173
	v_max3_u32 v158, v158, v176, v177
	v_cndmask_b32_e64 v161, 0, v161, s[98:99]
	v_cmp_ne_u32_e64 s[100:101], v162, v157
	v_max3_u32 v158, v158, v178, v159
	v_max3_u32 v158, v158, v160, v161
	v_cndmask_b32_e64 v162, 0, v162, s[100:101]
	v_cmp_ne_u32_e32 vcc, v164, v157
	v_cmp_ne_u32_e64 s[98:99], v0, v157
	v_cmp_ne_u32_e64 s[100:101], v1, v157
	v_cndmask_b32_e32 v164, 0, v164, vcc
	v_max3_u32 v158, v158, v162, v164
	v_cndmask_b32_e64 v0, 0, v0, s[98:99]
	v_cndmask_b32_e64 v1, 0, v1, s[100:101]
	v_cmp_ne_u32_e32 vcc, v2, v157
	v_max3_u32 v158, v158, v0, v1
	v_cmp_ne_u32_e64 s[98:99], v3, v157
	v_cndmask_b32_e32 v2, 0, v2, vcc
	s_nop 0
	v_cndmask_b32_e64 v3, 0, v3, s[98:99]
	v_max3_u32 v158, v158, v2, v3
	v_mov_b32_e32 v179, v158
	s_nop 1
	v_permlane16_swap_b32 v158, v179
	s_nop 1
	s_waitcnt lgkmcnt(0)
; DI void peer_topk_wave(const Params& p, int item, unsigned* lds  ) {
;     ...
; #pragma unroll
;     for (int rr = 0; rr < 16; ++rr) {
;       unsigned m = 0;
; #pragma unroll
;       for (int i = 0; i < 32; ++i) m = umax(m, kk[i]);
;       m = umax(m, (unsigned)__shfl_xor((int)m, 16));
;       m = umax(m, (unsigned)__shfl_xor((int)m, 32));
;       win[pp][rr] = m;
; #pragma unroll
;       for (int i = 0; i < 32; ++i) kk[i] = (kk[i] == m) ? 0u : kk[i];
;     }
	v_max_u32_e32 v158, v158, v179
	v_mov_b32_e32 v179, v158
	s_nop 1
	v_permlane32_swap_b32 v158, v179
	s_nop 1
	s_waitcnt lgkmcnt(0)
	v_max_u32_e32 v158, v158, v179
	v_cmp_ne_u32_e32 vcc, v4, v158
	v_cmp_ne_u32_e64 s[98:99], v5, v158
	v_cmp_ne_u32_e64 s[100:101], v6, v158
	v_cndmask_b32_e32 v4, 0, v4, vcc
	v_cndmask_b32_e64 v5, 0, v5, s[98:99]
	v_cndmask_b32_e64 v6, 0, v6, s[100:101]
	v_cmp_ne_u32_e32 vcc, v7, v158
	v_cmp_ne_u32_e64 s[98:99], v8, v158
	v_cmp_ne_u32_e64 s[100:101], v9, v158
	v_cndmask_b32_e32 v7, 0, v7, vcc
	v_cndmask_b32_e64 v8, 0, v8, s[98:99]
	v_cndmask_b32_e64 v9, 0, v9, s[100:101]
	v_cmp_ne_u32_e32 vcc, v10, v158
	v_cmp_ne_u32_e64 s[98:99], v11, v158
	v_cmp_ne_u32_e64 s[100:101], v12, v158
	v_cndmask_b32_e32 v10, 0, v10, vcc
	v_cndmask_b32_e64 v11, 0, v11, s[98:99]
	v_cndmask_b32_e64 v12, 0, v12, s[100:101]
	v_cmp_ne_u32_e32 vcc, v13, v158
	v_cmp_ne_u32_e64 s[98:99], v14, v158
	v_cmp_ne_u32_e64 s[100:101], v15, v158
	v_cndmask_b32_e32 v13, 0, v13, vcc
	v_cndmask_b32_e64 v14, 0, v14, s[98:99]
	v_cndmask_b32_e64 v15, 0, v15, s[100:101]
	v_cmp_ne_u32_e32 vcc, v165, v158
	v_cmp_ne_u32_e64 s[98:99], v166, v158
	v_cmp_ne_u32_e64 s[100:101], v167, v158
	v_cndmask_b32_e32 v165, 0, v165, vcc
	v_cndmask_b32_e64 v166, 0, v166, s[98:99]
	v_cndmask_b32_e64 v167, 0, v167, s[100:101]
	v_cmp_ne_u32_e32 vcc, v168, v158
	v_cmp_ne_u32_e64 s[98:99], v169, v158
	v_cmp_ne_u32_e64 s[100:101], v171, v158
	v_cndmask_b32_e32 v168, 0, v168, vcc
	v_cndmask_b32_e64 v169, 0, v169, s[98:99]
	v_cndmask_b32_e64 v171, 0, v171, s[100:101]
	v_cmp_ne_u32_e32 vcc, v172, v158
	v_cmp_ne_u32_e64 s[98:99], v173, v158
	v_cmp_ne_u32_e64 s[100:101], v176, v158
	v_cndmask_b32_e32 v172, 0, v172, vcc
	v_cndmask_b32_e64 v173, 0, v173, s[98:99]
	v_cndmask_b32_e64 v176, 0, v176, s[100:101]
	v_cmp_ne_u32_e32 vcc, v177, v158
	v_cmp_ne_u32_e64 s[98:99], v178, v158
	v_cmp_ne_u32_e64 s[100:101], v159, v158
	v_cndmask_b32_e32 v177, 0, v177, vcc
	v_cndmask_b32_e64 v178, 0, v178, s[98:99]
	v_cndmask_b32_e64 v179, 0, v159, s[100:101]
	v_max_u32_e32 v159, v4, v5
	v_max3_u32 v159, v159, v6, v7
	v_max3_u32 v159, v159, v8, v9
	v_max3_u32 v159, v159, v10, v11
	v_max3_u32 v159, v159, v12, v13
	v_max3_u32 v159, v159, v14, v15
	v_cmp_ne_u32_e32 vcc, v160, v158
	v_max3_u32 v159, v159, v165, v166
	v_max3_u32 v159, v159, v167, v168
	v_cndmask_b32_e32 v160, 0, v160, vcc
	v_cmp_ne_u32_e64 s[98:99], v161, v158
	v_max3_u32 v159, v159, v169, v171
	v_max3_u32 v159, v159, v172, v173
	v_cndmask_b32_e64 v161, 0, v161, s[98:99]
	v_cmp_ne_u32_e64 s[100:101], v162, v158
	v_max3_u32 v159, v159, v176, v177
	v_max3_u32 v159, v159, v178, v179
	v_cndmask_b32_e64 v162, 0, v162, s[100:101]
	v_cmp_ne_u32_e32 vcc, v164, v158
	v_max3_u32 v159, v159, v160, v161
	v_cmp_ne_u32_e64 s[98:99], v0, v158
	v_cndmask_b32_e32 v164, 0, v164, vcc
	v_max3_u32 v159, v159, v162, v164
	v_cndmask_b32_e64 v0, 0, v0, s[98:99]
	v_cmp_ne_u32_e64 s[100:101], v1, v158
	v_cmp_ne_u32_e32 vcc, v2, v158
	v_cmp_ne_u32_e64 s[98:99], v3, v158
	v_cndmask_b32_e64 v1, 0, v1, s[100:101]
	v_max3_u32 v159, v159, v0, v1
	v_cndmask_b32_e32 v2, 0, v2, vcc
	v_cndmask_b32_e64 v3, 0, v3, s[98:99]
	v_max3_u32 v159, v159, v2, v3
	v_mov_b32_e32 v180, v159
	s_nop 1
	v_permlane16_swap_b32 v159, v180
	s_nop 1
	s_waitcnt lgkmcnt(0)
	v_max_u32_e32 v159, v159, v180
	v_mov_b32_e32 v180, v159
	s_nop 1
	v_permlane32_swap_b32 v159, v180
	s_nop 1
	s_waitcnt lgkmcnt(0)
	v_max_u32_e32 v159, v159, v180
	v_cmp_ne_u32_e32 vcc, v4, v159
	v_cmp_ne_u32_e64 s[98:99], v5, v159
	v_cmp_ne_u32_e64 s[100:101], v6, v159
	v_cndmask_b32_e32 v4, 0, v4, vcc
	v_cndmask_b32_e64 v5, 0, v5, s[98:99]
	v_cndmask_b32_e64 v6, 0, v6, s[100:101]
	v_cmp_ne_u32_e32 vcc, v7, v159
	v_cmp_ne_u32_e64 s[98:99], v8, v159
	v_cmp_ne_u32_e64 s[100:101], v9, v159
	v_cndmask_b32_e32 v7, 0, v7, vcc
	v_cndmask_b32_e64 v8, 0, v8, s[98:99]
	v_cndmask_b32_e64 v9, 0, v9, s[100:101]
	v_cmp_ne_u32_e32 vcc, v10, v159
	v_cmp_ne_u32_e64 s[98:99], v11, v159
	v_cmp_ne_u32_e64 s[100:101], v12, v159
	v_cndmask_b32_e32 v10, 0, v10, vcc
	v_cndmask_b32_e64 v11, 0, v11, s[98:99]
	v_cndmask_b32_e64 v12, 0, v12, s[100:101]
	v_cmp_ne_u32_e32 vcc, v13, v159
	v_cmp_ne_u32_e64 s[98:99], v14, v159
	v_cmp_ne_u32_e64 s[100:101], v15, v159
	v_cndmask_b32_e32 v13, 0, v13, vcc
	v_cndmask_b32_e64 v14, 0, v14, s[98:99]
	v_cndmask_b32_e64 v15, 0, v15, s[100:101]
	v_cmp_ne_u32_e32 vcc, v165, v159
	v_cmp_ne_u32_e64 s[98:99], v166, v159
	v_cmp_ne_u32_e64 s[100:101], v167, v159
	v_cndmask_b32_e32 v165, 0, v165, vcc
	v_cndmask_b32_e64 v166, 0, v166, s[98:99]
	v_cndmask_b32_e64 v167, 0, v167, s[100:101]
	v_cmp_ne_u32_e32 vcc, v168, v159
	v_cmp_ne_u32_e64 s[98:99], v169, v159
	v_cmp_ne_u32_e64 s[100:101], v171, v159
	v_cndmask_b32_e32 v168, 0, v168, vcc
	v_cndmask_b32_e64 v169, 0, v169, s[98:99]
	v_cndmask_b32_e64 v171, 0, v171, s[100:101]
	v_cmp_ne_u32_e32 vcc, v172, v159
	v_cmp_ne_u32_e64 s[98:99], v173, v159
	v_cmp_ne_u32_e64 s[100:101], v176, v159
	v_cndmask_b32_e32 v172, 0, v172, vcc
	v_cndmask_b32_e64 v173, 0, v173, s[98:99]
	v_cndmask_b32_e64 v176, 0, v176, s[100:101]
	v_cmp_ne_u32_e32 vcc, v177, v159
	v_cmp_ne_u32_e64 s[98:99], v178, v159
	v_cmp_ne_u32_e64 s[100:101], v179, v159
	v_cndmask_b32_e32 v177, 0, v177, vcc
	v_cndmask_b32_e64 v178, 0, v178, s[98:99]
	v_cndmask_b32_e64 v179, 0, v179, s[100:101]
	v_cmp_ne_u32_e32 vcc, v160, v159
	v_cmp_ne_u32_e64 s[98:99], v161, v159
	v_cmp_ne_u32_e64 s[100:101], v162, v159
	v_cndmask_b32_e32 v180, 0, v160, vcc
	v_max_u32_e32 v160, v4, v5
	v_max3_u32 v160, v160, v6, v7
	v_max3_u32 v160, v160, v8, v9
	v_max3_u32 v160, v160, v10, v11
	v_max3_u32 v160, v160, v12, v13
	v_max3_u32 v160, v160, v14, v15
	v_max3_u32 v160, v160, v165, v166
	v_max3_u32 v160, v160, v167, v168
	v_max3_u32 v160, v160, v169, v171
	v_cndmask_b32_e64 v161, 0, v161, s[98:99]
	v_max3_u32 v160, v160, v172, v173
	v_max3_u32 v160, v160, v176, v177
	v_cndmask_b32_e64 v162, 0, v162, s[100:101]
	v_cmp_ne_u32_e32 vcc, v164, v159
	v_max3_u32 v160, v160, v178, v179
	v_max3_u32 v160, v160, v180, v161
	v_cndmask_b32_e32 v164, 0, v164, vcc
	v_cmp_ne_u32_e64 s[98:99], v0, v159
	v_max3_u32 v160, v160, v162, v164
	v_cmp_ne_u32_e64 s[100:101], v1, v159
	v_cndmask_b32_e64 v0, 0, v0, s[98:99]
	v_cmp_ne_u32_e32 vcc, v2, v159
	v_cndmask_b32_e64 v1, 0, v1, s[100:101]
	v_max3_u32 v160, v160, v0, v1
	v_cndmask_b32_e32 v2, 0, v2, vcc
	v_cmp_ne_u32_e64 s[98:99], v3, v159
	s_nop 0
	s_nop 0
	v_cndmask_b32_e64 v3, 0, v3, s[98:99]
	v_max3_u32 v160, v160, v2, v3
	v_mov_b32_e32 v181, v160
	s_nop 1
	v_permlane16_swap_b32 v160, v181
	s_nop 1
	s_waitcnt lgkmcnt(0)
; DI void peer_topk_wave(const Params& p, int item, unsigned* lds  ) {
;     ...
;   for (int pp = 0; pp < 2; ++pp) {
;     bf16x8 qf[4];
; #pragma unroll
;     for (int ks = 0; ks < 4; ++ks) qf[ks] = *(const bf16x8*)&p.pq[(size_t)(row0 + r) * 2048 + h * 256 + pp * 128 + ks * 32 + kg * 8];
;     ...
; #pragma unroll
;     for (int rr = 0; rr < 16; ++rr) {
;       unsigned m = 0;
; #pragma unroll
;       for (int i = 0; i < 32; ++i) m = umax(m, kk[i]);
;       m = umax(m, (unsigned)__shfl_xor((int)m, 16));
;       m = umax(m, (unsigned)__shfl_xor((int)m, 32));
;       win[pp][rr] = m;
; #pragma unroll
;       for (int i = 0; i < 32; ++i) kk[i] = (kk[i] == m) ? 0u : kk[i];
;     }
	v_max_u32_e32 v160, v160, v181
	v_mov_b32_e32 v181, v160
	s_nop 1
	v_permlane32_swap_b32 v160, v181
	s_nop 1
	s_waitcnt lgkmcnt(0)
	v_max_u32_e32 v160, v160, v181
	v_cmp_ne_u32_e64 s[0:1], v5, v160
	v_cmp_eq_u32_e32 vcc, v4, v160
	v_cmp_eq_u32_e64 s[2:3], v7, v160
	v_cndmask_b32_e64 v5, 0, v5, s[0:1]
	v_max_u32_e32 v4, v4, v5
	v_cndmask_b32_e32 v4, v4, v5, vcc
	v_cmp_eq_u32_e64 s[0:1], v6, v160
	v_max_u32_e32 v5, v4, v6
	v_cmp_eq_u32_e64 s[14:15], v8, v160
	v_cndmask_b32_e64 v4, v5, v4, s[0:1]
	v_max_u32_e32 v5, v4, v7
	v_cndmask_b32_e64 v4, v5, v4, s[2:3]
	v_max_u32_e32 v5, v4, v8
	v_cndmask_b32_e64 v4, v5, v4, s[14:15]
	v_cmp_eq_u32_e64 s[16:17], v9, v160
	v_max_u32_e32 v5, v4, v9
	v_cmp_eq_u32_e64 s[18:19], v10, v160
	v_cndmask_b32_e64 v4, v5, v4, s[16:17]
	v_max_u32_e32 v5, v4, v10
	v_cndmask_b32_e64 v4, v5, v4, s[18:19]
	v_cmp_eq_u32_e64 s[20:21], v11, v160
	v_max_u32_e32 v5, v4, v11
	v_cmp_eq_u32_e64 s[22:23], v12, v160
	v_cndmask_b32_e64 v4, v5, v4, s[20:21]
	v_max_u32_e32 v5, v4, v12
	v_cndmask_b32_e64 v4, v5, v4, s[22:23]
	v_cmp_eq_u32_e64 s[24:25], v13, v160
	v_max_u32_e32 v5, v4, v13
	v_cmp_eq_u32_e64 s[26:27], v14, v160
	v_cndmask_b32_e64 v4, v5, v4, s[24:25]
	v_max_u32_e32 v5, v4, v14
	v_cndmask_b32_e64 v4, v5, v4, s[26:27]
	v_cmp_eq_u32_e64 s[28:29], v15, v160
	v_max_u32_e32 v5, v4, v15
	v_cmp_eq_u32_e64 s[30:31], v165, v160
	v_cndmask_b32_e64 v4, v5, v4, s[28:29]
	v_max_u32_e32 v5, v4, v165
	v_cndmask_b32_e64 v4, v5, v4, s[30:31]
	v_cmp_eq_u32_e64 s[34:35], v166, v160
	v_max_u32_e32 v5, v4, v166
	v_cmp_eq_u32_e64 s[36:37], v167, v160
	v_cndmask_b32_e64 v4, v5, v4, s[34:35]
	v_max_u32_e32 v5, v4, v167
	v_cndmask_b32_e64 v4, v5, v4, s[36:37]
	v_cmp_eq_u32_e64 s[38:39], v168, v160
	v_max_u32_e32 v5, v4, v168
	v_cmp_eq_u32_e64 s[40:41], v169, v160
	v_cndmask_b32_e64 v4, v5, v4, s[38:39]
	v_max_u32_e32 v5, v4, v169
	v_cndmask_b32_e64 v4, v5, v4, s[40:41]
	v_cmp_eq_u32_e64 s[42:43], v171, v160
	v_max_u32_e32 v5, v4, v171
	v_cmp_eq_u32_e64 s[44:45], v172, v160
	v_cndmask_b32_e64 v4, v5, v4, s[42:43]
	v_max_u32_e32 v5, v4, v172
	v_cndmask_b32_e64 v4, v5, v4, s[44:45]
	v_cmp_eq_u32_e64 s[46:47], v173, v160
	v_max_u32_e32 v5, v4, v173
	v_cmp_eq_u32_e64 s[48:49], v176, v160
	v_cndmask_b32_e64 v4, v5, v4, s[46:47]
	v_max_u32_e32 v5, v4, v176
	v_cndmask_b32_e64 v4, v5, v4, s[48:49]
	v_cmp_eq_u32_e64 s[50:51], v177, v160
	v_max_u32_e32 v5, v4, v177
	v_cmp_eq_u32_e64 s[52:53], v178, v160
	v_cndmask_b32_e64 v4, v5, v4, s[50:51]
	v_max_u32_e32 v5, v4, v178
	v_cndmask_b32_e64 v4, v5, v4, s[52:53]
	v_cmp_eq_u32_e64 s[54:55], v179, v160
	v_max_u32_e32 v5, v4, v179
	v_cmp_eq_u32_e64 s[56:57], v180, v160
	v_cndmask_b32_e64 v4, v5, v4, s[54:55]
	v_max_u32_e32 v5, v4, v180
	v_cndmask_b32_e64 v4, v5, v4, s[56:57]
	v_cmp_eq_u32_e64 s[58:59], v161, v160
	v_max_u32_e32 v5, v4, v161
	v_cmp_eq_u32_e64 s[60:61], v162, v160
	v_cndmask_b32_e64 v4, v5, v4, s[58:59]
	v_max_u32_e32 v5, v4, v162
	v_cndmask_b32_e64 v4, v5, v4, s[60:61]
	v_cmp_eq_u32_e64 s[62:63], v164, v160
	v_max_u32_e32 v5, v4, v164
	v_cmp_eq_u32_e64 s[64:65], v0, v160
	v_cndmask_b32_e64 v4, v5, v4, s[62:63]
	v_max_u32_e32 v0, v4, v0
	v_cndmask_b32_e64 v0, v0, v4, s[64:65]
	v_cmp_eq_u32_e64 s[66:67], v1, v160
	v_max_u32_e32 v1, v0, v1
	v_cmp_eq_u32_e64 s[68:69], v2, v160
	v_cndmask_b32_e64 v0, v1, v0, s[66:67]
	v_max_u32_e32 v1, v0, v2
	v_cndmask_b32_e64 v0, v1, v0, s[68:69]
	v_cmp_eq_u32_e64 s[70:71], v3, v160
	v_max_u32_e32 v1, v0, v3
	v_lshl_add_u64 v[172:173], v[86:87], 0, v[24:25]
	v_cndmask_b32_e64 v0, v1, v0, s[70:71]
	v_mov_b32_e32 v1, v0
	s_nop 1
	v_permlane16_swap_b32 v0, v1
	s_nop 1
	s_waitcnt lgkmcnt(0)
	v_max_u32_e32 v161, v0, v1
	v_lshl_add_u64 v[236:237], v[88:89], 0, s[90:91]
	s_cmp_lg_u32 s88, 0
	s_cbranch_scc1 .Lp10q_mov1
	flat_load_dwordx4 v[12:15], v[88:89] offset:256
	flat_load_dwordx4 v[8:11], v[88:89] offset:320
	flat_load_dwordx4 v[4:7], v[88:89] offset:384
	flat_load_dwordx4 v[0:3], v[88:89] offset:448
	s_branch .Lp10q_done1
.Lp10q_mov1:
	v_mov_b32_e32 v12, v220
	v_mov_b32_e32 v13, v221
	v_mov_b32_e32 v14, v222
	v_mov_b32_e32 v15, v223
	v_mov_b32_e32 v8, v224
	v_mov_b32_e32 v9, v225
	v_mov_b32_e32 v10, v226
	v_mov_b32_e32 v11, v227
	v_mov_b32_e32 v4, v228
	v_mov_b32_e32 v5, v229
	v_mov_b32_e32 v6, v230
	v_mov_b32_e32 v7, v231
	v_mov_b32_e32 v0, v232
	v_mov_b32_e32 v1, v233
	v_mov_b32_e32 v2, v234
	v_mov_b32_e32 v3, v235
; #define MFMA(a, b, c) __builtin_amdgcn_mfma_f32_16x16x32_bf16((a), (b), (c), 0, 0, 0)
; DI unsigned ordf(float f) { unsigned u = __float_as_uint(f); return (u & 0x80000000u) ? ~u : (u | 0x80000000u); }
; DI void peer_topk_wave(const Params& p, int item, unsigned* lds  ) {
;     ...
;     for (int ks = 0; ks < 4; ++ks) qf[ks] = *(const bf16x8*)&p.pq[(size_t)(row0 + r) * 2048 + h * 256 + pp * 128 + ks * 32 + kg * 8];
;     unsigned kk[32];
;     const u16* sk = p.subkb + (size_t)(h * 2 + pp) * 16384;
; #pragma unroll
;     for (int mt = 0; mt < 8; ++mt) {
;       f32x4 a = (f32x4){0.f, 0.f, 0.f, 0.f};
; #pragma unroll
;       for (int ks = 0; ks < 4; ++ks) {
;         bf16x8 kf = *(const bf16x8*)&sk[(mt * 16 + r) * 128 + ks * 32 + kg * 8];
;         a = MFMA(kf, qf[ks], a);
;       }
; #pragma unroll
;       for (int j = 0; j < 4; ++j) kk[mt * 4 + j] = (ordf(a[j]) & ~127u) | (unsigned)(mt * 16 + kg * 4 + j);
.Lp10q_done1:
	ds_bpermute_b32 v162, v112, v161
	v_readfirstlane_b32 s0, v86
	v_readfirstlane_b32 s1, v87
	s_nop 3
	s_add_u32 s0, s0, 0x8000
	s_addc_u32 s1, s1, 0
	s_add_u32 s2, s0, 0x0
	s_addc_u32 s3, s1, 0
	global_load_dwordx4 v[24:27], v20, s[2:3]
	global_load_dwordx4 v[28:31], v20, s[2:3] offset:64
	global_load_dwordx4 v[32:35], v20, s[2:3] offset:128
	global_load_dwordx4 v[36:39], v20, s[2:3] offset:192
	s_add_u32 s2, s0, 0x1000
	s_addc_u32 s3, s1, 0
	global_load_dwordx4 v[40:43], v20, s[2:3]
	global_load_dwordx4 v[44:47], v20, s[2:3] offset:64
	global_load_dwordx4 v[48:51], v20, s[2:3] offset:128
	global_load_dwordx4 v[52:55], v20, s[2:3] offset:192
	s_add_u32 s2, s0, 0x2000
	s_addc_u32 s3, s1, 0
	global_load_dwordx4 v[56:59], v20, s[2:3]
	global_load_dwordx4 v[60:63], v20, s[2:3] offset:64
	global_load_dwordx4 v[64:67], v20, s[2:3] offset:128
	global_load_dwordx4 v[68:71], v20, s[2:3] offset:192
	s_add_u32 s2, s0, 0x3000
	s_addc_u32 s3, s1, 0
	global_load_dwordx4 v[72:75], v20, s[2:3]
	global_load_dwordx4 v[76:79], v20, s[2:3] offset:64
	global_load_dwordx4 v[80:83], v20, s[2:3] offset:128
	s_waitcnt vmcnt(11) lgkmcnt(0)
	v_mfma_f32_16x16x32_bf16 v[190:193], v[24:27], v[12:15], 0
	v_mfma_f32_16x16x32_bf16 v[190:193], v[28:31], v[8:11], v[190:193]
	v_mfma_f32_16x16x32_bf16 v[190:193], v[32:35], v[4:7], v[190:193]
	v_mfma_f32_16x16x32_bf16 v[190:193], v[36:39], v[0:3], v[190:193]
	global_load_dwordx4 v[24:27], v20, s[2:3] offset:192
	s_add_u32 s2, s0, 0x4000
	s_addc_u32 s3, s1, 0
	global_load_dwordx4 v[28:31], v20, s[2:3]
	global_load_dwordx4 v[32:35], v20, s[2:3] offset:64
	global_load_dwordx4 v[36:39], v20, s[2:3] offset:128
	s_waitcnt vmcnt(11)
	v_mfma_f32_16x16x32_bf16 v[198:201], v[40:43], v[12:15], 0
	v_mfma_f32_16x16x32_bf16 v[198:201], v[44:47], v[8:11], v[198:201]
	v_mfma_f32_16x16x32_bf16 v[198:201], v[48:51], v[4:7], v[198:201]
	v_mfma_f32_16x16x32_bf16 v[198:201], v[52:55], v[0:3], v[198:201]
	global_load_dwordx4 v[40:43], v20, s[2:3] offset:192
	s_add_u32 s2, s0, 0x5000
	s_addc_u32 s3, s1, 0
	global_load_dwordx4 v[44:47], v20, s[2:3]
	global_load_dwordx4 v[48:51], v20, s[2:3] offset:64
	global_load_dwordx4 v[52:55], v20, s[2:3] offset:128
	s_nop 7
	s_nop 3
	v_ashrrev_i32_e32 v197, 31, v190
	v_or_b32_e32 v197, 0x80000000, v197
	v_xor_b32_e32 v197, v190, v197
	v_and_or_b32 v88, v197, s80, v170
	v_ashrrev_i32_e32 v202, 31, v191
	v_or_b32_e32 v202, 0x80000000, v202
	v_xor_b32_e32 v202, v191, v202
	v_and_or_b32 v89, v202, s80, v113
	v_ashrrev_i32_e32 v197, 31, v192
	v_or_b32_e32 v197, 0x80000000, v197
	v_xor_b32_e32 v197, v192, v197
	v_and_or_b32 v164, v197, s80, v114
	v_ashrrev_i32_e32 v202, 31, v193
	v_or_b32_e32 v202, 0x80000000, v202
	v_xor_b32_e32 v202, v193, v202
	v_and_or_b32 v165, v202, s80, v115
	s_waitcnt vmcnt(11)
	v_mfma_f32_16x16x32_bf16 v[190:193], v[56:59], v[12:15], 0
	v_mfma_f32_16x16x32_bf16 v[190:193], v[60:63], v[8:11], v[190:193]
	v_mfma_f32_16x16x32_bf16 v[190:193], v[64:67], v[4:7], v[190:193]
	v_mfma_f32_16x16x32_bf16 v[190:193], v[68:71], v[0:3], v[190:193]
	global_load_dwordx4 v[56:59], v20, s[2:3] offset:192
	s_add_u32 s2, s0, 0x6000
	s_addc_u32 s3, s1, 0
	global_load_dwordx4 v[60:63], v20, s[2:3]
	global_load_dwordx4 v[64:67], v20, s[2:3] offset:64
	global_load_dwordx4 v[68:71], v20, s[2:3] offset:128
	s_nop 7
	s_nop 3
	v_ashrrev_i32_e32 v197, 31, v198
	v_or_b32_e32 v197, 0x80000000, v197
	v_xor_b32_e32 v197, v198, v197
	v_and_or_b32 v166, v197, s80, v90
	v_ashrrev_i32_e32 v202, 31, v199
	v_or_b32_e32 v202, 0x80000000, v202
	v_xor_b32_e32 v202, v199, v202
	v_and_or_b32 v167, v202, s80, v116
	v_ashrrev_i32_e32 v197, 31, v200
	v_or_b32_e32 v197, 0x80000000, v197
	v_xor_b32_e32 v197, v200, v197
	v_and_or_b32 v168, v197, s80, v117
	v_ashrrev_i32_e32 v202, 31, v201
	v_or_b32_e32 v202, 0x80000000, v202
	v_xor_b32_e32 v202, v201, v202
	v_and_or_b32 v169, v202, s80, v118
	s_waitcnt vmcnt(11)
	v_mfma_f32_16x16x32_bf16 v[198:201], v[72:75], v[12:15], 0
	v_mfma_f32_16x16x32_bf16 v[198:201], v[76:79], v[8:11], v[198:201]
	v_mfma_f32_16x16x32_bf16 v[198:201], v[80:83], v[4:7], v[198:201]
	v_mfma_f32_16x16x32_bf16 v[198:201], v[24:27], v[0:3], v[198:201]
	global_load_dwordx4 v[72:75], v20, s[2:3] offset:192
	s_add_u32 s2, s0, 0x7000
	s_addc_u32 s3, s1, 0
	global_load_dwordx4 v[76:79], v20, s[2:3]
	global_load_dwordx4 v[80:83], v20, s[2:3] offset:64
	global_load_dwordx4 v[24:27], v20, s[2:3] offset:128
	s_nop 7
	s_nop 3
	v_ashrrev_i32_e32 v197, 31, v190
	v_or_b32_e32 v197, 0x80000000, v197
	v_xor_b32_e32 v197, v190, v197
	v_and_or_b32 v171, v197, s80, v91
	v_ashrrev_i32_e32 v202, 31, v191
	v_or_b32_e32 v202, 0x80000000, v202
	v_xor_b32_e32 v202, v191, v202
	v_and_or_b32 v172, v202, s80, v119
	v_ashrrev_i32_e32 v197, 31, v192
	v_or_b32_e32 v197, 0x80000000, v197
	v_xor_b32_e32 v197, v192, v197
	v_and_or_b32 v173, v197, s80, v120
	v_ashrrev_i32_e32 v202, 31, v193
	v_or_b32_e32 v202, 0x80000000, v202
	v_xor_b32_e32 v202, v193, v202
	v_and_or_b32 v176, v202, s80, v121
	s_waitcnt vmcnt(11)
	v_mfma_f32_16x16x32_bf16 v[190:193], v[28:31], v[12:15], 0
	v_mfma_f32_16x16x32_bf16 v[190:193], v[32:35], v[8:11], v[190:193]
	v_mfma_f32_16x16x32_bf16 v[190:193], v[36:39], v[4:7], v[190:193]
	v_mfma_f32_16x16x32_bf16 v[190:193], v[40:43], v[0:3], v[190:193]
	global_load_dwordx4 v[28:31], v20, s[2:3] offset:192
	s_nop 7
	s_nop 3
	v_ashrrev_i32_e32 v197, 31, v198
	v_or_b32_e32 v197, 0x80000000, v197
	v_xor_b32_e32 v197, v198, v197
	v_and_or_b32 v177, v197, s80, v92
	v_ashrrev_i32_e32 v202, 31, v199
	v_or_b32_e32 v202, 0x80000000, v202
	v_xor_b32_e32 v202, v199, v202
	v_and_or_b32 v178, v202, s80, v122
	v_ashrrev_i32_e32 v197, 31, v200
	v_or_b32_e32 v197, 0x80000000, v197
	v_xor_b32_e32 v197, v200, v197
	v_and_or_b32 v179, v197, s80, v123
	v_ashrrev_i32_e32 v202, 31, v201
	v_or_b32_e32 v202, 0x80000000, v202
	v_xor_b32_e32 v202, v201, v202
	v_and_or_b32 v180, v202, s80, v124
	s_waitcnt vmcnt(8)
; #define MFMA(a, b, c) __builtin_amdgcn_mfma_f32_16x16x32_bf16((a), (b), (c), 0, 0, 0)
; DI unsigned ordf(float f) { unsigned u = __float_as_uint(f); return (u & 0x80000000u) ? ~u : (u | 0x80000000u); }
; DI void peer_topk_wave(const Params& p, int item, unsigned* lds  ) {
;     ...
;   for (int pp = 0; pp < 2; ++pp) {
;     bf16x8 qf[4];
; #pragma unroll
;     for (int ks = 0; ks < 4; ++ks) qf[ks] = *(const bf16x8*)&p.pq[(size_t)(row0 + r) * 2048 + h * 256 + pp * 128 + ks * 32 + kg * 8];
;     ...
;     for (int mt = 0; mt < 8; ++mt) {
;       f32x4 a = (f32x4){0.f, 0.f, 0.f, 0.f};
; #pragma unroll
;       for (int ks = 0; ks < 4; ++ks) {
;         bf16x8 kf = *(const bf16x8*)&sk[(mt * 16 + r) * 128 + ks * 32 + kg * 8];
;         a = MFMA(kf, qf[ks], a);
;       }
; #pragma unroll
;       for (int j = 0; j < 4; ++j) kk[mt * 4 + j] = (ordf(a[j]) & ~127u) | (unsigned)(mt * 16 + kg * 4 + j);
;     }
; #pragma unroll
;     for (int rr = 0; rr < 16; ++rr) {
;       unsigned m = 0;
; #pragma unroll
;       for (int i = 0; i < 32; ++i) m = umax(m, kk[i]);
;       m = umax(m, (unsigned)__shfl_xor((int)m, 16));
;       m = umax(m, (unsigned)__shfl_xor((int)m, 32));
	v_mfma_f32_16x16x32_bf16 v[198:201], v[44:47], v[12:15], 0
	v_mfma_f32_16x16x32_bf16 v[198:201], v[48:51], v[8:11], v[198:201]
	v_mfma_f32_16x16x32_bf16 v[198:201], v[52:55], v[4:7], v[198:201]
	v_mfma_f32_16x16x32_bf16 v[198:201], v[56:59], v[0:3], v[198:201]
	s_nop 7
	s_nop 3
	v_ashrrev_i32_e32 v197, 31, v190
	v_or_b32_e32 v197, 0x80000000, v197
	v_xor_b32_e32 v197, v190, v197
	v_and_or_b32 v181, v197, s80, v93
	v_ashrrev_i32_e32 v202, 31, v191
	v_or_b32_e32 v202, 0x80000000, v202
	v_xor_b32_e32 v202, v191, v202
	v_and_or_b32 v182, v202, s80, v125
	v_ashrrev_i32_e32 v197, 31, v192
	v_or_b32_e32 v197, 0x80000000, v197
	v_xor_b32_e32 v197, v192, v197
	v_and_or_b32 v183, v197, s80, v126
	v_ashrrev_i32_e32 v202, 31, v193
	v_or_b32_e32 v202, 0x80000000, v202
	v_xor_b32_e32 v202, v193, v202
	v_and_or_b32 v184, v202, s80, v127
	s_waitcnt vmcnt(4)
	v_mfma_f32_16x16x32_bf16 v[190:193], v[60:63], v[12:15], 0
	v_mfma_f32_16x16x32_bf16 v[190:193], v[64:67], v[8:11], v[190:193]
	v_mfma_f32_16x16x32_bf16 v[190:193], v[68:71], v[4:7], v[190:193]
	v_mfma_f32_16x16x32_bf16 v[190:193], v[72:75], v[0:3], v[190:193]
	s_nop 7
	s_nop 3
	v_ashrrev_i32_e32 v197, 31, v198
	v_or_b32_e32 v197, 0x80000000, v197
	v_xor_b32_e32 v197, v198, v197
	v_and_or_b32 v185, v197, s80, v94
	v_ashrrev_i32_e32 v202, 31, v199
	v_or_b32_e32 v202, 0x80000000, v202
	v_xor_b32_e32 v202, v199, v202
	v_and_or_b32 v186, v202, s80, v129
	v_ashrrev_i32_e32 v197, 31, v200
	v_or_b32_e32 v197, 0x80000000, v197
	v_xor_b32_e32 v197, v200, v197
	v_and_or_b32 v187, v197, s80, v130
	v_ashrrev_i32_e32 v202, 31, v201
	v_or_b32_e32 v202, 0x80000000, v202
	v_xor_b32_e32 v202, v201, v202
	v_and_or_b32 v188, v202, s80, v131
	s_waitcnt vmcnt(0)
	v_mfma_f32_16x16x32_bf16 v[198:201], v[76:79], v[12:15], 0
	v_mfma_f32_16x16x32_bf16 v[198:201], v[80:83], v[8:11], v[198:201]
	v_mfma_f32_16x16x32_bf16 v[198:201], v[24:27], v[4:7], v[198:201]
	v_mfma_f32_16x16x32_bf16 v[198:201], v[28:31], v[0:3], v[198:201]
	s_nop 7
	s_nop 3
	v_ashrrev_i32_e32 v197, 31, v190
	v_or_b32_e32 v197, 0x80000000, v197
	v_xor_b32_e32 v197, v190, v197
	v_and_or_b32 v189, v197, s80, v95
	v_ashrrev_i32_e32 v202, 31, v191
	v_or_b32_e32 v202, 0x80000000, v202
	v_xor_b32_e32 v202, v191, v202
	v_and_or_b32 v194, v202, s80, v135
	v_ashrrev_i32_e32 v197, 31, v192
	v_or_b32_e32 v197, 0x80000000, v197
	v_xor_b32_e32 v197, v192, v197
	v_and_or_b32 v195, v197, s80, v136
	v_ashrrev_i32_e32 v202, 31, v193
	v_or_b32_e32 v202, 0x80000000, v202
	v_xor_b32_e32 v202, v193, v202
	v_and_or_b32 v196, v202, s80, v137
	s_nop 7
	s_nop 3
	v_ashrrev_i32_e32 v197, 31, v198
	v_or_b32_e32 v197, 0x80000000, v197
	v_xor_b32_e32 v197, v198, v197
	v_and_or_b32 v4, v197, s80, v96
	v_ashrrev_i32_e32 v202, 31, v199
	v_or_b32_e32 v202, 0x80000000, v202
	v_xor_b32_e32 v202, v199, v202
	v_and_or_b32 v1, v202, s80, v138
	v_ashrrev_i32_e32 v197, 31, v200
	v_or_b32_e32 v197, 0x80000000, v197
	v_xor_b32_e32 v197, v200, v197
	v_and_or_b32 v2, v197, s80, v139
	v_ashrrev_i32_e32 v202, 31, v201
	v_or_b32_e32 v202, 0x80000000, v202
	v_xor_b32_e32 v202, v201, v202
	v_and_or_b32 v3, v202, s80, v140
	global_load_dwordx4 v[204:207], v[236:237], off
	global_load_dwordx4 v[208:211], v[236:237], off offset:64
	global_load_dwordx4 v[212:215], v[236:237], off offset:128
	global_load_dwordx4 v[216:219], v[236:237], off offset:192
	global_load_dwordx4 v[220:223], v[236:237], off offset:256
	global_load_dwordx4 v[224:227], v[236:237], off offset:320
	global_load_dwordx4 v[228:231], v[236:237], off offset:384
	global_load_dwordx4 v[232:235], v[236:237], off offset:448
	s_mov_b32 s88, 1
	v_max_u32_e32 v0, v88, v89
	v_max3_u32 v0, v0, v164, v165
	v_max3_u32 v0, v0, v166, v167
	v_max3_u32 v0, v0, v168, v169
	v_max3_u32 v0, v0, v171, v172
	v_max3_u32 v0, v0, v173, v176
	v_max3_u32 v0, v0, v177, v178
	v_max3_u32 v0, v0, v179, v180
	v_max3_u32 v0, v0, v181, v182
	v_max3_u32 v0, v0, v183, v184
	v_max3_u32 v0, v0, v185, v186
	v_max3_u32 v0, v0, v187, v188
	v_max3_u32 v0, v0, v189, v194
	v_max3_u32 v0, v0, v195, v196
	v_max3_u32 v0, v0, v4, v1
	v_max3_u32 v0, v0, v2, v3
	v_mov_b32_e32 v5, v0
	s_nop 1
	v_permlane16_swap_b32 v0, v5
	s_nop 1
	s_waitcnt lgkmcnt(0)
	v_max_u32_e32 v0, v0, v5
	v_mov_b32_e32 v5, v0
	s_nop 1
	v_permlane32_swap_b32 v0, v5
	s_nop 1
	s_waitcnt lgkmcnt(0)
; DI void peer_topk_wave(const Params& p, int item, unsigned* lds  ) {
;     ...
; #pragma unroll
;     for (int rr = 0; rr < 16; ++rr) {
;       unsigned m = 0;
; #pragma unroll
;       for (int i = 0; i < 32; ++i) m = umax(m, kk[i]);
;       m = umax(m, (unsigned)__shfl_xor((int)m, 16));
;       m = umax(m, (unsigned)__shfl_xor((int)m, 32));
;       win[pp][rr] = m;
; #pragma unroll
;       for (int i = 0; i < 32; ++i) kk[i] = (kk[i] == m) ? 0u : kk[i];
;     }
	v_max_u32_e32 v0, v0, v5
	v_cmp_ne_u32_e32 vcc, v88, v0
	v_cmp_ne_u32_e64 s[98:99], v89, v0
	v_cmp_ne_u32_e64 s[100:101], v164, v0
	v_cndmask_b32_e32 v5, 0, v88, vcc
	v_cndmask_b32_e64 v6, 0, v89, s[98:99]
	v_cndmask_b32_e64 v7, 0, v164, s[100:101]
	v_cmp_ne_u32_e32 vcc, v165, v0
	v_cmp_ne_u32_e64 s[98:99], v166, v0
	v_cmp_ne_u32_e64 s[100:101], v167, v0
	v_cndmask_b32_e32 v8, 0, v165, vcc
	v_cndmask_b32_e64 v9, 0, v166, s[98:99]
	v_cndmask_b32_e64 v10, 0, v167, s[100:101]
	v_cmp_ne_u32_e32 vcc, v168, v0
	v_cmp_ne_u32_e64 s[98:99], v169, v0
	v_cmp_ne_u32_e64 s[100:101], v171, v0
	v_cndmask_b32_e32 v11, 0, v168, vcc
	v_cndmask_b32_e64 v12, 0, v169, s[98:99]
	v_cndmask_b32_e64 v13, 0, v171, s[100:101]
	v_cmp_ne_u32_e32 vcc, v172, v0
	v_cmp_ne_u32_e64 s[98:99], v173, v0
	v_cmp_ne_u32_e64 s[100:101], v176, v0
	v_cndmask_b32_e32 v14, 0, v172, vcc
	v_cndmask_b32_e64 v15, 0, v173, s[98:99]
	v_cndmask_b32_e64 v86, 0, v176, s[100:101]
	v_cmp_ne_u32_e32 vcc, v177, v0
	v_cmp_ne_u32_e64 s[98:99], v178, v0
	v_cmp_ne_u32_e64 s[100:101], v179, v0
	v_cndmask_b32_e32 v87, 0, v177, vcc
	v_cndmask_b32_e64 v88, 0, v178, s[98:99]
	v_cndmask_b32_e64 v89, 0, v179, s[100:101]
	v_cmp_ne_u32_e32 vcc, v180, v0
	v_cmp_ne_u32_e64 s[98:99], v181, v0
	v_cmp_ne_u32_e64 s[100:101], v182, v0
	v_cndmask_b32_e32 v164, 0, v180, vcc
	v_cndmask_b32_e64 v165, 0, v181, s[98:99]
	v_cndmask_b32_e64 v166, 0, v182, s[100:101]
	v_cmp_ne_u32_e32 vcc, v183, v0
	v_cmp_ne_u32_e64 s[98:99], v184, v0
	v_cmp_ne_u32_e64 s[100:101], v185, v0
	v_cndmask_b32_e32 v167, 0, v183, vcc
	v_cndmask_b32_e64 v168, 0, v184, s[98:99]
	v_cndmask_b32_e64 v169, 0, v185, s[100:101]
	v_cmp_ne_u32_e32 vcc, v186, v0
	v_cmp_ne_u32_e64 s[98:99], v187, v0
	v_cmp_ne_u32_e64 s[100:101], v188, v0
	v_cndmask_b32_e32 v171, 0, v186, vcc
	v_cndmask_b32_e64 v172, 0, v187, s[98:99]
	v_cndmask_b32_e64 v173, 0, v188, s[100:101]
	v_cmp_ne_u32_e32 vcc, v189, v0
	v_cmp_ne_u32_e64 s[98:99], v194, v0
	v_cmp_ne_u32_e64 s[100:101], v195, v0
	v_cndmask_b32_e32 v176, 0, v189, vcc
	v_cndmask_b32_e64 v177, 0, v194, s[98:99]
	v_cndmask_b32_e64 v178, 0, v195, s[100:101]
	v_cmp_ne_u32_e32 vcc, v196, v0
	v_cmp_ne_u32_e64 s[98:99], v4, v0
	v_cmp_ne_u32_e64 s[100:101], v1, v0
	v_cndmask_b32_e32 v179, 0, v196, vcc
	v_cndmask_b32_e64 v4, 0, v4, s[98:99]
	v_cndmask_b32_e64 v180, 0, v1, s[100:101]
	v_max_u32_e32 v1, v5, v6
	v_max3_u32 v1, v1, v7, v8
	v_max3_u32 v1, v1, v9, v10
	v_max3_u32 v1, v1, v11, v12
	v_max3_u32 v1, v1, v13, v14
	v_max3_u32 v1, v1, v15, v86
	v_max3_u32 v1, v1, v87, v88
	v_max3_u32 v1, v1, v89, v164
	v_max3_u32 v1, v1, v165, v166
	v_max3_u32 v1, v1, v167, v168
	v_max3_u32 v1, v1, v169, v171
	v_max3_u32 v1, v1, v172, v173
	v_cmp_ne_u32_e32 vcc, v2, v0
	v_max3_u32 v1, v1, v176, v177
	v_max3_u32 v1, v1, v178, v179
	v_cndmask_b32_e32 v2, 0, v2, vcc
	v_cmp_ne_u32_e64 s[98:99], v3, v0
	v_max3_u32 v1, v1, v4, v180
	s_nop 0
	v_cndmask_b32_e64 v3, 0, v3, s[98:99]
	v_max3_u32 v1, v1, v2, v3
	v_mov_b32_e32 v181, v1
	s_nop 1
	v_permlane16_swap_b32 v1, v181
	s_nop 1
	s_waitcnt lgkmcnt(0)
	v_max_u32_e32 v1, v1, v181
	v_mov_b32_e32 v181, v1
	s_nop 1
	v_permlane32_swap_b32 v1, v181
	s_nop 1
	s_waitcnt lgkmcnt(0)
	v_max_u32_e32 v1, v1, v181
	v_cmp_ne_u32_e32 vcc, v5, v1
	v_cmp_ne_u32_e64 s[98:99], v6, v1
	v_cmp_ne_u32_e64 s[100:101], v7, v1
	v_cndmask_b32_e32 v5, 0, v5, vcc
	v_cndmask_b32_e64 v6, 0, v6, s[98:99]
	v_cndmask_b32_e64 v7, 0, v7, s[100:101]
	v_cmp_ne_u32_e32 vcc, v8, v1
	v_cmp_ne_u32_e64 s[98:99], v9, v1
	v_cmp_ne_u32_e64 s[100:101], v10, v1
	v_cndmask_b32_e32 v8, 0, v8, vcc
	v_cndmask_b32_e64 v9, 0, v9, s[98:99]
	v_cndmask_b32_e64 v10, 0, v10, s[100:101]
	v_cmp_ne_u32_e32 vcc, v11, v1
	v_cmp_ne_u32_e64 s[98:99], v12, v1
	v_cmp_ne_u32_e64 s[100:101], v13, v1
	v_cndmask_b32_e32 v11, 0, v11, vcc
	v_cndmask_b32_e64 v12, 0, v12, s[98:99]
	v_cndmask_b32_e64 v13, 0, v13, s[100:101]
	v_cmp_ne_u32_e32 vcc, v14, v1
	v_cmp_ne_u32_e64 s[98:99], v15, v1
	v_cmp_ne_u32_e64 s[100:101], v86, v1
	v_cndmask_b32_e32 v14, 0, v14, vcc
	v_cndmask_b32_e64 v15, 0, v15, s[98:99]
	v_cndmask_b32_e64 v86, 0, v86, s[100:101]
	v_cmp_ne_u32_e32 vcc, v87, v1
	v_cmp_ne_u32_e64 s[98:99], v88, v1
	v_cmp_ne_u32_e64 s[100:101], v89, v1
	v_cndmask_b32_e32 v87, 0, v87, vcc
	v_cndmask_b32_e64 v88, 0, v88, s[98:99]
	v_cndmask_b32_e64 v89, 0, v89, s[100:101]
	v_cmp_ne_u32_e32 vcc, v164, v1
	v_cmp_ne_u32_e64 s[98:99], v165, v1
	v_cmp_ne_u32_e64 s[100:101], v166, v1
	v_cndmask_b32_e32 v164, 0, v164, vcc
	v_cndmask_b32_e64 v165, 0, v165, s[98:99]
	v_cndmask_b32_e64 v166, 0, v166, s[100:101]
	v_cmp_ne_u32_e32 vcc, v167, v1
	v_cmp_ne_u32_e64 s[98:99], v168, v1
	v_cmp_ne_u32_e64 s[100:101], v169, v1
	v_cndmask_b32_e32 v167, 0, v167, vcc
	v_cndmask_b32_e64 v168, 0, v168, s[98:99]
	v_cndmask_b32_e64 v169, 0, v169, s[100:101]
	v_cmp_ne_u32_e32 vcc, v171, v1
	v_cmp_ne_u32_e64 s[98:99], v172, v1
	v_cmp_ne_u32_e64 s[100:101], v173, v1
	v_cndmask_b32_e32 v171, 0, v171, vcc
	v_cndmask_b32_e64 v172, 0, v172, s[98:99]
	v_cndmask_b32_e64 v173, 0, v173, s[100:101]
	v_cmp_ne_u32_e32 vcc, v176, v1
	v_cmp_ne_u32_e64 s[98:99], v177, v1
	v_cmp_ne_u32_e64 s[100:101], v178, v1
	v_cndmask_b32_e32 v176, 0, v176, vcc
	v_cndmask_b32_e64 v177, 0, v177, s[98:99]
	v_cndmask_b32_e64 v178, 0, v178, s[100:101]
	v_cmp_ne_u32_e32 vcc, v179, v1
	v_cmp_ne_u32_e64 s[98:99], v4, v1
	v_cmp_ne_u32_e64 s[100:101], v180, v1
	v_cndmask_b32_e32 v179, 0, v179, vcc
	v_cndmask_b32_e64 v4, 0, v4, s[98:99]
	v_cndmask_b32_e64 v180, 0, v180, s[100:101]
	v_cmp_ne_u32_e32 vcc, v2, v1
	v_cmp_ne_u32_e64 s[98:99], v3, v1
	s_nop 0
	v_cndmask_b32_e32 v181, 0, v2, vcc
	v_max_u32_e32 v2, v5, v6
	v_max3_u32 v2, v2, v7, v8
	v_max3_u32 v2, v2, v9, v10
	v_max3_u32 v2, v2, v11, v12
	v_max3_u32 v2, v2, v13, v14
	v_max3_u32 v2, v2, v15, v86
	v_max3_u32 v2, v2, v87, v88
	v_max3_u32 v2, v2, v89, v164
	v_max3_u32 v2, v2, v165, v166
	v_max3_u32 v2, v2, v167, v168
	v_max3_u32 v2, v2, v169, v171
	v_max3_u32 v2, v2, v172, v173
	v_max3_u32 v2, v2, v176, v177
	v_max3_u32 v2, v2, v178, v179
	v_max3_u32 v2, v2, v4, v180
	v_cndmask_b32_e64 v3, 0, v3, s[98:99]
	v_max3_u32 v2, v2, v181, v3
	v_mov_b32_e32 v182, v2
	s_nop 1
	v_permlane16_swap_b32 v2, v182
	s_nop 1
	s_waitcnt lgkmcnt(0)
; DI void peer_topk_wave(const Params& p, int item, unsigned* lds  ) {
;     ...
; #pragma unroll
;     for (int rr = 0; rr < 16; ++rr) {
;       unsigned m = 0;
; #pragma unroll
;       for (int i = 0; i < 32; ++i) m = umax(m, kk[i]);
;       m = umax(m, (unsigned)__shfl_xor((int)m, 16));
;       m = umax(m, (unsigned)__shfl_xor((int)m, 32));
;       win[pp][rr] = m;
; #pragma unroll
;       for (int i = 0; i < 32; ++i) kk[i] = (kk[i] == m) ? 0u : kk[i];
;     }
	v_max_u32_e32 v2, v2, v182
	v_mov_b32_e32 v182, v2
	s_nop 1
	v_permlane32_swap_b32 v2, v182
	s_nop 1
	s_waitcnt lgkmcnt(0)
	v_max_u32_e32 v2, v2, v182
	v_cmp_ne_u32_e32 vcc, v5, v2
	v_cmp_ne_u32_e64 s[98:99], v6, v2
	v_cmp_ne_u32_e64 s[100:101], v7, v2
	v_cndmask_b32_e32 v5, 0, v5, vcc
	v_cndmask_b32_e64 v6, 0, v6, s[98:99]
	v_cndmask_b32_e64 v7, 0, v7, s[100:101]
	v_cmp_ne_u32_e32 vcc, v8, v2
	v_cmp_ne_u32_e64 s[98:99], v9, v2
	v_cmp_ne_u32_e64 s[100:101], v10, v2
	v_cndmask_b32_e32 v8, 0, v8, vcc
	v_cndmask_b32_e64 v9, 0, v9, s[98:99]
	v_cndmask_b32_e64 v10, 0, v10, s[100:101]
	v_cmp_ne_u32_e32 vcc, v11, v2
	v_cmp_ne_u32_e64 s[98:99], v12, v2
	v_cmp_ne_u32_e64 s[100:101], v13, v2
	v_cndmask_b32_e32 v11, 0, v11, vcc
	v_cndmask_b32_e64 v12, 0, v12, s[98:99]
	v_cndmask_b32_e64 v13, 0, v13, s[100:101]
	v_cmp_ne_u32_e32 vcc, v14, v2
	v_cmp_ne_u32_e64 s[98:99], v15, v2
	v_cmp_ne_u32_e64 s[100:101], v86, v2
	v_cndmask_b32_e32 v14, 0, v14, vcc
	v_cndmask_b32_e64 v15, 0, v15, s[98:99]
	v_cndmask_b32_e64 v86, 0, v86, s[100:101]
	v_cmp_ne_u32_e32 vcc, v87, v2
	v_cmp_ne_u32_e64 s[98:99], v88, v2
	v_cmp_ne_u32_e64 s[100:101], v89, v2
	v_cndmask_b32_e32 v87, 0, v87, vcc
	v_cndmask_b32_e64 v88, 0, v88, s[98:99]
	v_cndmask_b32_e64 v89, 0, v89, s[100:101]
	v_cmp_ne_u32_e32 vcc, v164, v2
	v_cmp_ne_u32_e64 s[98:99], v165, v2
	v_cmp_ne_u32_e64 s[100:101], v166, v2
	v_cndmask_b32_e32 v164, 0, v164, vcc
	v_cndmask_b32_e64 v165, 0, v165, s[98:99]
	v_cndmask_b32_e64 v166, 0, v166, s[100:101]
	v_cmp_ne_u32_e32 vcc, v167, v2
	v_cmp_ne_u32_e64 s[98:99], v168, v2
	v_cmp_ne_u32_e64 s[100:101], v169, v2
	v_cndmask_b32_e32 v167, 0, v167, vcc
	v_cndmask_b32_e64 v168, 0, v168, s[98:99]
	v_cndmask_b32_e64 v169, 0, v169, s[100:101]
	v_cmp_ne_u32_e32 vcc, v171, v2
	v_cmp_ne_u32_e64 s[98:99], v172, v2
	v_cmp_ne_u32_e64 s[100:101], v173, v2
	v_cndmask_b32_e32 v171, 0, v171, vcc
	v_cndmask_b32_e64 v172, 0, v172, s[98:99]
	v_cndmask_b32_e64 v173, 0, v173, s[100:101]
	v_cmp_ne_u32_e32 vcc, v176, v2
	v_cmp_ne_u32_e64 s[98:99], v177, v2
	v_cmp_ne_u32_e64 s[100:101], v178, v2
	v_cndmask_b32_e32 v176, 0, v176, vcc
	v_cndmask_b32_e64 v177, 0, v177, s[98:99]
	v_cndmask_b32_e64 v178, 0, v178, s[100:101]
	v_cmp_ne_u32_e32 vcc, v179, v2
	v_cmp_ne_u32_e64 s[98:99], v4, v2
	v_cmp_ne_u32_e64 s[100:101], v180, v2
	v_cndmask_b32_e32 v179, 0, v179, vcc
	v_cndmask_b32_e64 v4, 0, v4, s[98:99]
	v_cndmask_b32_e64 v180, 0, v180, s[100:101]
	v_cmp_ne_u32_e32 vcc, v181, v2
	v_cmp_ne_u32_e64 s[98:99], v3, v2
	s_nop 0
	v_cndmask_b32_e32 v181, 0, v181, vcc
	v_cndmask_b32_e64 v182, 0, v3, s[98:99]
	v_max_u32_e32 v3, v5, v6
	v_max3_u32 v3, v3, v7, v8
	v_max3_u32 v3, v3, v9, v10
	v_max3_u32 v3, v3, v11, v12
	v_max3_u32 v3, v3, v13, v14
	v_max3_u32 v3, v3, v15, v86
	v_max3_u32 v3, v3, v87, v88
	v_max3_u32 v3, v3, v89, v164
	v_max3_u32 v3, v3, v165, v166
	v_max3_u32 v3, v3, v167, v168
	v_max3_u32 v3, v3, v169, v171
	v_max3_u32 v3, v3, v172, v173
	v_max3_u32 v3, v3, v176, v177
	v_max3_u32 v3, v3, v178, v179
	v_max3_u32 v3, v3, v4, v180
	v_max3_u32 v3, v3, v181, v182
	v_mov_b32_e32 v183, v3
	s_nop 1
	v_permlane16_swap_b32 v3, v183
	s_nop 1
	s_waitcnt lgkmcnt(0)
	v_max_u32_e32 v3, v3, v183
	v_mov_b32_e32 v183, v3
	s_nop 1
	v_permlane32_swap_b32 v3, v183
	s_nop 1
	s_waitcnt lgkmcnt(0)
	v_max_u32_e32 v3, v3, v183
	v_cmp_ne_u32_e32 vcc, v5, v3
	v_cmp_ne_u32_e64 s[98:99], v6, v3
	v_cmp_ne_u32_e64 s[100:101], v7, v3
	v_cndmask_b32_e32 v5, 0, v5, vcc
	v_cndmask_b32_e64 v6, 0, v6, s[98:99]
	v_cndmask_b32_e64 v7, 0, v7, s[100:101]
	v_cmp_ne_u32_e32 vcc, v8, v3
	v_cmp_ne_u32_e64 s[98:99], v9, v3
	v_cmp_ne_u32_e64 s[100:101], v10, v3
	v_cndmask_b32_e32 v8, 0, v8, vcc
	v_cndmask_b32_e64 v9, 0, v9, s[98:99]
	v_cndmask_b32_e64 v10, 0, v10, s[100:101]
	v_cmp_ne_u32_e32 vcc, v11, v3
	v_cmp_ne_u32_e64 s[98:99], v12, v3
	v_cmp_ne_u32_e64 s[100:101], v13, v3
	v_cndmask_b32_e32 v11, 0, v11, vcc
	v_cndmask_b32_e64 v12, 0, v12, s[98:99]
	v_cndmask_b32_e64 v13, 0, v13, s[100:101]
	v_cmp_ne_u32_e32 vcc, v14, v3
	v_cmp_ne_u32_e64 s[98:99], v15, v3
	v_cmp_ne_u32_e64 s[100:101], v86, v3
	v_cndmask_b32_e32 v14, 0, v14, vcc
	v_cndmask_b32_e64 v15, 0, v15, s[98:99]
	v_cndmask_b32_e64 v86, 0, v86, s[100:101]
	v_cmp_ne_u32_e32 vcc, v87, v3
	v_cmp_ne_u32_e64 s[98:99], v88, v3
	v_cmp_ne_u32_e64 s[100:101], v89, v3
	v_cndmask_b32_e32 v87, 0, v87, vcc
	v_cndmask_b32_e64 v88, 0, v88, s[98:99]
	v_cndmask_b32_e64 v89, 0, v89, s[100:101]
	v_cmp_ne_u32_e32 vcc, v164, v3
	v_cmp_ne_u32_e64 s[98:99], v165, v3
	v_cmp_ne_u32_e64 s[100:101], v166, v3
	v_cndmask_b32_e32 v164, 0, v164, vcc
	v_cndmask_b32_e64 v165, 0, v165, s[98:99]
	v_cndmask_b32_e64 v166, 0, v166, s[100:101]
	v_cmp_ne_u32_e32 vcc, v167, v3
	v_cmp_ne_u32_e64 s[98:99], v168, v3
	v_cmp_ne_u32_e64 s[100:101], v169, v3
	v_cndmask_b32_e32 v167, 0, v167, vcc
	v_cndmask_b32_e64 v168, 0, v168, s[98:99]
	v_cndmask_b32_e64 v169, 0, v169, s[100:101]
	v_cmp_ne_u32_e32 vcc, v171, v3
	v_cmp_ne_u32_e64 s[98:99], v172, v3
	v_cmp_ne_u32_e64 s[100:101], v173, v3
	v_cndmask_b32_e32 v171, 0, v171, vcc
	v_cndmask_b32_e64 v172, 0, v172, s[98:99]
	v_cndmask_b32_e64 v173, 0, v173, s[100:101]
	v_cmp_ne_u32_e32 vcc, v176, v3
	v_cmp_ne_u32_e64 s[98:99], v177, v3
	v_cmp_ne_u32_e64 s[100:101], v178, v3
	v_cndmask_b32_e32 v176, 0, v176, vcc
	v_cndmask_b32_e64 v177, 0, v177, s[98:99]
	v_cndmask_b32_e64 v178, 0, v178, s[100:101]
	v_cmp_ne_u32_e32 vcc, v179, v3
	v_cmp_ne_u32_e64 s[98:99], v4, v3
	v_cmp_ne_u32_e64 s[100:101], v180, v3
	v_cndmask_b32_e32 v179, 0, v179, vcc
	v_cndmask_b32_e64 v183, 0, v4, s[98:99]
	v_max_u32_e32 v4, v5, v6
	v_max3_u32 v4, v4, v7, v8
	v_max3_u32 v4, v4, v9, v10
	v_max3_u32 v4, v4, v11, v12
	v_max3_u32 v4, v4, v13, v14
	v_max3_u32 v4, v4, v15, v86
	v_max3_u32 v4, v4, v87, v88
	v_max3_u32 v4, v4, v89, v164
	v_max3_u32 v4, v4, v165, v166
	v_max3_u32 v4, v4, v167, v168
	v_max3_u32 v4, v4, v169, v171
	v_max3_u32 v4, v4, v172, v173
	v_max3_u32 v4, v4, v176, v177
	v_cndmask_b32_e64 v180, 0, v180, s[100:101]
	v_cmp_ne_u32_e32 vcc, v181, v3
	v_max3_u32 v4, v4, v178, v179
	v_max3_u32 v4, v4, v183, v180
	v_cndmask_b32_e32 v181, 0, v181, vcc
	v_cmp_ne_u32_e64 s[98:99], v182, v3
	s_nop 0
	s_nop 0
	v_cndmask_b32_e64 v182, 0, v182, s[98:99]
	v_max3_u32 v4, v4, v181, v182
	v_mov_b32_e32 v184, v4
	s_nop 1
	v_permlane16_swap_b32 v4, v184
	s_nop 1
	s_waitcnt lgkmcnt(0)
; DI void peer_topk_wave(const Params& p, int item, unsigned* lds  ) {
;     ...
; #pragma unroll
;     for (int rr = 0; rr < 16; ++rr) {
;       unsigned m = 0;
; #pragma unroll
;       for (int i = 0; i < 32; ++i) m = umax(m, kk[i]);
;       m = umax(m, (unsigned)__shfl_xor((int)m, 16));
;       m = umax(m, (unsigned)__shfl_xor((int)m, 32));
;       win[pp][rr] = m;
; #pragma unroll
;       for (int i = 0; i < 32; ++i) kk[i] = (kk[i] == m) ? 0u : kk[i];
;     }
	v_max_u32_e32 v4, v4, v184
	v_mov_b32_e32 v184, v4
	s_nop 1
	v_permlane32_swap_b32 v4, v184
	s_nop 1
	s_waitcnt lgkmcnt(0)
	v_max_u32_e32 v4, v4, v184
	v_cmp_ne_u32_e32 vcc, v5, v4
	v_cmp_ne_u32_e64 s[98:99], v6, v4
	v_cmp_ne_u32_e64 s[100:101], v7, v4
	v_cndmask_b32_e32 v184, 0, v5, vcc
	v_cndmask_b32_e64 v6, 0, v6, s[98:99]
	v_max_u32_e32 v5, v184, v6
	v_cndmask_b32_e64 v7, 0, v7, s[100:101]
	v_cmp_ne_u32_e32 vcc, v8, v4
	v_cmp_ne_u32_e64 s[98:99], v9, v4
	v_cmp_ne_u32_e64 s[100:101], v10, v4
	v_cndmask_b32_e32 v8, 0, v8, vcc
	v_max3_u32 v5, v5, v7, v8
	v_cndmask_b32_e64 v9, 0, v9, s[98:99]
	v_cndmask_b32_e64 v10, 0, v10, s[100:101]
	v_cmp_ne_u32_e32 vcc, v11, v4
	v_max3_u32 v5, v5, v9, v10
	v_cmp_ne_u32_e64 s[98:99], v12, v4
	v_cndmask_b32_e32 v11, 0, v11, vcc
	v_cmp_ne_u32_e64 s[100:101], v13, v4
	v_cndmask_b32_e64 v12, 0, v12, s[98:99]
	v_max3_u32 v5, v5, v11, v12
	v_cndmask_b32_e64 v13, 0, v13, s[100:101]
	v_cmp_ne_u32_e32 vcc, v14, v4
	v_cmp_ne_u32_e64 s[98:99], v15, v4
	v_cmp_ne_u32_e64 s[100:101], v86, v4
	v_cndmask_b32_e32 v14, 0, v14, vcc
	v_max3_u32 v5, v5, v13, v14
	v_cndmask_b32_e64 v15, 0, v15, s[98:99]
	v_cndmask_b32_e64 v86, 0, v86, s[100:101]
	v_cmp_ne_u32_e32 vcc, v87, v4
	v_max3_u32 v5, v5, v15, v86
	v_cmp_ne_u32_e64 s[98:99], v88, v4
	v_cndmask_b32_e32 v87, 0, v87, vcc
	v_cmp_ne_u32_e64 s[100:101], v89, v4
	v_cndmask_b32_e64 v88, 0, v88, s[98:99]
	v_max3_u32 v5, v5, v87, v88
	v_cndmask_b32_e64 v89, 0, v89, s[100:101]
	v_cmp_ne_u32_e32 vcc, v164, v4
	v_cmp_ne_u32_e64 s[98:99], v165, v4
	v_cmp_ne_u32_e64 s[100:101], v166, v4
	v_cndmask_b32_e32 v164, 0, v164, vcc
	v_max3_u32 v5, v5, v89, v164
	v_cndmask_b32_e64 v165, 0, v165, s[98:99]
	v_cndmask_b32_e64 v166, 0, v166, s[100:101]
	v_cmp_ne_u32_e32 vcc, v167, v4
	v_max3_u32 v5, v5, v165, v166
	v_cmp_ne_u32_e64 s[98:99], v168, v4
	v_cndmask_b32_e32 v167, 0, v167, vcc
	v_cmp_ne_u32_e64 s[100:101], v169, v4
	v_cndmask_b32_e64 v168, 0, v168, s[98:99]
	v_max3_u32 v5, v5, v167, v168
	v_cndmask_b32_e64 v169, 0, v169, s[100:101]
	v_cmp_ne_u32_e32 vcc, v171, v4
	v_cmp_ne_u32_e64 s[98:99], v172, v4
	v_cmp_ne_u32_e64 s[100:101], v173, v4
	v_cndmask_b32_e32 v171, 0, v171, vcc
	v_max3_u32 v5, v5, v169, v171
	v_cndmask_b32_e64 v172, 0, v172, s[98:99]
	v_cndmask_b32_e64 v173, 0, v173, s[100:101]
	v_cmp_ne_u32_e32 vcc, v176, v4
	v_max3_u32 v5, v5, v172, v173
	v_cmp_ne_u32_e64 s[98:99], v177, v4
	v_cndmask_b32_e32 v176, 0, v176, vcc
	v_cmp_ne_u32_e64 s[100:101], v178, v4
	v_cndmask_b32_e64 v177, 0, v177, s[98:99]
	v_max3_u32 v5, v5, v176, v177
	v_cndmask_b32_e64 v178, 0, v178, s[100:101]
	v_cmp_ne_u32_e32 vcc, v179, v4
	v_cmp_ne_u32_e64 s[98:99], v183, v4
	v_cmp_ne_u32_e64 s[100:101], v180, v4
	v_cndmask_b32_e32 v179, 0, v179, vcc
	v_max3_u32 v5, v5, v178, v179
	v_cndmask_b32_e64 v183, 0, v183, s[98:99]
	v_cndmask_b32_e64 v180, 0, v180, s[100:101]
	v_cmp_ne_u32_e32 vcc, v181, v4
	v_max3_u32 v5, v5, v183, v180
	v_cmp_ne_u32_e64 s[98:99], v182, v4
	v_cndmask_b32_e32 v181, 0, v181, vcc
	s_nop 0
	v_cndmask_b32_e64 v182, 0, v182, s[98:99]
	v_max3_u32 v5, v5, v181, v182
	v_mov_b32_e32 v185, v5
	s_nop 1
	v_permlane16_swap_b32 v5, v185
	s_nop 1
	s_waitcnt lgkmcnt(0)
	v_max_u32_e32 v5, v5, v185
	v_mov_b32_e32 v185, v5
	s_nop 1
	v_permlane32_swap_b32 v5, v185
	s_nop 1
	s_waitcnt lgkmcnt(0)
	v_max_u32_e32 v5, v5, v185
	v_cmp_ne_u32_e32 vcc, v184, v5
	v_cmp_ne_u32_e64 s[98:99], v6, v5
	v_cmp_ne_u32_e64 s[100:101], v7, v5
	v_cndmask_b32_e32 v184, 0, v184, vcc
	v_cndmask_b32_e64 v185, 0, v6, s[98:99]
	v_max_u32_e32 v6, v184, v185
	v_cndmask_b32_e64 v7, 0, v7, s[100:101]
	v_cmp_ne_u32_e32 vcc, v8, v5
	v_cmp_ne_u32_e64 s[98:99], v9, v5
	v_cmp_ne_u32_e64 s[100:101], v10, v5
	v_cndmask_b32_e32 v8, 0, v8, vcc
	v_max3_u32 v6, v6, v7, v8
	v_cndmask_b32_e64 v9, 0, v9, s[98:99]
	v_cndmask_b32_e64 v10, 0, v10, s[100:101]
	v_cmp_ne_u32_e32 vcc, v11, v5
	v_max3_u32 v6, v6, v9, v10
	v_cmp_ne_u32_e64 s[98:99], v12, v5
	v_cndmask_b32_e32 v11, 0, v11, vcc
	v_cmp_ne_u32_e64 s[100:101], v13, v5
	v_cndmask_b32_e64 v12, 0, v12, s[98:99]
	v_max3_u32 v6, v6, v11, v12
	v_cndmask_b32_e64 v13, 0, v13, s[100:101]
	v_cmp_ne_u32_e32 vcc, v14, v5
	v_cmp_ne_u32_e64 s[98:99], v15, v5
	v_cmp_ne_u32_e64 s[100:101], v86, v5
	v_cndmask_b32_e32 v14, 0, v14, vcc
	v_max3_u32 v6, v6, v13, v14
	v_cndmask_b32_e64 v15, 0, v15, s[98:99]
	v_cndmask_b32_e64 v86, 0, v86, s[100:101]
	v_cmp_ne_u32_e32 vcc, v87, v5
	v_max3_u32 v6, v6, v15, v86
	v_cmp_ne_u32_e64 s[98:99], v88, v5
	v_cndmask_b32_e32 v87, 0, v87, vcc
	v_cmp_ne_u32_e64 s[100:101], v89, v5
	v_cndmask_b32_e64 v88, 0, v88, s[98:99]
	v_max3_u32 v6, v6, v87, v88
	v_cndmask_b32_e64 v89, 0, v89, s[100:101]
	v_cmp_ne_u32_e32 vcc, v164, v5
	v_cmp_ne_u32_e64 s[98:99], v165, v5
	v_cmp_ne_u32_e64 s[100:101], v166, v5
	v_cndmask_b32_e32 v164, 0, v164, vcc
	v_max3_u32 v6, v6, v89, v164
	v_cndmask_b32_e64 v165, 0, v165, s[98:99]
	v_cndmask_b32_e64 v166, 0, v166, s[100:101]
	v_cmp_ne_u32_e32 vcc, v167, v5
	v_max3_u32 v6, v6, v165, v166
	v_cmp_ne_u32_e64 s[98:99], v168, v5
	v_cndmask_b32_e32 v167, 0, v167, vcc
	v_cmp_ne_u32_e64 s[100:101], v169, v5
	v_cndmask_b32_e64 v168, 0, v168, s[98:99]
	v_max3_u32 v6, v6, v167, v168
	v_cndmask_b32_e64 v169, 0, v169, s[100:101]
	v_cmp_ne_u32_e32 vcc, v171, v5
	v_cmp_ne_u32_e64 s[98:99], v172, v5
	v_cmp_ne_u32_e64 s[100:101], v173, v5
	v_cndmask_b32_e32 v171, 0, v171, vcc
	v_max3_u32 v6, v6, v169, v171
	v_cndmask_b32_e64 v172, 0, v172, s[98:99]
	v_cndmask_b32_e64 v173, 0, v173, s[100:101]
	v_cmp_ne_u32_e32 vcc, v176, v5
	v_max3_u32 v6, v6, v172, v173
	v_cmp_ne_u32_e64 s[98:99], v177, v5
	v_cndmask_b32_e32 v176, 0, v176, vcc
	v_cmp_ne_u32_e64 s[100:101], v178, v5
	v_cndmask_b32_e64 v177, 0, v177, s[98:99]
	v_max3_u32 v6, v6, v176, v177
	v_cndmask_b32_e64 v178, 0, v178, s[100:101]
	v_cmp_ne_u32_e32 vcc, v179, v5
	v_cmp_ne_u32_e64 s[98:99], v183, v5
	v_cmp_ne_u32_e64 s[100:101], v180, v5
	v_cndmask_b32_e32 v179, 0, v179, vcc
	v_max3_u32 v6, v6, v178, v179
	v_cndmask_b32_e64 v183, 0, v183, s[98:99]
	v_cndmask_b32_e64 v180, 0, v180, s[100:101]
	v_cmp_ne_u32_e32 vcc, v181, v5
	v_max3_u32 v6, v6, v183, v180
	v_cmp_ne_u32_e64 s[98:99], v182, v5
	v_cndmask_b32_e32 v181, 0, v181, vcc
	s_nop 0
	v_cndmask_b32_e64 v182, 0, v182, s[98:99]
	v_max3_u32 v6, v6, v181, v182
	v_mov_b32_e32 v186, v6
	s_nop 1
	v_permlane16_swap_b32 v6, v186
	s_nop 1
	s_waitcnt lgkmcnt(0)
; DI void peer_topk_wave(const Params& p, int item, unsigned* lds  ) {
;     ...
; #pragma unroll
;     for (int rr = 0; rr < 16; ++rr) {
;       unsigned m = 0;
; #pragma unroll
;       for (int i = 0; i < 32; ++i) m = umax(m, kk[i]);
;       m = umax(m, (unsigned)__shfl_xor((int)m, 16));
;       m = umax(m, (unsigned)__shfl_xor((int)m, 32));
;       win[pp][rr] = m;
; #pragma unroll
;       for (int i = 0; i < 32; ++i) kk[i] = (kk[i] == m) ? 0u : kk[i];
;     }
	v_max_u32_e32 v6, v6, v186
	v_mov_b32_e32 v186, v6
	s_nop 1
	v_permlane32_swap_b32 v6, v186
	s_nop 1
	s_waitcnt lgkmcnt(0)
	v_max_u32_e32 v6, v6, v186
	v_cmp_ne_u32_e32 vcc, v184, v6
	v_cmp_ne_u32_e64 s[98:99], v185, v6
	v_cmp_ne_u32_e64 s[100:101], v7, v6
	v_cndmask_b32_e32 v184, 0, v184, vcc
	v_cndmask_b32_e64 v185, 0, v185, s[98:99]
	v_cndmask_b32_e64 v186, 0, v7, s[100:101]
	v_cmp_ne_u32_e32 vcc, v8, v6
	v_max_u32_e32 v7, v184, v185
	v_cmp_ne_u32_e64 s[98:99], v9, v6
	v_cndmask_b32_e32 v8, 0, v8, vcc
	v_max3_u32 v7, v7, v186, v8
	v_cndmask_b32_e64 v9, 0, v9, s[98:99]
	v_cmp_ne_u32_e64 s[100:101], v10, v6
	v_cmp_ne_u32_e32 vcc, v11, v6
	v_cmp_ne_u32_e64 s[98:99], v12, v6
	v_cndmask_b32_e64 v10, 0, v10, s[100:101]
	v_max3_u32 v7, v7, v9, v10
	v_cndmask_b32_e32 v11, 0, v11, vcc
	v_cndmask_b32_e64 v12, 0, v12, s[98:99]
	v_cmp_ne_u32_e64 s[100:101], v13, v6
	v_max3_u32 v7, v7, v11, v12
	v_cmp_ne_u32_e32 vcc, v14, v6
	v_cndmask_b32_e64 v13, 0, v13, s[100:101]
	v_cmp_ne_u32_e64 s[98:99], v15, v6
	v_cndmask_b32_e32 v14, 0, v14, vcc
	v_max3_u32 v7, v7, v13, v14
	v_cndmask_b32_e64 v15, 0, v15, s[98:99]
	v_cmp_ne_u32_e64 s[100:101], v86, v6
	v_cmp_ne_u32_e32 vcc, v87, v6
	v_cmp_ne_u32_e64 s[98:99], v88, v6
	v_cndmask_b32_e64 v86, 0, v86, s[100:101]
	v_max3_u32 v7, v7, v15, v86
	v_cndmask_b32_e32 v87, 0, v87, vcc
	v_cndmask_b32_e64 v88, 0, v88, s[98:99]
	v_cmp_ne_u32_e64 s[100:101], v89, v6
	v_max3_u32 v7, v7, v87, v88
	v_cmp_ne_u32_e32 vcc, v164, v6
	v_cndmask_b32_e64 v89, 0, v89, s[100:101]
	v_cmp_ne_u32_e64 s[98:99], v165, v6
	v_cndmask_b32_e32 v164, 0, v164, vcc
	v_max3_u32 v7, v7, v89, v164
	v_cndmask_b32_e64 v165, 0, v165, s[98:99]
	v_cmp_ne_u32_e64 s[100:101], v166, v6
	v_cmp_ne_u32_e32 vcc, v167, v6
	v_cmp_ne_u32_e64 s[98:99], v168, v6
	v_cndmask_b32_e64 v166, 0, v166, s[100:101]
	v_max3_u32 v7, v7, v165, v166
	v_cndmask_b32_e32 v167, 0, v167, vcc
	v_cndmask_b32_e64 v168, 0, v168, s[98:99]
	v_cmp_ne_u32_e64 s[100:101], v169, v6
	v_max3_u32 v7, v7, v167, v168
	v_cmp_ne_u32_e32 vcc, v171, v6
	v_cndmask_b32_e64 v169, 0, v169, s[100:101]
	v_cmp_ne_u32_e64 s[98:99], v172, v6
	v_cndmask_b32_e32 v171, 0, v171, vcc
	v_max3_u32 v7, v7, v169, v171
	v_cndmask_b32_e64 v172, 0, v172, s[98:99]
	v_cmp_ne_u32_e64 s[100:101], v173, v6
	v_cmp_ne_u32_e32 vcc, v176, v6
	v_cmp_ne_u32_e64 s[98:99], v177, v6
	v_cndmask_b32_e64 v173, 0, v173, s[100:101]
	v_max3_u32 v7, v7, v172, v173
	v_cndmask_b32_e32 v176, 0, v176, vcc
	v_cndmask_b32_e64 v177, 0, v177, s[98:99]
	v_cmp_ne_u32_e64 s[100:101], v178, v6
	v_max3_u32 v7, v7, v176, v177
	v_cmp_ne_u32_e32 vcc, v179, v6
	v_cndmask_b32_e64 v178, 0, v178, s[100:101]
	v_cmp_ne_u32_e64 s[98:99], v183, v6
	v_cndmask_b32_e32 v179, 0, v179, vcc
	v_max3_u32 v7, v7, v178, v179
	v_cndmask_b32_e64 v183, 0, v183, s[98:99]
	v_cmp_ne_u32_e64 s[100:101], v180, v6
	v_cmp_ne_u32_e32 vcc, v181, v6
	v_cmp_ne_u32_e64 s[98:99], v182, v6
	v_cndmask_b32_e64 v180, 0, v180, s[100:101]
	v_max3_u32 v7, v7, v183, v180
	v_cndmask_b32_e32 v181, 0, v181, vcc
	v_cndmask_b32_e64 v182, 0, v182, s[98:99]
	v_max3_u32 v7, v7, v181, v182
	v_mov_b32_e32 v187, v7
	s_nop 1
	v_permlane16_swap_b32 v7, v187
	s_nop 1
	s_waitcnt lgkmcnt(0)
	v_max_u32_e32 v7, v7, v187
	v_mov_b32_e32 v187, v7
	s_nop 1
	v_permlane32_swap_b32 v7, v187
	s_nop 1
	s_waitcnt lgkmcnt(0)
	v_max_u32_e32 v7, v7, v187
	v_cmp_ne_u32_e32 vcc, v184, v7
	v_cmp_ne_u32_e64 s[98:99], v185, v7
	v_cmp_ne_u32_e64 s[100:101], v186, v7
	v_cndmask_b32_e32 v184, 0, v184, vcc
	v_cndmask_b32_e64 v185, 0, v185, s[98:99]
	v_cndmask_b32_e64 v186, 0, v186, s[100:101]
	v_cmp_ne_u32_e32 vcc, v8, v7
	v_cmp_ne_u32_e64 s[98:99], v9, v7
	v_cmp_ne_u32_e64 s[100:101], v10, v7
	v_cndmask_b32_e32 v187, 0, v8, vcc
	v_max_u32_e32 v8, v184, v185
	v_max3_u32 v8, v8, v186, v187
	v_cndmask_b32_e64 v9, 0, v9, s[98:99]
	v_cndmask_b32_e64 v10, 0, v10, s[100:101]
	v_cmp_ne_u32_e32 vcc, v11, v7
	v_max3_u32 v8, v8, v9, v10
	v_cmp_ne_u32_e64 s[98:99], v12, v7
	v_cndmask_b32_e32 v11, 0, v11, vcc
	v_cmp_ne_u32_e64 s[100:101], v13, v7
	v_cndmask_b32_e64 v12, 0, v12, s[98:99]
	v_max3_u32 v8, v8, v11, v12
	v_cndmask_b32_e64 v13, 0, v13, s[100:101]
	v_cmp_ne_u32_e32 vcc, v14, v7
	v_cmp_ne_u32_e64 s[98:99], v15, v7
	v_cmp_ne_u32_e64 s[100:101], v86, v7
	v_cndmask_b32_e32 v14, 0, v14, vcc
	v_max3_u32 v8, v8, v13, v14
	v_cndmask_b32_e64 v15, 0, v15, s[98:99]
	v_cndmask_b32_e64 v86, 0, v86, s[100:101]
	v_cmp_ne_u32_e32 vcc, v87, v7
	v_max3_u32 v8, v8, v15, v86
	v_cmp_ne_u32_e64 s[98:99], v88, v7
	v_cndmask_b32_e32 v87, 0, v87, vcc
	v_cmp_ne_u32_e64 s[100:101], v89, v7
	v_cndmask_b32_e64 v88, 0, v88, s[98:99]
	v_max3_u32 v8, v8, v87, v88
	v_cndmask_b32_e64 v89, 0, v89, s[100:101]
	v_cmp_ne_u32_e32 vcc, v164, v7
	v_cmp_ne_u32_e64 s[98:99], v165, v7
	v_cmp_ne_u32_e64 s[100:101], v166, v7
	v_cndmask_b32_e32 v164, 0, v164, vcc
	v_max3_u32 v8, v8, v89, v164
	v_cndmask_b32_e64 v165, 0, v165, s[98:99]
	v_cndmask_b32_e64 v166, 0, v166, s[100:101]
	v_cmp_ne_u32_e32 vcc, v167, v7
	v_max3_u32 v8, v8, v165, v166
	v_cmp_ne_u32_e64 s[98:99], v168, v7
	v_cndmask_b32_e32 v167, 0, v167, vcc
	v_cmp_ne_u32_e64 s[100:101], v169, v7
	v_cndmask_b32_e64 v168, 0, v168, s[98:99]
	v_max3_u32 v8, v8, v167, v168
	v_cndmask_b32_e64 v169, 0, v169, s[100:101]
	v_cmp_ne_u32_e32 vcc, v171, v7
	v_cmp_ne_u32_e64 s[98:99], v172, v7
	v_cmp_ne_u32_e64 s[100:101], v173, v7
	v_cndmask_b32_e32 v171, 0, v171, vcc
	v_max3_u32 v8, v8, v169, v171
	v_cndmask_b32_e64 v172, 0, v172, s[98:99]
	v_cndmask_b32_e64 v173, 0, v173, s[100:101]
	v_cmp_ne_u32_e32 vcc, v176, v7
	v_max3_u32 v8, v8, v172, v173
	v_cmp_ne_u32_e64 s[98:99], v177, v7
	v_cndmask_b32_e32 v176, 0, v176, vcc
	v_cmp_ne_u32_e64 s[100:101], v178, v7
	v_cndmask_b32_e64 v177, 0, v177, s[98:99]
	v_max3_u32 v8, v8, v176, v177
	v_cndmask_b32_e64 v178, 0, v178, s[100:101]
	v_cmp_ne_u32_e32 vcc, v179, v7
	v_cmp_ne_u32_e64 s[98:99], v183, v7
	v_cmp_ne_u32_e64 s[100:101], v180, v7
	v_cndmask_b32_e32 v179, 0, v179, vcc
	v_max3_u32 v8, v8, v178, v179
	v_cndmask_b32_e64 v183, 0, v183, s[98:99]
	v_cndmask_b32_e64 v180, 0, v180, s[100:101]
	v_cmp_ne_u32_e32 vcc, v181, v7
	v_max3_u32 v8, v8, v183, v180
	v_cmp_ne_u32_e64 s[98:99], v182, v7
	v_cndmask_b32_e32 v181, 0, v181, vcc
	s_nop 0
	v_cndmask_b32_e64 v182, 0, v182, s[98:99]
	v_max3_u32 v8, v8, v181, v182
	v_mov_b32_e32 v188, v8
	s_nop 1
	v_permlane16_swap_b32 v8, v188
	s_nop 1
	s_waitcnt lgkmcnt(0)
; DI void peer_topk_wave(const Params& p, int item, unsigned* lds  ) {
;     ...
; #pragma unroll
;     for (int rr = 0; rr < 16; ++rr) {
;       unsigned m = 0;
; #pragma unroll
;       for (int i = 0; i < 32; ++i) m = umax(m, kk[i]);
;       m = umax(m, (unsigned)__shfl_xor((int)m, 16));
;       m = umax(m, (unsigned)__shfl_xor((int)m, 32));
;       win[pp][rr] = m;
; #pragma unroll
;       for (int i = 0; i < 32; ++i) kk[i] = (kk[i] == m) ? 0u : kk[i];
;     }
	v_max_u32_e32 v8, v8, v188
	v_mov_b32_e32 v188, v8
	s_nop 1
	v_permlane32_swap_b32 v8, v188
	s_nop 1
	s_waitcnt lgkmcnt(0)
	v_max_u32_e32 v8, v8, v188
	v_cmp_ne_u32_e32 vcc, v184, v8
	v_cmp_ne_u32_e64 s[98:99], v185, v8
	v_cmp_ne_u32_e64 s[100:101], v186, v8
	v_cndmask_b32_e32 v184, 0, v184, vcc
	v_cndmask_b32_e64 v185, 0, v185, s[98:99]
	v_cndmask_b32_e64 v186, 0, v186, s[100:101]
	v_cmp_ne_u32_e32 vcc, v187, v8
	v_cmp_ne_u32_e64 s[98:99], v9, v8
	v_cmp_ne_u32_e64 s[100:101], v10, v8
	v_cndmask_b32_e32 v187, 0, v187, vcc
	v_cndmask_b32_e64 v188, 0, v9, s[98:99]
	v_max_u32_e32 v9, v184, v185
	v_max3_u32 v9, v9, v186, v187
	v_cndmask_b32_e64 v10, 0, v10, s[100:101]
	v_cmp_ne_u32_e32 vcc, v11, v8
	v_max3_u32 v9, v9, v188, v10
	v_cmp_ne_u32_e64 s[98:99], v12, v8
	v_cndmask_b32_e32 v11, 0, v11, vcc
	v_cmp_ne_u32_e64 s[100:101], v13, v8
	v_cndmask_b32_e64 v12, 0, v12, s[98:99]
	v_max3_u32 v9, v9, v11, v12
	v_cndmask_b32_e64 v13, 0, v13, s[100:101]
	v_cmp_ne_u32_e32 vcc, v14, v8
	v_cmp_ne_u32_e64 s[98:99], v15, v8
	v_cmp_ne_u32_e64 s[100:101], v86, v8
	v_cndmask_b32_e32 v14, 0, v14, vcc
	v_max3_u32 v9, v9, v13, v14
	v_cndmask_b32_e64 v15, 0, v15, s[98:99]
	v_cndmask_b32_e64 v86, 0, v86, s[100:101]
	v_cmp_ne_u32_e32 vcc, v87, v8
	v_max3_u32 v9, v9, v15, v86
	v_cmp_ne_u32_e64 s[98:99], v88, v8
	v_cndmask_b32_e32 v87, 0, v87, vcc
	v_cmp_ne_u32_e64 s[100:101], v89, v8
	v_cndmask_b32_e64 v88, 0, v88, s[98:99]
	v_max3_u32 v9, v9, v87, v88
	v_cndmask_b32_e64 v89, 0, v89, s[100:101]
	v_cmp_ne_u32_e32 vcc, v164, v8
	v_cmp_ne_u32_e64 s[98:99], v165, v8
	v_cmp_ne_u32_e64 s[100:101], v166, v8
	v_cndmask_b32_e32 v164, 0, v164, vcc
	v_max3_u32 v9, v9, v89, v164
	v_cndmask_b32_e64 v165, 0, v165, s[98:99]
	v_cndmask_b32_e64 v166, 0, v166, s[100:101]
	v_cmp_ne_u32_e32 vcc, v167, v8
	v_max3_u32 v9, v9, v165, v166
	v_cmp_ne_u32_e64 s[98:99], v168, v8
	v_cndmask_b32_e32 v167, 0, v167, vcc
	v_cmp_ne_u32_e64 s[100:101], v169, v8
	v_cndmask_b32_e64 v168, 0, v168, s[98:99]
	v_max3_u32 v9, v9, v167, v168
	v_cndmask_b32_e64 v169, 0, v169, s[100:101]
	v_cmp_ne_u32_e32 vcc, v171, v8
	v_cmp_ne_u32_e64 s[98:99], v172, v8
	v_cmp_ne_u32_e64 s[100:101], v173, v8
	v_cndmask_b32_e32 v171, 0, v171, vcc
	v_max3_u32 v9, v9, v169, v171
	v_cndmask_b32_e64 v172, 0, v172, s[98:99]
	v_cndmask_b32_e64 v173, 0, v173, s[100:101]
	v_cmp_ne_u32_e32 vcc, v176, v8
	v_max3_u32 v9, v9, v172, v173
	v_cmp_ne_u32_e64 s[98:99], v177, v8
	v_cndmask_b32_e32 v176, 0, v176, vcc
	v_cmp_ne_u32_e64 s[100:101], v178, v8
	v_cndmask_b32_e64 v177, 0, v177, s[98:99]
	v_max3_u32 v9, v9, v176, v177
	v_cndmask_b32_e64 v178, 0, v178, s[100:101]
	v_cmp_ne_u32_e32 vcc, v179, v8
	v_cmp_ne_u32_e64 s[98:99], v183, v8
	v_cmp_ne_u32_e64 s[100:101], v180, v8
	v_cndmask_b32_e32 v179, 0, v179, vcc
	v_max3_u32 v9, v9, v178, v179
	v_cndmask_b32_e64 v183, 0, v183, s[98:99]
	v_cndmask_b32_e64 v180, 0, v180, s[100:101]
	v_cmp_ne_u32_e32 vcc, v181, v8
	v_max3_u32 v9, v9, v183, v180
	v_cmp_ne_u32_e64 s[98:99], v182, v8
	v_cndmask_b32_e32 v181, 0, v181, vcc
	s_nop 0
	v_cndmask_b32_e64 v182, 0, v182, s[98:99]
	v_max3_u32 v9, v9, v181, v182
	v_mov_b32_e32 v189, v9
	s_nop 1
	v_permlane16_swap_b32 v9, v189
	s_nop 1
	s_waitcnt lgkmcnt(0)
	v_max_u32_e32 v9, v9, v189
	v_mov_b32_e32 v189, v9
	s_nop 1
	v_permlane32_swap_b32 v9, v189
	s_nop 1
	s_waitcnt lgkmcnt(0)
	v_max_u32_e32 v9, v9, v189
	v_cmp_ne_u32_e32 vcc, v184, v9
	v_cmp_ne_u32_e64 s[98:99], v185, v9
	v_cmp_ne_u32_e64 s[100:101], v186, v9
	v_cndmask_b32_e32 v184, 0, v184, vcc
	v_cndmask_b32_e64 v185, 0, v185, s[98:99]
	v_cndmask_b32_e64 v186, 0, v186, s[100:101]
	v_cmp_ne_u32_e32 vcc, v187, v9
	v_cmp_ne_u32_e64 s[98:99], v188, v9
	v_cmp_ne_u32_e64 s[100:101], v10, v9
	v_cndmask_b32_e32 v187, 0, v187, vcc
	v_cndmask_b32_e64 v188, 0, v188, s[98:99]
	v_cndmask_b32_e64 v189, 0, v10, s[100:101]
	v_cmp_ne_u32_e32 vcc, v11, v9
	v_max_u32_e32 v10, v184, v185
	v_max3_u32 v10, v10, v186, v187
	v_cndmask_b32_e32 v11, 0, v11, vcc
	v_cmp_ne_u32_e64 s[98:99], v12, v9
	v_max3_u32 v10, v10, v188, v189
	v_cmp_ne_u32_e64 s[100:101], v13, v9
	v_cndmask_b32_e64 v12, 0, v12, s[98:99]
	v_max3_u32 v10, v10, v11, v12
	v_cndmask_b32_e64 v13, 0, v13, s[100:101]
	v_cmp_ne_u32_e32 vcc, v14, v9
	v_cmp_ne_u32_e64 s[98:99], v15, v9
	v_cmp_ne_u32_e64 s[100:101], v86, v9
	v_cndmask_b32_e32 v14, 0, v14, vcc
	v_max3_u32 v10, v10, v13, v14
	v_cndmask_b32_e64 v15, 0, v15, s[98:99]
	v_cndmask_b32_e64 v86, 0, v86, s[100:101]
	v_cmp_ne_u32_e32 vcc, v87, v9
	v_max3_u32 v10, v10, v15, v86
	v_cmp_ne_u32_e64 s[98:99], v88, v9
	v_cndmask_b32_e32 v87, 0, v87, vcc
	v_cmp_ne_u32_e64 s[100:101], v89, v9
	v_cndmask_b32_e64 v88, 0, v88, s[98:99]
	v_max3_u32 v10, v10, v87, v88
	v_cndmask_b32_e64 v89, 0, v89, s[100:101]
	v_cmp_ne_u32_e32 vcc, v164, v9
	v_cmp_ne_u32_e64 s[98:99], v165, v9
	v_cmp_ne_u32_e64 s[100:101], v166, v9
	v_cndmask_b32_e32 v164, 0, v164, vcc
	v_max3_u32 v10, v10, v89, v164
	v_cndmask_b32_e64 v165, 0, v165, s[98:99]
	v_cndmask_b32_e64 v166, 0, v166, s[100:101]
	v_cmp_ne_u32_e32 vcc, v167, v9
	v_max3_u32 v10, v10, v165, v166
	v_cmp_ne_u32_e64 s[98:99], v168, v9
	v_cndmask_b32_e32 v167, 0, v167, vcc
	v_cmp_ne_u32_e64 s[100:101], v169, v9
	v_cndmask_b32_e64 v168, 0, v168, s[98:99]
	v_max3_u32 v10, v10, v167, v168
	v_cndmask_b32_e64 v169, 0, v169, s[100:101]
	v_cmp_ne_u32_e32 vcc, v171, v9
	v_cmp_ne_u32_e64 s[98:99], v172, v9
	v_cmp_ne_u32_e64 s[100:101], v173, v9
	v_cndmask_b32_e32 v171, 0, v171, vcc
	v_max3_u32 v10, v10, v169, v171
	v_cndmask_b32_e64 v172, 0, v172, s[98:99]
	v_cndmask_b32_e64 v173, 0, v173, s[100:101]
	v_cmp_ne_u32_e32 vcc, v176, v9
	v_max3_u32 v10, v10, v172, v173
	v_cmp_ne_u32_e64 s[98:99], v177, v9
	v_cndmask_b32_e32 v176, 0, v176, vcc
	v_cmp_ne_u32_e64 s[100:101], v178, v9
	v_cndmask_b32_e64 v177, 0, v177, s[98:99]
	v_max3_u32 v10, v10, v176, v177
	v_cndmask_b32_e64 v178, 0, v178, s[100:101]
	v_cmp_ne_u32_e32 vcc, v179, v9
	v_cmp_ne_u32_e64 s[98:99], v183, v9
	v_cmp_ne_u32_e64 s[100:101], v180, v9
	v_cndmask_b32_e32 v179, 0, v179, vcc
	v_max3_u32 v10, v10, v178, v179
	v_cndmask_b32_e64 v183, 0, v183, s[98:99]
	v_cndmask_b32_e64 v180, 0, v180, s[100:101]
	v_cmp_ne_u32_e32 vcc, v181, v9
	v_max3_u32 v10, v10, v183, v180
	v_cmp_ne_u32_e64 s[98:99], v182, v9
	v_cndmask_b32_e32 v181, 0, v181, vcc
	s_nop 0
	v_cndmask_b32_e64 v182, 0, v182, s[98:99]
	v_max3_u32 v10, v10, v181, v182
	v_mov_b32_e32 v190, v10
	s_nop 1
	v_permlane16_swap_b32 v10, v190
	s_nop 1
	s_waitcnt lgkmcnt(0)
; DI void peer_topk_wave(const Params& p, int item, unsigned* lds  ) {
;     ...
; #pragma unroll
;     for (int rr = 0; rr < 16; ++rr) {
;       unsigned m = 0;
; #pragma unroll
;       for (int i = 0; i < 32; ++i) m = umax(m, kk[i]);
;       m = umax(m, (unsigned)__shfl_xor((int)m, 16));
;       m = umax(m, (unsigned)__shfl_xor((int)m, 32));
;       win[pp][rr] = m;
; #pragma unroll
;       for (int i = 0; i < 32; ++i) kk[i] = (kk[i] == m) ? 0u : kk[i];
;     }
	v_max_u32_e32 v10, v10, v190
	v_mov_b32_e32 v190, v10
	s_nop 1
	v_permlane32_swap_b32 v10, v190
	s_nop 1
	s_waitcnt lgkmcnt(0)
	v_max_u32_e32 v10, v10, v190
	v_cmp_ne_u32_e32 vcc, v184, v10
	v_cmp_ne_u32_e64 s[98:99], v185, v10
	v_cmp_ne_u32_e64 s[100:101], v186, v10
	v_cndmask_b32_e32 v184, 0, v184, vcc
	v_cndmask_b32_e64 v185, 0, v185, s[98:99]
	v_cndmask_b32_e64 v186, 0, v186, s[100:101]
	v_cmp_ne_u32_e32 vcc, v187, v10
	v_cmp_ne_u32_e64 s[98:99], v188, v10
	v_cmp_ne_u32_e64 s[100:101], v189, v10
	v_cndmask_b32_e32 v187, 0, v187, vcc
	v_cndmask_b32_e64 v188, 0, v188, s[98:99]
	v_cndmask_b32_e64 v189, 0, v189, s[100:101]
	v_cmp_ne_u32_e32 vcc, v11, v10
	v_cmp_ne_u32_e64 s[98:99], v12, v10
	v_cmp_ne_u32_e64 s[100:101], v13, v10
	v_cndmask_b32_e32 v190, 0, v11, vcc
	v_max_u32_e32 v11, v184, v185
	v_max3_u32 v11, v11, v186, v187
	v_cndmask_b32_e64 v12, 0, v12, s[98:99]
	v_max3_u32 v11, v11, v188, v189
	v_max3_u32 v11, v11, v190, v12
	v_cndmask_b32_e64 v13, 0, v13, s[100:101]
	v_cmp_ne_u32_e32 vcc, v14, v10
	v_cmp_ne_u32_e64 s[98:99], v15, v10
	v_cmp_ne_u32_e64 s[100:101], v86, v10
	v_cndmask_b32_e32 v14, 0, v14, vcc
	v_max3_u32 v11, v11, v13, v14
	v_cndmask_b32_e64 v15, 0, v15, s[98:99]
	v_cndmask_b32_e64 v86, 0, v86, s[100:101]
	v_cmp_ne_u32_e32 vcc, v87, v10
	v_max3_u32 v11, v11, v15, v86
	v_cmp_ne_u32_e64 s[98:99], v88, v10
	v_cndmask_b32_e32 v87, 0, v87, vcc
	v_cmp_ne_u32_e64 s[100:101], v89, v10
	v_cndmask_b32_e64 v88, 0, v88, s[98:99]
	v_max3_u32 v11, v11, v87, v88
	v_cndmask_b32_e64 v89, 0, v89, s[100:101]
	v_cmp_ne_u32_e32 vcc, v164, v10
	v_cmp_ne_u32_e64 s[98:99], v165, v10
	v_cmp_ne_u32_e64 s[100:101], v166, v10
	v_cndmask_b32_e32 v164, 0, v164, vcc
	v_max3_u32 v11, v11, v89, v164
	v_cndmask_b32_e64 v165, 0, v165, s[98:99]
	v_cndmask_b32_e64 v166, 0, v166, s[100:101]
	v_cmp_ne_u32_e32 vcc, v167, v10
	v_max3_u32 v11, v11, v165, v166
	v_cmp_ne_u32_e64 s[98:99], v168, v10
	v_cndmask_b32_e32 v167, 0, v167, vcc
	v_cmp_ne_u32_e64 s[100:101], v169, v10
	v_cndmask_b32_e64 v168, 0, v168, s[98:99]
	v_max3_u32 v11, v11, v167, v168
	v_cndmask_b32_e64 v169, 0, v169, s[100:101]
	v_cmp_ne_u32_e32 vcc, v171, v10
	v_cmp_ne_u32_e64 s[98:99], v172, v10
	v_cmp_ne_u32_e64 s[100:101], v173, v10
	v_cndmask_b32_e32 v171, 0, v171, vcc
	v_max3_u32 v11, v11, v169, v171
	v_cndmask_b32_e64 v172, 0, v172, s[98:99]
	v_cndmask_b32_e64 v173, 0, v173, s[100:101]
	v_cmp_ne_u32_e32 vcc, v176, v10
	v_max3_u32 v11, v11, v172, v173
	v_cmp_ne_u32_e64 s[98:99], v177, v10
	v_cndmask_b32_e32 v176, 0, v176, vcc
	v_cmp_ne_u32_e64 s[100:101], v178, v10
	v_cndmask_b32_e64 v177, 0, v177, s[98:99]
	v_max3_u32 v11, v11, v176, v177
	v_cndmask_b32_e64 v178, 0, v178, s[100:101]
	v_cmp_ne_u32_e32 vcc, v179, v10
	v_cmp_ne_u32_e64 s[98:99], v183, v10
	v_cmp_ne_u32_e64 s[100:101], v180, v10
	v_cndmask_b32_e32 v179, 0, v179, vcc
	v_max3_u32 v11, v11, v178, v179
	v_cndmask_b32_e64 v183, 0, v183, s[98:99]
	v_cndmask_b32_e64 v180, 0, v180, s[100:101]
	v_cmp_ne_u32_e32 vcc, v181, v10
	v_max3_u32 v11, v11, v183, v180
	v_cmp_ne_u32_e64 s[98:99], v182, v10
	v_cndmask_b32_e32 v181, 0, v181, vcc
	s_nop 0
	v_cndmask_b32_e64 v182, 0, v182, s[98:99]
	v_max3_u32 v11, v11, v181, v182
	v_mov_b32_e32 v191, v11
	s_nop 1
	v_permlane16_swap_b32 v11, v191
	s_nop 1
	s_waitcnt lgkmcnt(0)
	v_max_u32_e32 v11, v11, v191
	v_mov_b32_e32 v191, v11
	s_nop 1
	v_permlane32_swap_b32 v11, v191
	s_nop 1
	s_waitcnt lgkmcnt(0)
	v_max_u32_e32 v11, v11, v191
	v_cmp_ne_u32_e32 vcc, v184, v11
	v_cmp_ne_u32_e64 s[98:99], v185, v11
	v_cmp_ne_u32_e64 s[100:101], v186, v11
	v_cndmask_b32_e32 v184, 0, v184, vcc
	v_cndmask_b32_e64 v185, 0, v185, s[98:99]
	v_cndmask_b32_e64 v186, 0, v186, s[100:101]
	v_cmp_ne_u32_e32 vcc, v187, v11
	v_cmp_ne_u32_e64 s[98:99], v188, v11
	v_cmp_ne_u32_e64 s[100:101], v189, v11
	v_cndmask_b32_e32 v187, 0, v187, vcc
	v_cndmask_b32_e64 v188, 0, v188, s[98:99]
	v_cndmask_b32_e64 v189, 0, v189, s[100:101]
	v_cmp_ne_u32_e32 vcc, v190, v11
	v_cmp_ne_u32_e64 s[98:99], v12, v11
	v_cmp_ne_u32_e64 s[100:101], v13, v11
	v_cndmask_b32_e32 v190, 0, v190, vcc
	v_cndmask_b32_e64 v191, 0, v12, s[98:99]
	v_max_u32_e32 v12, v184, v185
	v_max3_u32 v12, v12, v186, v187
	v_cndmask_b32_e64 v13, 0, v13, s[100:101]
	v_cmp_ne_u32_e32 vcc, v14, v11
	v_max3_u32 v12, v12, v188, v189
	v_max3_u32 v12, v12, v190, v191
	v_cndmask_b32_e32 v14, 0, v14, vcc
	v_cmp_ne_u32_e64 s[98:99], v15, v11
	v_max3_u32 v12, v12, v13, v14
	v_cmp_ne_u32_e64 s[100:101], v86, v11
	v_cndmask_b32_e64 v15, 0, v15, s[98:99]
	v_cmp_ne_u32_e32 vcc, v87, v11
	v_cndmask_b32_e64 v86, 0, v86, s[100:101]
	v_max3_u32 v12, v12, v15, v86
	v_cndmask_b32_e32 v87, 0, v87, vcc
	v_cmp_ne_u32_e64 s[98:99], v88, v11
	v_cmp_ne_u32_e64 s[100:101], v89, v11
	v_cmp_ne_u32_e32 vcc, v164, v11
	v_cndmask_b32_e64 v88, 0, v88, s[98:99]
	v_max3_u32 v12, v12, v87, v88
	v_cndmask_b32_e64 v89, 0, v89, s[100:101]
	v_cndmask_b32_e32 v164, 0, v164, vcc
	v_cmp_ne_u32_e64 s[98:99], v165, v11
	v_max3_u32 v12, v12, v89, v164
	v_cmp_ne_u32_e64 s[100:101], v166, v11
	v_cndmask_b32_e64 v165, 0, v165, s[98:99]
	v_cmp_ne_u32_e32 vcc, v167, v11
	v_cndmask_b32_e64 v166, 0, v166, s[100:101]
	v_max3_u32 v12, v12, v165, v166
	v_cndmask_b32_e32 v167, 0, v167, vcc
	v_cmp_ne_u32_e64 s[98:99], v168, v11
	v_cmp_ne_u32_e64 s[100:101], v169, v11
	v_cmp_ne_u32_e32 vcc, v171, v11
	v_cndmask_b32_e64 v168, 0, v168, s[98:99]
	v_max3_u32 v12, v12, v167, v168
	v_cndmask_b32_e64 v169, 0, v169, s[100:101]
	v_cndmask_b32_e32 v171, 0, v171, vcc
	v_cmp_ne_u32_e64 s[98:99], v172, v11
	v_max3_u32 v12, v12, v169, v171
	v_cmp_ne_u32_e64 s[100:101], v173, v11
	v_cndmask_b32_e64 v172, 0, v172, s[98:99]
	v_cmp_ne_u32_e32 vcc, v176, v11
	v_cndmask_b32_e64 v173, 0, v173, s[100:101]
	v_max3_u32 v12, v12, v172, v173
	v_cndmask_b32_e32 v176, 0, v176, vcc
	v_cmp_ne_u32_e64 s[98:99], v177, v11
	v_cmp_ne_u32_e64 s[100:101], v178, v11
	v_cmp_ne_u32_e32 vcc, v179, v11
	v_cndmask_b32_e64 v177, 0, v177, s[98:99]
	v_max3_u32 v12, v12, v176, v177
	v_cndmask_b32_e64 v178, 0, v178, s[100:101]
	v_cndmask_b32_e32 v179, 0, v179, vcc
	v_cmp_ne_u32_e64 s[98:99], v183, v11
	v_max3_u32 v12, v12, v178, v179
	v_cmp_ne_u32_e64 s[100:101], v180, v11
	v_cndmask_b32_e64 v183, 0, v183, s[98:99]
	v_cmp_ne_u32_e32 vcc, v181, v11
	v_cndmask_b32_e64 v180, 0, v180, s[100:101]
	v_max3_u32 v12, v12, v183, v180
	v_cndmask_b32_e32 v181, 0, v181, vcc
	v_cmp_ne_u32_e64 s[98:99], v182, v11
	s_nop 0
	s_nop 0
	v_cndmask_b32_e64 v182, 0, v182, s[98:99]
	v_max3_u32 v12, v12, v181, v182
	v_mov_b32_e32 v192, v12
	s_nop 1
	v_permlane16_swap_b32 v12, v192
	s_nop 1
	s_waitcnt lgkmcnt(0)
; DI void peer_topk_wave(const Params& p, int item, unsigned* lds  ) {
;     ...
; #pragma unroll
;     for (int rr = 0; rr < 16; ++rr) {
;       unsigned m = 0;
; #pragma unroll
;       for (int i = 0; i < 32; ++i) m = umax(m, kk[i]);
;       m = umax(m, (unsigned)__shfl_xor((int)m, 16));
;       m = umax(m, (unsigned)__shfl_xor((int)m, 32));
;       win[pp][rr] = m;
; #pragma unroll
;       for (int i = 0; i < 32; ++i) kk[i] = (kk[i] == m) ? 0u : kk[i];
;     }
	v_max_u32_e32 v12, v12, v192
	v_mov_b32_e32 v192, v12
	s_nop 1
	v_permlane32_swap_b32 v12, v192
	s_nop 1
	s_waitcnt lgkmcnt(0)
	v_max_u32_e32 v12, v12, v192
	v_cmp_ne_u32_e32 vcc, v184, v12
	v_cmp_ne_u32_e64 s[98:99], v185, v12
	v_cmp_ne_u32_e64 s[100:101], v186, v12
	v_cndmask_b32_e32 v184, 0, v184, vcc
	v_cndmask_b32_e64 v185, 0, v185, s[98:99]
	v_cndmask_b32_e64 v186, 0, v186, s[100:101]
	v_cmp_ne_u32_e32 vcc, v187, v12
	v_cmp_ne_u32_e64 s[98:99], v188, v12
	v_cmp_ne_u32_e64 s[100:101], v189, v12
	v_cndmask_b32_e32 v187, 0, v187, vcc
	v_cndmask_b32_e64 v188, 0, v188, s[98:99]
	v_cndmask_b32_e64 v189, 0, v189, s[100:101]
	v_cmp_ne_u32_e32 vcc, v190, v12
	v_cmp_ne_u32_e64 s[98:99], v191, v12
	v_cmp_ne_u32_e64 s[100:101], v13, v12
	v_cndmask_b32_e32 v190, 0, v190, vcc
	v_cndmask_b32_e64 v191, 0, v191, s[98:99]
	v_cndmask_b32_e64 v192, 0, v13, s[100:101]
	v_cmp_ne_u32_e32 vcc, v14, v12
	v_max_u32_e32 v13, v184, v185
	v_max3_u32 v13, v13, v186, v187
	v_cndmask_b32_e32 v14, 0, v14, vcc
	v_cmp_ne_u32_e64 s[98:99], v15, v12
	v_max3_u32 v13, v13, v188, v189
	v_max3_u32 v13, v13, v190, v191
	v_cndmask_b32_e64 v15, 0, v15, s[98:99]
	v_cmp_ne_u32_e64 s[100:101], v86, v12
	v_max3_u32 v13, v13, v192, v14
	v_cmp_ne_u32_e32 vcc, v87, v12
	v_cndmask_b32_e64 v86, 0, v86, s[100:101]
	v_max3_u32 v13, v13, v15, v86
	v_cndmask_b32_e32 v87, 0, v87, vcc
	v_cmp_ne_u32_e64 s[98:99], v88, v12
	v_cmp_ne_u32_e64 s[100:101], v89, v12
	v_cmp_ne_u32_e32 vcc, v164, v12
	v_cndmask_b32_e64 v88, 0, v88, s[98:99]
	v_max3_u32 v13, v13, v87, v88
	v_cndmask_b32_e64 v89, 0, v89, s[100:101]
	v_cndmask_b32_e32 v164, 0, v164, vcc
	v_cmp_ne_u32_e64 s[98:99], v165, v12
	v_max3_u32 v13, v13, v89, v164
	v_cmp_ne_u32_e64 s[100:101], v166, v12
	v_cndmask_b32_e64 v165, 0, v165, s[98:99]
	v_cmp_ne_u32_e32 vcc, v167, v12
	v_cndmask_b32_e64 v166, 0, v166, s[100:101]
	v_max3_u32 v13, v13, v165, v166
	v_cndmask_b32_e32 v167, 0, v167, vcc
	v_cmp_ne_u32_e64 s[98:99], v168, v12
	v_cmp_ne_u32_e64 s[100:101], v169, v12
	v_cmp_ne_u32_e32 vcc, v171, v12
	v_cndmask_b32_e64 v168, 0, v168, s[98:99]
	v_max3_u32 v13, v13, v167, v168
	v_cndmask_b32_e64 v169, 0, v169, s[100:101]
	v_cndmask_b32_e32 v171, 0, v171, vcc
	v_cmp_ne_u32_e64 s[98:99], v172, v12
	v_max3_u32 v13, v13, v169, v171
	v_cmp_ne_u32_e64 s[100:101], v173, v12
	v_cndmask_b32_e64 v172, 0, v172, s[98:99]
	v_cmp_ne_u32_e32 vcc, v176, v12
	v_cndmask_b32_e64 v173, 0, v173, s[100:101]
	v_max3_u32 v13, v13, v172, v173
	v_cndmask_b32_e32 v176, 0, v176, vcc
	v_cmp_ne_u32_e64 s[98:99], v177, v12
	v_cmp_ne_u32_e64 s[100:101], v178, v12
	v_cmp_ne_u32_e32 vcc, v179, v12
	v_cndmask_b32_e64 v177, 0, v177, s[98:99]
	v_max3_u32 v13, v13, v176, v177
	v_cndmask_b32_e64 v178, 0, v178, s[100:101]
	v_cndmask_b32_e32 v179, 0, v179, vcc
	v_cmp_ne_u32_e64 s[98:99], v183, v12
	v_max3_u32 v13, v13, v178, v179
	v_cmp_ne_u32_e64 s[100:101], v180, v12
	v_cndmask_b32_e64 v183, 0, v183, s[98:99]
	v_cmp_ne_u32_e32 vcc, v181, v12
	v_cndmask_b32_e64 v180, 0, v180, s[100:101]
	v_max3_u32 v13, v13, v183, v180
	v_cndmask_b32_e32 v181, 0, v181, vcc
	v_cmp_ne_u32_e64 s[98:99], v182, v12
	s_nop 0
	s_nop 0
	v_cndmask_b32_e64 v182, 0, v182, s[98:99]
	v_max3_u32 v13, v13, v181, v182
	v_mov_b32_e32 v193, v13
	s_nop 1
	v_permlane16_swap_b32 v13, v193
	s_nop 1
	s_waitcnt lgkmcnt(0)
	v_max_u32_e32 v13, v13, v193
	v_mov_b32_e32 v193, v13
	s_nop 1
	v_permlane32_swap_b32 v13, v193
	s_nop 1
	s_waitcnt lgkmcnt(0)
	v_max_u32_e32 v13, v13, v193
	v_cmp_ne_u32_e32 vcc, v184, v13
	v_cmp_ne_u32_e64 s[98:99], v185, v13
	v_cmp_ne_u32_e64 s[100:101], v186, v13
	v_cndmask_b32_e32 v184, 0, v184, vcc
	v_cndmask_b32_e64 v185, 0, v185, s[98:99]
	v_cndmask_b32_e64 v186, 0, v186, s[100:101]
	v_cmp_ne_u32_e32 vcc, v187, v13
	v_cmp_ne_u32_e64 s[98:99], v188, v13
	v_cmp_ne_u32_e64 s[100:101], v189, v13
	v_cndmask_b32_e32 v187, 0, v187, vcc
	v_cndmask_b32_e64 v188, 0, v188, s[98:99]
	v_cndmask_b32_e64 v189, 0, v189, s[100:101]
	v_cmp_ne_u32_e32 vcc, v190, v13
	v_cmp_ne_u32_e64 s[98:99], v191, v13
	v_cmp_ne_u32_e64 s[100:101], v192, v13
	v_cndmask_b32_e32 v190, 0, v190, vcc
	v_cndmask_b32_e64 v191, 0, v191, s[98:99]
	v_cndmask_b32_e64 v192, 0, v192, s[100:101]
	v_cmp_ne_u32_e32 vcc, v14, v13
	v_cmp_ne_u32_e64 s[98:99], v15, v13
	v_cmp_ne_u32_e64 s[100:101], v86, v13
	v_cndmask_b32_e32 v193, 0, v14, vcc
	v_max_u32_e32 v14, v184, v185
	v_max3_u32 v14, v14, v186, v187
	v_cndmask_b32_e64 v15, 0, v15, s[98:99]
	v_max3_u32 v14, v14, v188, v189
	v_max3_u32 v14, v14, v190, v191
	v_cndmask_b32_e64 v86, 0, v86, s[100:101]
	v_cmp_ne_u32_e32 vcc, v87, v13
	v_max3_u32 v14, v14, v192, v193
	v_max3_u32 v14, v14, v15, v86
	v_cndmask_b32_e32 v87, 0, v87, vcc
	v_cmp_ne_u32_e64 s[98:99], v88, v13
	v_cmp_ne_u32_e64 s[100:101], v89, v13
	v_cmp_ne_u32_e32 vcc, v164, v13
	v_cndmask_b32_e64 v88, 0, v88, s[98:99]
	v_max3_u32 v14, v14, v87, v88
	v_cndmask_b32_e64 v89, 0, v89, s[100:101]
	v_cndmask_b32_e32 v164, 0, v164, vcc
	v_cmp_ne_u32_e64 s[98:99], v165, v13
	v_max3_u32 v14, v14, v89, v164
	v_cmp_ne_u32_e64 s[100:101], v166, v13
	v_cndmask_b32_e64 v165, 0, v165, s[98:99]
	v_cmp_ne_u32_e32 vcc, v167, v13
	v_cndmask_b32_e64 v166, 0, v166, s[100:101]
	v_max3_u32 v14, v14, v165, v166
	v_cndmask_b32_e32 v167, 0, v167, vcc
	v_cmp_ne_u32_e64 s[98:99], v168, v13
	v_cmp_ne_u32_e64 s[100:101], v169, v13
	v_cmp_ne_u32_e32 vcc, v171, v13
	v_cndmask_b32_e64 v168, 0, v168, s[98:99]
	v_max3_u32 v14, v14, v167, v168
	v_cndmask_b32_e64 v169, 0, v169, s[100:101]
	v_cndmask_b32_e32 v171, 0, v171, vcc
	v_cmp_ne_u32_e64 s[98:99], v172, v13
	v_max3_u32 v14, v14, v169, v171
	v_cmp_ne_u32_e64 s[100:101], v173, v13
	v_cndmask_b32_e64 v172, 0, v172, s[98:99]
	v_cmp_ne_u32_e32 vcc, v176, v13
	v_cndmask_b32_e64 v173, 0, v173, s[100:101]
	v_max3_u32 v14, v14, v172, v173
	v_cndmask_b32_e32 v176, 0, v176, vcc
	v_cmp_ne_u32_e64 s[98:99], v177, v13
	v_cmp_ne_u32_e64 s[100:101], v178, v13
	v_cmp_ne_u32_e32 vcc, v179, v13
	v_cndmask_b32_e64 v177, 0, v177, s[98:99]
	v_max3_u32 v14, v14, v176, v177
	v_cndmask_b32_e64 v178, 0, v178, s[100:101]
	v_cndmask_b32_e32 v179, 0, v179, vcc
	v_cmp_ne_u32_e64 s[98:99], v183, v13
	v_max3_u32 v14, v14, v178, v179
	v_cmp_ne_u32_e64 s[100:101], v180, v13
	v_cndmask_b32_e64 v183, 0, v183, s[98:99]
	v_cmp_ne_u32_e32 vcc, v181, v13
	v_cndmask_b32_e64 v180, 0, v180, s[100:101]
	v_max3_u32 v14, v14, v183, v180
	v_cndmask_b32_e32 v181, 0, v181, vcc
	v_cmp_ne_u32_e64 s[98:99], v182, v13
	s_nop 0
	s_nop 0
	v_cndmask_b32_e64 v182, 0, v182, s[98:99]
	v_max3_u32 v14, v14, v181, v182
	v_mov_b32_e32 v194, v14
	s_nop 1
	v_permlane16_swap_b32 v14, v194
	s_nop 1
	s_waitcnt lgkmcnt(0)
; DI float unordf(unsigned k) { unsigned u = (k & 0x80000000u) ? (k & 0x7fffffffu) : ~k; return __uint_as_float(u); }
; DI void peer_topk_wave(const Params& p, int item, unsigned* lds  ) {
;     ...
; #pragma unroll
;     for (int rr = 0; rr < 16; ++rr) {
;       unsigned m = 0;
; #pragma unroll
;       for (int i = 0; i < 32; ++i) m = umax(m, kk[i]);
;       m = umax(m, (unsigned)__shfl_xor((int)m, 16));
;       m = umax(m, (unsigned)__shfl_xor((int)m, 32));
;       win[pp][rr] = m;
; #pragma unroll
;       for (int i = 0; i < 32; ++i) kk[i] = (kk[i] == m) ? 0u : kk[i];
;     }
;   }
;   float f0[16], f1[16];
; #pragma unroll
;   for (int i = 0; i < 16; ++i) { f0[i] = unordf(win[0][i] & ~127u); f1[i] = unordf(win[1][i] & ~127u); }
;   unsigned cand[13];
	v_max_u32_e32 v14, v14, v194
	ds_bpermute_b32 v194, v112, v14
	s_waitcnt lgkmcnt(0)
	v_max_u32_e32 v14, v14, v194
	v_cmp_ne_u32_e32 vcc, v185, v14
	v_cmp_eq_u32_e64 s[68:69], v184, v14
	v_cmp_eq_u32_e64 s[70:71], v186, v14
	v_cndmask_b32_e32 v185, 0, v185, vcc
	v_max_u32_e32 v184, v184, v185
	v_cndmask_b32_e64 v184, v184, v185, s[68:69]
	v_max_u32_e32 v185, v184, v186
	v_cndmask_b32_e64 v184, v185, v184, s[70:71]
	v_cmp_eq_u32_e64 s[66:67], v187, v14
	v_max_u32_e32 v185, v184, v187
	v_cmp_eq_u32_e64 s[64:65], v188, v14
	v_cndmask_b32_e64 v184, v185, v184, s[66:67]
	v_max_u32_e32 v185, v184, v188
	v_cndmask_b32_e64 v184, v185, v184, s[64:65]
	v_cmp_eq_u32_e64 s[62:63], v189, v14
	v_max_u32_e32 v185, v184, v189
	v_cmp_eq_u32_e64 s[60:61], v190, v14
	v_cndmask_b32_e64 v184, v185, v184, s[62:63]
	v_max_u32_e32 v185, v184, v190
	v_cndmask_b32_e64 v184, v185, v184, s[60:61]
	v_cmp_eq_u32_e64 s[58:59], v191, v14
	v_max_u32_e32 v185, v184, v191
	v_cmp_eq_u32_e64 s[56:57], v192, v14
	v_cndmask_b32_e64 v184, v185, v184, s[58:59]
	v_max_u32_e32 v185, v184, v192
	v_cndmask_b32_e64 v184, v185, v184, s[56:57]
	v_cmp_eq_u32_e64 s[54:55], v193, v14
	v_max_u32_e32 v185, v184, v193
	v_cmp_eq_u32_e64 s[52:53], v15, v14
	v_cndmask_b32_e64 v184, v185, v184, s[54:55]
	v_max_u32_e32 v15, v184, v15
	v_cndmask_b32_e64 v15, v15, v184, s[52:53]
	v_cmp_eq_u32_e64 s[50:51], v86, v14
	v_max_u32_e32 v86, v15, v86
	v_cmp_eq_u32_e64 s[48:49], v87, v14
	v_cndmask_b32_e64 v15, v86, v15, s[50:51]
	v_max_u32_e32 v86, v15, v87
	v_cndmask_b32_e64 v15, v86, v15, s[48:49]
	v_cmp_eq_u32_e64 s[46:47], v88, v14
	v_max_u32_e32 v86, v15, v88
	v_cmp_eq_u32_e64 s[44:45], v89, v14
	v_cndmask_b32_e64 v15, v86, v15, s[46:47]
	v_max_u32_e32 v86, v15, v89
	v_cndmask_b32_e64 v15, v86, v15, s[44:45]
	v_cmp_eq_u32_e64 s[42:43], v164, v14
	v_max_u32_e32 v86, v15, v164
	v_cmp_eq_u32_e64 s[40:41], v165, v14
	v_cndmask_b32_e64 v15, v86, v15, s[42:43]
	v_max_u32_e32 v86, v15, v165
	v_cndmask_b32_e64 v15, v86, v15, s[40:41]
	v_cmp_eq_u32_e64 s[38:39], v166, v14
	v_max_u32_e32 v86, v15, v166
	v_cmp_eq_u32_e64 s[36:37], v167, v14
	v_cndmask_b32_e64 v15, v86, v15, s[38:39]
	v_max_u32_e32 v86, v15, v167
	v_cndmask_b32_e64 v15, v86, v15, s[36:37]
	v_cmp_eq_u32_e64 s[34:35], v168, v14
	v_max_u32_e32 v86, v15, v168
	v_cmp_eq_u32_e64 s[30:31], v169, v14
	v_cndmask_b32_e64 v15, v86, v15, s[34:35]
	v_max_u32_e32 v86, v15, v169
	v_cndmask_b32_e64 v15, v86, v15, s[30:31]
	v_cmp_eq_u32_e64 s[28:29], v171, v14
	v_max_u32_e32 v86, v15, v171
	v_cmp_eq_u32_e64 s[26:27], v172, v14
	v_cndmask_b32_e64 v15, v86, v15, s[28:29]
	v_max_u32_e32 v86, v15, v172
	v_cndmask_b32_e64 v15, v86, v15, s[26:27]
	v_cmp_eq_u32_e64 s[24:25], v173, v14
	v_max_u32_e32 v86, v15, v173
	v_cmp_eq_u32_e64 s[22:23], v176, v14
	v_cndmask_b32_e64 v15, v86, v15, s[24:25]
	v_max_u32_e32 v86, v15, v176
	v_cndmask_b32_e64 v15, v86, v15, s[22:23]
	v_cmp_eq_u32_e64 s[20:21], v177, v14
	v_max_u32_e32 v86, v15, v177
	v_cmp_eq_u32_e64 s[18:19], v178, v14
	v_cndmask_b32_e64 v15, v86, v15, s[20:21]
	v_max_u32_e32 v86, v15, v178
	v_cndmask_b32_e64 v15, v86, v15, s[18:19]
	v_cmp_eq_u32_e64 s[16:17], v179, v14
	v_max_u32_e32 v86, v15, v179
	v_cmp_eq_u32_e64 s[14:15], v183, v14
	v_cndmask_b32_e64 v15, v86, v15, s[16:17]
	v_max_u32_e32 v86, v15, v183
	v_cndmask_b32_e64 v15, v86, v15, s[14:15]
	v_cmp_eq_u32_e64 s[2:3], v180, v14
	v_max_u32_e32 v86, v15, v180
	v_cmp_eq_u32_e64 s[0:1], v181, v14
	v_cndmask_b32_e64 v15, v86, v15, s[2:3]
	v_max_u32_e32 v86, v15, v181
	v_cndmask_b32_e64 v15, v86, v15, s[0:1]
	v_cmp_eq_u32_e32 vcc, v182, v14
	v_max_u32_e32 v86, v15, v182
	v_bitop3_b32 v87, v0, s81, v0 bitop3:0xcf
	v_cndmask_b32_e32 v15, v86, v15, vcc
	ds_bpermute_b32 v86, v111, v15
	v_cmp_gt_i32_e32 vcc, 0, v0
	s_waitcnt lgkmcnt(0)
	v_max_u32_e32 v15, v15, v86
	ds_bpermute_b32 v166, v112, v15
	v_and_b32_e32 v86, 0x7fffff80, v0
	v_cndmask_b32_e32 v89, v87, v86, vcc
	v_and_b32_e32 v86, 0x7fffff80, v1
	v_bitop3_b32 v87, v1, s81, v1 bitop3:0xcf
	v_cmp_gt_i32_e32 vcc, 0, v1
	s_nop 1
	v_cndmask_b32_e32 v164, v87, v86, vcc
	v_cmp_lt_i32_e32 vcc, 0, v175
	v_mov_b32_e32 v86, v89
	s_and_saveexec_b64 s[0:1], vcc
	s_cbranch_execz .LBB0_1097
	v_cmp_ne_u32_e32 vcc, 1, v175
	s_and_saveexec_b64 s[2:3], vcc
	s_xor_b64 s[2:3], exec, s[2:3]
	v_cndmask_b32_e64 v86, v164, v89, s[10:11]
	s_andn2_saveexec_b64 s[2:3], s[2:3]
	v_and_b32_e32 v86, 0x7fffff80, v13
	v_bitop3_b32 v87, v13, s81, v13 bitop3:0xcf
	v_cmp_gt_i32_e32 vcc, 0, v13
	s_nop 1
	v_cndmask_b32_e32 v86, v87, v86, vcc
	s_or_b64 exec, exec, s[2:3]

; DI void peer_topk_wave(const Params& p, int item, unsigned* lds  ) {
;     ...
;   CAND(0, 0, 0, 0, 13, 2, 0, 6, 1)
;   CAND(1, 0, 1, 0, 14, 2, 1, 7, 0)
;   CAND(2, 0, 2, 0, 15, 2, 2, 7, 1)
;   CAND(3, 0, 3, 1, 0, 2, 3, 8, 0)
;   CAND(4, 0, 4, 1, 1, 2, 4, 9, 0)
;   CAND(5, 0, 5, 1, 2, 3, 0, 10, 0)
;   CAND(6, 0, 6, 1, 3, 3, 1, 11, 0)
;   CAND(7, 0, 7, 1, 4, 3, 2, 12, 0)
;   CAND(8, 0, 8, 1, 5, 3, 3, 13, 0)
;   CAND(9, 0, 9, 1, 6, 4, 2, 14, 0)
;   CAND(10, 0, 10, 1, 7, 5, 0, 15, 0)
;   CAND(11, 0, 11, 4, 0, 5, 1, -1, -1)
;   CAND(12, 0, 12, 4, 1, 6, 0, -1, -1)
;     ...
;   unsigned w2[16];
; #pragma unroll
;   for (int rr = 0; rr < 16; ++rr) {
;     unsigned m = 0;
; #pragma unroll
;     for (int i = 0; i < 13; ++i) m = umax(m, cand[i]);
;     m = umax(m, (unsigned)__shfl_xor((int)m, 16));
;     m = umax(m, (unsigned)__shfl_xor((int)m, 32));
;     w2[rr] = m;
; #pragma unroll
;     for (int i = 0; i < 13; ++i) cand[i] = (cand[i] == m) ? 0u : cand[i];
;   }
.LBB0_1279:
	s_or_b64 exec, exec, s[0:1]
	v_add_f32_e32 v164, v197, v198
	v_not_b32_e32 v197, v164
	v_or_b32_e32 v198, 0x80000000, v164
	v_cmp_gt_i32_e32 vcc, 0, v164
	v_add_f32_e32 v162, v162, v183
	v_not_b32_e32 v183, v162
	v_cndmask_b32_e32 v164, v198, v197, vcc
	v_or_b32_e32 v197, 0x80000000, v162
	v_cmp_gt_i32_e32 vcc, 0, v162
	v_add_f32_e32 v187, v187, v188
	v_not_b32_e32 v188, v187
	v_cndmask_b32_e32 v162, v197, v183, vcc
	v_add_f32_e32 v183, v193, v194
	v_not_b32_e32 v193, v183
	v_or_b32_e32 v194, 0x80000000, v183
	v_cmp_gt_i32_e32 vcc, 0, v183
	v_add_f32_e32 v184, v184, v185
	v_not_b32_e32 v185, v184
	v_cndmask_b32_e32 v183, v194, v193, vcc
	v_and_or_b32 v182, v183, s82, v182
	v_add_f32_e32 v183, v190, v192
	v_not_b32_e32 v190, v183
	v_or_b32_e32 v192, 0x80000000, v183
	v_cmp_gt_i32_e32 vcc, 0, v183
	v_add_f32_e32 v179, v179, v180
	v_not_b32_e32 v180, v179
	v_cndmask_b32_e32 v183, v192, v190, vcc
	v_or_b32_e32 v190, 0x80000000, v187
	v_cmp_gt_i32_e32 vcc, 0, v187
	v_add_f32_e32 v176, v176, v177
	v_not_b32_e32 v177, v176
	v_cndmask_b32_e32 v187, v190, v188, vcc
	v_or_b32_e32 v188, 0x80000000, v184
	v_cmp_gt_i32_e32 vcc, 0, v184
	v_add_f32_e32 v171, v171, v172
	v_not_b32_e32 v172, v171
	v_cndmask_b32_e32 v184, v188, v185, vcc
	v_or_b32_e32 v185, 0x80000000, v179
	v_cmp_gt_i32_e32 vcc, 0, v179
	v_and_or_b32 v184, v184, s82, v186
	v_and_or_b32 v183, v183, s82, v191
	v_cndmask_b32_e32 v179, v185, v180, vcc
	v_or_b32_e32 v180, 0x80000000, v176
	v_cmp_gt_i32_e32 vcc, 0, v176
	v_and_or_b32 v179, v179, s82, v181
	v_and_or_b32 v187, v187, s82, v189
	v_cndmask_b32_e32 v176, v180, v177, vcc
	v_or_b32_e32 v177, 0x80000000, v171
	v_cmp_gt_i32_e32 vcc, 0, v171
	v_and_or_b32 v176, v176, s82, v178
	v_and_or_b32 v164, v164, s82, v201
	v_cndmask_b32_e32 v171, v177, v172, vcc
	v_and_or_b32 v171, v171, s82, v173
	v_and_b32_e32 v172, 0x7fffff80, v153
	v_bitop3_b32 v173, v153, s81, v153 bitop3:0xcf
	v_cmp_gt_i32_e32 vcc, 0, v153
	v_and_or_b32 v162, v162, s82, v195
	v_cndmask_b32_e64 v164, v164, 0, s[12:13]
	v_cndmask_b32_e32 v172, v173, v172, vcc
	v_cndmask_b32_e64 v172, v172, v169, s[10:11]
	v_cndmask_b32_e64 v172, v172, v168, s[4:5]
	v_add_f32_e32 v166, v172, v166
	v_not_b32_e32 v173, v166
	v_or_b32_e32 v177, 0x80000000, v166
	v_cmp_gt_i32_e32 vcc, 0, v166
	v_add_f32_e32 v88, v172, v88
	v_or_b32_e32 v172, 0x80000000, v88
	v_cndmask_b32_e32 v166, v177, v173, vcc
	v_and_or_b32 v167, v166, s82, v167
	v_not_b32_e32 v166, v88
	v_cmp_gt_i32_e32 vcc, 0, v88
	s_nop 1
	v_cndmask_b32_e32 v88, v172, v166, vcc
	v_and_or_b32 v88, v88, s82, v165
	v_cndmask_b32_e64 v165, v200, v169, s[10:11]
	v_cndmask_b32_e64 v165, v165, v168, s[4:5]
	v_add_f32_e32 v86, v165, v86
	v_not_b32_e32 v165, v86
	v_or_b32_e32 v166, 0x80000000, v86
	v_cmp_gt_i32_e32 vcc, 0, v86
	s_nop 1
	v_cndmask_b32_e32 v86, v166, v165, vcc
	v_and_or_b32 v86, v86, s82, v87
	v_add_f32_e32 v87, v199, v196
	v_not_b32_e32 v165, v87
	v_or_b32_e32 v166, 0x80000000, v87
	v_cmp_gt_i32_e32 vcc, 0, v87
	s_nop 1
	v_cndmask_b32_e32 v87, v166, v165, vcc
	v_and_or_b32 v87, v87, s82, v89
	v_max3_u32 v89, v86, v88, v167
	v_max3_u32 v89, v89, v171, v176
	v_max3_u32 v89, v89, v179, v184
	v_max3_u32 v89, v89, v187, v183
	v_cndmask_b32_e64 v87, v87, 0, s[12:13]
	v_max3_u32 v89, v89, v182, v162
	v_max3_u32 v89, v89, v164, v87
	v_mov_b32_e32 v165, v89
	s_nop 1
	v_permlane16_swap_b32 v89, v165
	s_nop 1
	s_waitcnt lgkmcnt(0)
	v_max_u32_e32 v89, v89, v165
	v_mov_b32_e32 v165, v89
	s_nop 1
	v_permlane32_swap_b32 v89, v165
	s_nop 1
	s_waitcnt lgkmcnt(0)
	v_max_u32_e32 v166, v89, v165
	v_cmp_ne_u32_e32 vcc, v86, v166
	v_cmp_ne_u32_e64 s[98:99], v88, v166
	v_cmp_ne_u32_e64 s[100:101], v167, v166
	v_cndmask_b32_e32 v86, 0, v86, vcc
	v_cndmask_b32_e64 v89, 0, v88, s[98:99]
	v_cndmask_b32_e64 v165, 0, v167, s[100:101]
	v_cmp_ne_u32_e32 vcc, v171, v166
	v_max3_u32 v88, v86, v89, v165
	v_cmp_ne_u32_e64 s[98:99], v176, v166
	v_cndmask_b32_e32 v167, 0, v171, vcc
	v_cmp_ne_u32_e64 s[100:101], v179, v166
	v_cndmask_b32_e64 v168, 0, v176, s[98:99]
	v_max3_u32 v88, v88, v167, v168
	v_cndmask_b32_e64 v169, 0, v179, s[100:101]
	v_cmp_ne_u32_e32 vcc, v184, v166
	v_cmp_ne_u32_e64 s[98:99], v187, v166
	v_cmp_ne_u32_e64 s[100:101], v183, v166
	v_cndmask_b32_e32 v171, 0, v184, vcc
	v_max3_u32 v88, v88, v169, v171
	v_cndmask_b32_e64 v172, 0, v187, s[98:99]
	v_cndmask_b32_e64 v173, 0, v183, s[100:101]
	v_cmp_ne_u32_e32 vcc, v182, v166
	v_max3_u32 v88, v88, v172, v173
	v_cmp_ne_u32_e64 s[98:99], v162, v166
	v_cndmask_b32_e32 v176, 0, v182, vcc
	v_cmp_ne_u32_e64 s[100:101], v164, v166
	v_cndmask_b32_e64 v162, 0, v162, s[98:99]
	v_max3_u32 v88, v88, v176, v162
	v_cndmask_b32_e64 v164, 0, v164, s[100:101]
	v_cmp_ne_u32_e32 vcc, v87, v166
	s_nop 0
	s_nop 0
	v_cndmask_b32_e32 v87, 0, v87, vcc
	v_max3_u32 v88, v88, v164, v87
	v_mov_b32_e32 v177, v88
	s_nop 1
	v_permlane16_swap_b32 v88, v177
	s_nop 1
	s_waitcnt lgkmcnt(0)
	v_max_u32_e32 v88, v88, v177
	v_mov_b32_e32 v177, v88
	s_nop 1
	v_permlane32_swap_b32 v88, v177
	s_nop 1
	s_waitcnt lgkmcnt(0)
; DI void peer_topk_wave(const Params& p, int item, unsigned* lds  ) {
;     ...
;   unsigned w2[16];
; #pragma unroll
;   for (int rr = 0; rr < 16; ++rr) {
;     unsigned m = 0;
; #pragma unroll
;     for (int i = 0; i < 13; ++i) m = umax(m, cand[i]);
;     m = umax(m, (unsigned)__shfl_xor((int)m, 16));
;     m = umax(m, (unsigned)__shfl_xor((int)m, 32));
;     w2[rr] = m;
; #pragma unroll
;     for (int i = 0; i < 13; ++i) cand[i] = (cand[i] == m) ? 0u : cand[i];
;   }
	v_max_u32_e32 v88, v88, v177
	v_cmp_ne_u32_e32 vcc, v86, v88
	v_cmp_ne_u32_e64 s[98:99], v89, v88
	v_cmp_ne_u32_e64 s[100:101], v165, v88
	v_cndmask_b32_e32 v86, 0, v86, vcc
	v_cndmask_b32_e64 v89, 0, v89, s[98:99]
	v_cndmask_b32_e64 v165, 0, v165, s[100:101]
	v_cmp_ne_u32_e32 vcc, v167, v88
	v_cmp_ne_u32_e64 s[98:99], v168, v88
	v_cmp_ne_u32_e64 s[100:101], v169, v88
	v_cndmask_b32_e32 v167, 0, v167, vcc
	v_cndmask_b32_e64 v168, 0, v168, s[98:99]
	v_cndmask_b32_e64 v169, 0, v169, s[100:101]
	v_cmp_ne_u32_e32 vcc, v171, v88
	v_cmp_ne_u32_e64 s[98:99], v172, v88
	v_cmp_ne_u32_e64 s[100:101], v173, v88
	v_cndmask_b32_e32 v171, 0, v171, vcc
	v_cndmask_b32_e64 v172, 0, v172, s[98:99]
	v_cndmask_b32_e64 v173, 0, v173, s[100:101]
	v_cmp_ne_u32_e32 vcc, v176, v88
	v_cmp_ne_u32_e64 s[98:99], v162, v88
	v_cmp_ne_u32_e64 s[100:101], v164, v88
	v_cndmask_b32_e32 v176, 0, v176, vcc
	v_cndmask_b32_e64 v162, 0, v162, s[98:99]
	v_cndmask_b32_e64 v164, 0, v164, s[100:101]
	v_cmp_ne_u32_e32 vcc, v87, v88
	s_nop 0
	s_nop 0
	v_cndmask_b32_e32 v177, 0, v87, vcc
	v_max3_u32 v87, v86, v89, v165
	v_max3_u32 v87, v87, v167, v168
	v_max3_u32 v87, v87, v169, v171
	v_max3_u32 v87, v87, v172, v173
	v_max3_u32 v87, v87, v176, v162
	v_max3_u32 v87, v87, v164, v177
	v_mov_b32_e32 v178, v87
	s_nop 1
	v_permlane16_swap_b32 v87, v178
	s_nop 1
	s_waitcnt lgkmcnt(0)
	v_max_u32_e32 v87, v87, v178
	v_mov_b32_e32 v178, v87
	s_nop 1
	v_permlane32_swap_b32 v87, v178
	s_nop 1
	s_waitcnt lgkmcnt(0)
	v_max_u32_e32 v87, v87, v178
	v_cmp_ne_u32_e32 vcc, v86, v87
	v_cmp_ne_u32_e64 s[98:99], v89, v87
	v_cmp_ne_u32_e64 s[100:101], v165, v87
	v_cndmask_b32_e32 v178, 0, v86, vcc
	v_cndmask_b32_e64 v89, 0, v89, s[98:99]
	v_cndmask_b32_e64 v165, 0, v165, s[100:101]
	v_cmp_ne_u32_e32 vcc, v167, v87
	v_max3_u32 v86, v178, v89, v165
	v_cmp_ne_u32_e64 s[98:99], v168, v87
	v_cndmask_b32_e32 v167, 0, v167, vcc
	v_cmp_ne_u32_e64 s[100:101], v169, v87
	v_cndmask_b32_e64 v168, 0, v168, s[98:99]
	v_max3_u32 v86, v86, v167, v168
	v_cndmask_b32_e64 v169, 0, v169, s[100:101]
	v_cmp_ne_u32_e32 vcc, v171, v87
	v_cmp_ne_u32_e64 s[98:99], v172, v87
	v_cmp_ne_u32_e64 s[100:101], v173, v87
	v_cndmask_b32_e32 v171, 0, v171, vcc
	v_max3_u32 v86, v86, v169, v171
	v_cndmask_b32_e64 v172, 0, v172, s[98:99]
	v_cndmask_b32_e64 v173, 0, v173, s[100:101]
	v_cmp_ne_u32_e32 vcc, v176, v87
	v_max3_u32 v86, v86, v172, v173
	v_cmp_ne_u32_e64 s[98:99], v162, v87
	v_cndmask_b32_e32 v176, 0, v176, vcc
	v_cmp_ne_u32_e64 s[100:101], v164, v87
	v_cndmask_b32_e64 v162, 0, v162, s[98:99]
	v_max3_u32 v86, v86, v176, v162
	v_cndmask_b32_e64 v164, 0, v164, s[100:101]
	v_cmp_ne_u32_e32 vcc, v177, v87
	s_nop 0
	s_nop 0
	v_cndmask_b32_e32 v177, 0, v177, vcc
	v_max3_u32 v86, v86, v164, v177
	v_mov_b32_e32 v179, v86
	s_nop 1
	v_permlane16_swap_b32 v86, v179
	s_nop 1
	s_waitcnt lgkmcnt(0)
	v_max_u32_e32 v86, v86, v179
	v_mov_b32_e32 v179, v86
	s_nop 1
	v_permlane32_swap_b32 v86, v179
	s_nop 1
	s_waitcnt lgkmcnt(0)
	v_max_u32_e32 v86, v86, v179
	v_cmp_ne_u32_e32 vcc, v178, v86
	v_cmp_ne_u32_e64 s[98:99], v89, v86
	v_cmp_ne_u32_e64 s[100:101], v165, v86
	v_cndmask_b32_e32 v178, 0, v178, vcc
	v_cndmask_b32_e64 v89, 0, v89, s[98:99]
	v_cndmask_b32_e64 v165, 0, v165, s[100:101]
	v_cmp_ne_u32_e32 vcc, v167, v86
	v_cmp_ne_u32_e64 s[98:99], v168, v86
	v_cmp_ne_u32_e64 s[100:101], v169, v86
	v_cndmask_b32_e32 v167, 0, v167, vcc
	v_cndmask_b32_e64 v168, 0, v168, s[98:99]
	v_cndmask_b32_e64 v179, 0, v169, s[100:101]
	v_cmp_ne_u32_e32 vcc, v171, v86
	v_max3_u32 v169, v178, v89, v165
	v_max3_u32 v169, v169, v167, v168
	v_cndmask_b32_e32 v171, 0, v171, vcc
	v_cmp_ne_u32_e64 s[98:99], v172, v86
	v_max3_u32 v169, v169, v179, v171
	v_cmp_ne_u32_e64 s[100:101], v173, v86
	v_cndmask_b32_e64 v172, 0, v172, s[98:99]
	v_cmp_ne_u32_e32 vcc, v176, v86
	v_cndmask_b32_e64 v173, 0, v173, s[100:101]
	v_max3_u32 v169, v169, v172, v173
	v_cndmask_b32_e32 v176, 0, v176, vcc
	v_cmp_ne_u32_e64 s[98:99], v162, v86
	v_cmp_ne_u32_e64 s[100:101], v164, v86
	v_cmp_ne_u32_e32 vcc, v177, v86
	v_cndmask_b32_e64 v162, 0, v162, s[98:99]
	v_max3_u32 v169, v169, v176, v162
	v_cndmask_b32_e64 v164, 0, v164, s[100:101]
	v_cndmask_b32_e32 v177, 0, v177, vcc
	v_max3_u32 v169, v169, v164, v177
	v_mov_b32_e32 v180, v169
	s_nop 1
	v_permlane16_swap_b32 v169, v180
	s_nop 1
	s_waitcnt lgkmcnt(0)
	v_max_u32_e32 v169, v169, v180
	v_mov_b32_e32 v180, v169
	s_nop 1
	v_permlane32_swap_b32 v169, v180
	s_nop 1
	s_waitcnt lgkmcnt(0)
	v_max_u32_e32 v169, v169, v180
	v_cmp_ne_u32_e32 vcc, v178, v169
	v_cmp_ne_u32_e64 s[98:99], v89, v169
	v_cmp_ne_u32_e64 s[100:101], v165, v169
	v_cndmask_b32_e32 v178, 0, v178, vcc
	v_cndmask_b32_e64 v89, 0, v89, s[98:99]
	v_cndmask_b32_e64 v165, 0, v165, s[100:101]
	v_cmp_ne_u32_e32 vcc, v167, v169
	v_cmp_ne_u32_e64 s[98:99], v168, v169
	v_cmp_ne_u32_e64 s[100:101], v179, v169
	v_cndmask_b32_e32 v167, 0, v167, vcc
	v_cndmask_b32_e64 v168, 0, v168, s[98:99]
	v_cndmask_b32_e64 v179, 0, v179, s[100:101]
	v_cmp_ne_u32_e32 vcc, v171, v169
	v_cmp_ne_u32_e64 s[98:99], v172, v169
	v_cmp_ne_u32_e64 s[100:101], v173, v169
	v_cndmask_b32_e32 v171, 0, v171, vcc
	v_cndmask_b32_e64 v172, 0, v172, s[98:99]
	v_cndmask_b32_e64 v173, 0, v173, s[100:101]
	v_cmp_ne_u32_e32 vcc, v176, v169
	v_cmp_ne_u32_e64 s[98:99], v162, v169
	v_cmp_ne_u32_e64 s[100:101], v164, v169
	v_cndmask_b32_e32 v176, 0, v176, vcc
	v_cndmask_b32_e64 v162, 0, v162, s[98:99]
	v_cndmask_b32_e64 v180, 0, v164, s[100:101]
	v_max3_u32 v164, v178, v89, v165
	v_max3_u32 v164, v164, v167, v168
	v_max3_u32 v164, v164, v179, v171
	v_cmp_ne_u32_e32 vcc, v177, v169
	v_max3_u32 v164, v164, v172, v173
	v_max3_u32 v164, v164, v176, v162
	v_cndmask_b32_e32 v177, 0, v177, vcc
	v_max3_u32 v164, v164, v180, v177
	v_mov_b32_e32 v181, v164
	s_nop 1
	v_permlane16_swap_b32 v164, v181
	s_nop 1
	s_waitcnt lgkmcnt(0)
; DI void peer_topk_wave(const Params& p, int item, unsigned* lds  ) {
;     ...
;   unsigned w2[16];
; #pragma unroll
;   for (int rr = 0; rr < 16; ++rr) {
;     unsigned m = 0;
; #pragma unroll
;     for (int i = 0; i < 13; ++i) m = umax(m, cand[i]);
;     m = umax(m, (unsigned)__shfl_xor((int)m, 16));
;     m = umax(m, (unsigned)__shfl_xor((int)m, 32));
;     w2[rr] = m;
; #pragma unroll
;     for (int i = 0; i < 13; ++i) cand[i] = (cand[i] == m) ? 0u : cand[i];
;   }
	v_max_u32_e32 v164, v164, v181
	v_mov_b32_e32 v181, v164
	s_nop 1
	v_permlane32_swap_b32 v164, v181
	s_nop 1
	s_waitcnt lgkmcnt(0)
	v_max_u32_e32 v164, v164, v181
	v_cmp_ne_u32_e32 vcc, v178, v164
	v_cmp_ne_u32_e64 s[98:99], v89, v164
	v_cmp_ne_u32_e64 s[100:101], v165, v164
	v_cndmask_b32_e32 v178, 0, v178, vcc
	v_cndmask_b32_e64 v89, 0, v89, s[98:99]
	v_cndmask_b32_e64 v165, 0, v165, s[100:101]
	v_cmp_ne_u32_e32 vcc, v167, v164
	v_cmp_ne_u32_e64 s[98:99], v168, v164
	v_cmp_ne_u32_e64 s[100:101], v179, v164
	v_cndmask_b32_e32 v167, 0, v167, vcc
	v_cndmask_b32_e64 v168, 0, v168, s[98:99]
	v_cndmask_b32_e64 v179, 0, v179, s[100:101]
	v_cmp_ne_u32_e32 vcc, v171, v164
	v_cmp_ne_u32_e64 s[98:99], v172, v164
	v_cmp_ne_u32_e64 s[100:101], v173, v164
	v_cndmask_b32_e32 v171, 0, v171, vcc
	v_cndmask_b32_e64 v172, 0, v172, s[98:99]
	v_cndmask_b32_e64 v173, 0, v173, s[100:101]
	v_cmp_ne_u32_e32 vcc, v176, v164
	v_cmp_ne_u32_e64 s[98:99], v162, v164
	v_cmp_ne_u32_e64 s[100:101], v180, v164
	v_cndmask_b32_e32 v176, 0, v176, vcc
	v_cndmask_b32_e64 v181, 0, v162, s[98:99]
	v_max3_u32 v162, v178, v89, v165
	v_max3_u32 v162, v162, v167, v168
	v_max3_u32 v162, v162, v179, v171
	v_max3_u32 v162, v162, v172, v173
	v_cndmask_b32_e64 v180, 0, v180, s[100:101]
	v_cmp_ne_u32_e32 vcc, v177, v164
	v_max3_u32 v162, v162, v176, v181
	s_nop 0
	v_cndmask_b32_e32 v177, 0, v177, vcc
	v_max3_u32 v162, v162, v180, v177
	v_mov_b32_e32 v182, v162
	s_nop 1
	v_permlane16_swap_b32 v162, v182
	s_nop 1
	s_waitcnt lgkmcnt(0)
	v_max_u32_e32 v162, v162, v182
	v_mov_b32_e32 v182, v162
	s_nop 1
	v_permlane32_swap_b32 v162, v182
	s_nop 1
	s_waitcnt lgkmcnt(0)
	v_max_u32_e32 v162, v162, v182
	v_cmp_ne_u32_e32 vcc, v178, v162
	v_cmp_ne_u32_e64 s[98:99], v89, v162
	v_cmp_ne_u32_e64 s[100:101], v165, v162
	v_cndmask_b32_e32 v178, 0, v178, vcc
	v_cndmask_b32_e64 v182, 0, v89, s[98:99]
	v_cndmask_b32_e64 v165, 0, v165, s[100:101]
	v_cmp_ne_u32_e32 vcc, v167, v162
	v_max3_u32 v89, v178, v182, v165
	v_cmp_ne_u32_e64 s[98:99], v168, v162
	v_cndmask_b32_e32 v167, 0, v167, vcc
	v_cmp_ne_u32_e64 s[100:101], v179, v162
	v_cndmask_b32_e64 v168, 0, v168, s[98:99]
	v_max3_u32 v89, v89, v167, v168
	v_cndmask_b32_e64 v179, 0, v179, s[100:101]
	v_cmp_ne_u32_e32 vcc, v171, v162
	v_cmp_ne_u32_e64 s[98:99], v172, v162
	v_cmp_ne_u32_e64 s[100:101], v173, v162
	v_cndmask_b32_e32 v171, 0, v171, vcc
	v_max3_u32 v89, v89, v179, v171
	v_cndmask_b32_e64 v172, 0, v172, s[98:99]
	v_cndmask_b32_e64 v173, 0, v173, s[100:101]
	v_cmp_ne_u32_e32 vcc, v176, v162
	v_max3_u32 v89, v89, v172, v173
	v_cmp_ne_u32_e64 s[98:99], v181, v162
	v_cndmask_b32_e32 v176, 0, v176, vcc
	v_cmp_ne_u32_e64 s[100:101], v180, v162
	v_cndmask_b32_e64 v181, 0, v181, s[98:99]
	v_max3_u32 v89, v89, v176, v181
	v_cndmask_b32_e64 v180, 0, v180, s[100:101]
	v_cmp_ne_u32_e32 vcc, v177, v162
	s_nop 0
	s_nop 0
	v_cndmask_b32_e32 v177, 0, v177, vcc
	v_max3_u32 v89, v89, v180, v177
	v_mov_b32_e32 v183, v89
	s_nop 1
	v_permlane16_swap_b32 v89, v183
	s_nop 1
	s_waitcnt lgkmcnt(0)
	v_max_u32_e32 v89, v89, v183
	v_mov_b32_e32 v183, v89
	s_nop 1
	v_permlane32_swap_b32 v89, v183
	s_nop 1
	s_waitcnt lgkmcnt(0)
	v_max_u32_e32 v89, v89, v183
	v_cmp_ne_u32_e32 vcc, v178, v89
	v_cmp_ne_u32_e64 s[98:99], v182, v89
	v_cmp_ne_u32_e64 s[100:101], v165, v89
	v_cndmask_b32_e32 v178, 0, v178, vcc
	v_cndmask_b32_e64 v182, 0, v182, s[98:99]
	v_cndmask_b32_e64 v165, 0, v165, s[100:101]
	v_cmp_ne_u32_e32 vcc, v167, v89
	v_cmp_ne_u32_e64 s[98:99], v168, v89
	v_cmp_ne_u32_e64 s[100:101], v179, v89
	v_cndmask_b32_e32 v167, 0, v167, vcc
	v_cndmask_b32_e64 v168, 0, v168, s[98:99]
	v_cndmask_b32_e64 v179, 0, v179, s[100:101]
	v_cmp_ne_u32_e32 vcc, v171, v89
	v_cmp_ne_u32_e64 s[98:99], v172, v89
	v_cmp_ne_u32_e64 s[100:101], v173, v89
	v_cndmask_b32_e32 v171, 0, v171, vcc
	v_cndmask_b32_e64 v183, 0, v172, s[98:99]
	v_max3_u32 v172, v178, v182, v165
	v_max3_u32 v172, v172, v167, v168
	v_cndmask_b32_e64 v173, 0, v173, s[100:101]
	v_cmp_ne_u32_e32 vcc, v176, v89
	v_max3_u32 v172, v172, v179, v171
	v_max3_u32 v172, v172, v183, v173
	v_cndmask_b32_e32 v176, 0, v176, vcc
	v_cmp_ne_u32_e64 s[98:99], v181, v89
	v_cmp_ne_u32_e64 s[100:101], v180, v89
	v_cmp_ne_u32_e32 vcc, v177, v89
	v_cndmask_b32_e64 v181, 0, v181, s[98:99]
	v_max3_u32 v172, v172, v176, v181
	v_cndmask_b32_e64 v180, 0, v180, s[100:101]
	v_cndmask_b32_e32 v177, 0, v177, vcc
	v_max3_u32 v172, v172, v180, v177
	v_mov_b32_e32 v184, v172
	s_nop 1
	v_permlane16_swap_b32 v172, v184
	s_nop 1
	s_waitcnt lgkmcnt(0)
	v_max_u32_e32 v172, v172, v184
	v_mov_b32_e32 v184, v172
	s_nop 1
	v_permlane32_swap_b32 v172, v184
	s_nop 1
	s_waitcnt lgkmcnt(0)
	v_max_u32_e32 v172, v172, v184
	v_cmp_ne_u32_e32 vcc, v178, v172
	v_cmp_ne_u32_e64 s[98:99], v182, v172
	v_cmp_ne_u32_e64 s[100:101], v165, v172
	v_cndmask_b32_e32 v178, 0, v178, vcc
	v_cndmask_b32_e64 v182, 0, v182, s[98:99]
	v_cndmask_b32_e64 v165, 0, v165, s[100:101]
	v_cmp_ne_u32_e32 vcc, v167, v172
	v_cmp_ne_u32_e64 s[98:99], v168, v172
	v_cmp_ne_u32_e64 s[100:101], v179, v172
	v_cndmask_b32_e32 v167, 0, v167, vcc
	v_cndmask_b32_e64 v184, 0, v168, s[98:99]
	v_max3_u32 v168, v178, v182, v165
	v_max3_u32 v168, v168, v167, v184
	v_cndmask_b32_e64 v179, 0, v179, s[100:101]
	v_cmp_ne_u32_e32 vcc, v171, v172
	v_cmp_ne_u32_e64 s[98:99], v183, v172
	v_cmp_ne_u32_e64 s[100:101], v173, v172
	v_cndmask_b32_e32 v171, 0, v171, vcc
	v_max3_u32 v168, v168, v179, v171
	v_cndmask_b32_e64 v183, 0, v183, s[98:99]
	v_cndmask_b32_e64 v173, 0, v173, s[100:101]
	v_cmp_ne_u32_e32 vcc, v176, v172
	v_max3_u32 v168, v168, v183, v173
	v_cmp_ne_u32_e64 s[98:99], v181, v172
	v_cndmask_b32_e32 v176, 0, v176, vcc
	v_cmp_ne_u32_e64 s[100:101], v180, v172
	v_cndmask_b32_e64 v181, 0, v181, s[98:99]
	v_max3_u32 v168, v168, v176, v181
	v_cndmask_b32_e64 v180, 0, v180, s[100:101]
	v_cmp_ne_u32_e32 vcc, v177, v172
	s_nop 0
	s_nop 0
	v_cndmask_b32_e32 v177, 0, v177, vcc
	v_max3_u32 v168, v168, v180, v177
	v_mov_b32_e32 v185, v168
	s_nop 1
	v_permlane16_swap_b32 v168, v185
	s_nop 1
	s_waitcnt lgkmcnt(0)
; DI void peer_topk_wave(const Params& p, int item, unsigned* lds  ) {
;     ...
;   unsigned w2[16];
; #pragma unroll
;   for (int rr = 0; rr < 16; ++rr) {
;     unsigned m = 0;
; #pragma unroll
;     for (int i = 0; i < 13; ++i) m = umax(m, cand[i]);
;     m = umax(m, (unsigned)__shfl_xor((int)m, 16));
;     m = umax(m, (unsigned)__shfl_xor((int)m, 32));
;     w2[rr] = m;
; #pragma unroll
;     for (int i = 0; i < 13; ++i) cand[i] = (cand[i] == m) ? 0u : cand[i];
;   }
	v_max_u32_e32 v168, v168, v185
	v_mov_b32_e32 v185, v168
	s_nop 1
	v_permlane32_swap_b32 v168, v185
	s_nop 1
	s_waitcnt lgkmcnt(0)
	v_max_u32_e32 v168, v168, v185
	v_cmp_ne_u32_e32 vcc, v178, v168
	v_cmp_ne_u32_e64 s[98:99], v182, v168
	v_cmp_ne_u32_e64 s[100:101], v165, v168
	v_cndmask_b32_e32 v178, 0, v178, vcc
	v_cndmask_b32_e64 v182, 0, v182, s[98:99]
	v_cndmask_b32_e64 v165, 0, v165, s[100:101]
	v_cmp_ne_u32_e32 vcc, v167, v168
	v_cmp_ne_u32_e64 s[98:99], v184, v168
	v_cmp_ne_u32_e64 s[100:101], v179, v168
	v_cndmask_b32_e32 v185, 0, v167, vcc
	v_max3_u32 v167, v178, v182, v165
	v_cndmask_b32_e64 v184, 0, v184, s[98:99]
	v_max3_u32 v167, v167, v185, v184
	v_cndmask_b32_e64 v179, 0, v179, s[100:101]
	v_cmp_ne_u32_e32 vcc, v171, v168
	v_cmp_ne_u32_e64 s[98:99], v183, v168
	v_cmp_ne_u32_e64 s[100:101], v173, v168
	v_cndmask_b32_e32 v171, 0, v171, vcc
	v_max3_u32 v167, v167, v179, v171
	v_cndmask_b32_e64 v183, 0, v183, s[98:99]
	v_cndmask_b32_e64 v173, 0, v173, s[100:101]
	v_cmp_ne_u32_e32 vcc, v176, v168
	v_max3_u32 v167, v167, v183, v173
	v_cmp_ne_u32_e64 s[98:99], v181, v168
	v_cndmask_b32_e32 v176, 0, v176, vcc
	v_cmp_ne_u32_e64 s[100:101], v180, v168
	v_cndmask_b32_e64 v181, 0, v181, s[98:99]
	v_max3_u32 v167, v167, v176, v181
	v_cndmask_b32_e64 v180, 0, v180, s[100:101]
	v_cmp_ne_u32_e32 vcc, v177, v168
	s_nop 0
	s_nop 0
	v_cndmask_b32_e32 v177, 0, v177, vcc
	v_max3_u32 v167, v167, v180, v177
	v_mov_b32_e32 v186, v167
	s_nop 1
	v_permlane16_swap_b32 v167, v186
	s_nop 1
	s_waitcnt lgkmcnt(0)
	v_max_u32_e32 v167, v167, v186
	v_mov_b32_e32 v186, v167
	s_nop 1
	v_permlane32_swap_b32 v167, v186
	s_nop 1
	s_waitcnt lgkmcnt(0)
	v_max_u32_e32 v167, v167, v186
	v_cmp_ne_u32_e32 vcc, v178, v167
	v_cmp_ne_u32_e64 s[98:99], v182, v167
	v_cmp_ne_u32_e64 s[100:101], v165, v167
	v_cndmask_b32_e32 v178, 0, v178, vcc
	v_cndmask_b32_e64 v182, 0, v182, s[98:99]
	v_cndmask_b32_e64 v186, 0, v165, s[100:101]
	v_cmp_ne_u32_e32 vcc, v185, v167
	v_max3_u32 v165, v178, v182, v186
	v_cmp_ne_u32_e64 s[98:99], v184, v167
	v_cndmask_b32_e32 v185, 0, v185, vcc
	v_cmp_ne_u32_e64 s[100:101], v179, v167
	v_cndmask_b32_e64 v184, 0, v184, s[98:99]
	v_max3_u32 v165, v165, v185, v184
	v_cndmask_b32_e64 v179, 0, v179, s[100:101]
	v_cmp_ne_u32_e32 vcc, v171, v167
	v_cmp_ne_u32_e64 s[98:99], v183, v167
	v_cmp_ne_u32_e64 s[100:101], v173, v167
	v_cndmask_b32_e32 v171, 0, v171, vcc
	v_max3_u32 v165, v165, v179, v171
	v_cndmask_b32_e64 v183, 0, v183, s[98:99]
	v_cndmask_b32_e64 v173, 0, v173, s[100:101]
	v_cmp_ne_u32_e32 vcc, v176, v167
	v_max3_u32 v165, v165, v183, v173
	v_cmp_ne_u32_e64 s[98:99], v181, v167
	v_cndmask_b32_e32 v176, 0, v176, vcc
	v_cmp_ne_u32_e64 s[100:101], v180, v167
	v_cndmask_b32_e64 v181, 0, v181, s[98:99]
	v_max3_u32 v165, v165, v176, v181
	v_cndmask_b32_e64 v180, 0, v180, s[100:101]
	v_cmp_ne_u32_e32 vcc, v177, v167
	s_nop 0
	s_nop 0
	v_cndmask_b32_e32 v177, 0, v177, vcc
	v_max3_u32 v165, v165, v180, v177
	v_mov_b32_e32 v187, v165
	s_nop 1
	v_permlane16_swap_b32 v165, v187
	s_nop 1
	s_waitcnt lgkmcnt(0)
	v_max_u32_e32 v165, v165, v187
	v_mov_b32_e32 v187, v165
	s_nop 1
	v_permlane32_swap_b32 v165, v187
	s_nop 1
	s_waitcnt lgkmcnt(0)
	v_max_u32_e32 v165, v165, v187
	v_cmp_ne_u32_e32 vcc, v178, v165
	v_cmp_ne_u32_e64 s[98:99], v182, v165
	v_cmp_ne_u32_e64 s[100:101], v186, v165
	v_cndmask_b32_e32 v178, 0, v178, vcc
	v_cndmask_b32_e64 v182, 0, v182, s[98:99]
	v_cndmask_b32_e64 v186, 0, v186, s[100:101]
	v_cmp_ne_u32_e32 vcc, v185, v165
	v_cmp_ne_u32_e64 s[98:99], v184, v165
	v_cmp_ne_u32_e64 s[100:101], v179, v165
	v_cndmask_b32_e32 v185, 0, v185, vcc
	v_cndmask_b32_e64 v184, 0, v184, s[98:99]
	v_cndmask_b32_e64 v179, 0, v179, s[100:101]
	v_cmp_ne_u32_e32 vcc, v171, v165
	v_cmp_ne_u32_e64 s[98:99], v183, v165
	v_cmp_ne_u32_e64 s[100:101], v173, v165
	v_cndmask_b32_e32 v171, 0, v171, vcc
	v_cndmask_b32_e64 v183, 0, v183, s[98:99]
	v_cndmask_b32_e64 v173, 0, v173, s[100:101]
	v_cmp_ne_u32_e32 vcc, v176, v165
	v_cmp_ne_u32_e64 s[98:99], v181, v165
	v_cmp_ne_u32_e64 s[100:101], v180, v165
	v_cndmask_b32_e32 v187, 0, v176, vcc
	v_max3_u32 v176, v178, v182, v186
	v_max3_u32 v176, v176, v185, v184
	v_max3_u32 v176, v176, v179, v171
	v_cndmask_b32_e64 v181, 0, v181, s[98:99]
	v_max3_u32 v176, v176, v183, v173
	v_max3_u32 v176, v176, v187, v181
	v_cndmask_b32_e64 v180, 0, v180, s[100:101]
	v_cmp_ne_u32_e32 vcc, v177, v165
	s_nop 0
	s_nop 0
	v_cndmask_b32_e32 v177, 0, v177, vcc
	v_max3_u32 v176, v176, v180, v177
	v_mov_b32_e32 v188, v176
	s_nop 1
	v_permlane16_swap_b32 v176, v188
	s_nop 1
	s_waitcnt lgkmcnt(0)
	v_max_u32_e32 v176, v176, v188
	v_mov_b32_e32 v188, v176
	s_nop 1
	v_permlane32_swap_b32 v176, v188
	s_nop 1
	s_waitcnt lgkmcnt(0)
; DI void peer_topk_wave(const Params& p, int item, unsigned* lds  ) {
;     ...
;   unsigned w2[16];
; #pragma unroll
;   for (int rr = 0; rr < 16; ++rr) {
;     unsigned m = 0;
; #pragma unroll
;     for (int i = 0; i < 13; ++i) m = umax(m, cand[i]);
;     m = umax(m, (unsigned)__shfl_xor((int)m, 16));
;     m = umax(m, (unsigned)__shfl_xor((int)m, 32));
;     w2[rr] = m;
; #pragma unroll
;     for (int i = 0; i < 13; ++i) cand[i] = (cand[i] == m) ? 0u : cand[i];
;   }
;   if (kg == 0) {
; #pragma unroll
;     for (int i = 0; i < 16; ++i) { lds[r * 32 + i] = win[0][i] & 127u; lds[r * 32 + 16 + i] = win[1][i] & 127u; }
;   }
	v_max_u32_e32 v176, v176, v188
	v_cmp_ne_u32_e32 vcc, v178, v176
	v_cmp_ne_u32_e64 s[98:99], v182, v176
	v_cmp_ne_u32_e64 s[100:101], v186, v176
	v_cndmask_b32_e32 v178, 0, v178, vcc
	v_cndmask_b32_e64 v182, 0, v182, s[98:99]
	v_cndmask_b32_e64 v186, 0, v186, s[100:101]
	v_cmp_ne_u32_e32 vcc, v185, v176
	v_cmp_ne_u32_e64 s[98:99], v184, v176
	v_cmp_ne_u32_e64 s[100:101], v179, v176
	v_cndmask_b32_e32 v185, 0, v185, vcc
	v_cndmask_b32_e64 v184, 0, v184, s[98:99]
	v_cndmask_b32_e64 v179, 0, v179, s[100:101]
	v_cmp_ne_u32_e32 vcc, v171, v176
	v_cmp_ne_u32_e64 s[98:99], v183, v176
	v_cmp_ne_u32_e64 s[100:101], v173, v176
	v_cndmask_b32_e32 v171, 0, v171, vcc
	v_cndmask_b32_e64 v183, 0, v183, s[98:99]
	v_cndmask_b32_e64 v188, 0, v173, s[100:101]
	v_cmp_ne_u32_e32 vcc, v187, v176
	v_max3_u32 v173, v178, v182, v186
	v_max3_u32 v173, v173, v185, v184
	v_cndmask_b32_e32 v187, 0, v187, vcc
	v_cmp_ne_u32_e64 s[98:99], v181, v176
	v_max3_u32 v173, v173, v179, v171
	v_max3_u32 v173, v173, v183, v188
	v_cndmask_b32_e64 v181, 0, v181, s[98:99]
	v_cmp_ne_u32_e64 s[100:101], v180, v176
	v_max3_u32 v173, v173, v187, v181
	v_cmp_ne_u32_e32 vcc, v177, v176
	v_cndmask_b32_e64 v180, 0, v180, s[100:101]
	s_nop 0
	v_cndmask_b32_e32 v177, 0, v177, vcc
	v_max3_u32 v173, v173, v180, v177
	v_mov_b32_e32 v189, v173
	s_nop 1
	v_permlane16_swap_b32 v173, v189
	s_nop 1
	s_waitcnt lgkmcnt(0)
	v_max_u32_e32 v173, v173, v189
	v_mov_b32_e32 v189, v173
	s_nop 1
	v_permlane32_swap_b32 v173, v189
	s_nop 1
	s_waitcnt lgkmcnt(0)
	v_max_u32_e32 v173, v173, v189
	v_cmp_ne_u32_e32 vcc, v178, v173
	v_cmp_ne_u32_e64 s[98:99], v182, v173
	v_cmp_ne_u32_e64 s[100:101], v186, v173
	v_cndmask_b32_e32 v178, 0, v178, vcc
	v_cndmask_b32_e64 v182, 0, v182, s[98:99]
	v_cndmask_b32_e64 v186, 0, v186, s[100:101]
	v_cmp_ne_u32_e32 vcc, v185, v173
	v_cmp_ne_u32_e64 s[98:99], v184, v173
	v_cmp_ne_u32_e64 s[100:101], v179, v173
	v_cndmask_b32_e32 v185, 0, v185, vcc
	v_cndmask_b32_e64 v184, 0, v184, s[98:99]
	v_cndmask_b32_e64 v179, 0, v179, s[100:101]
	v_cmp_ne_u32_e32 vcc, v171, v173
	v_cmp_ne_u32_e64 s[98:99], v183, v173
	v_cmp_ne_u32_e64 s[100:101], v188, v173
	v_cndmask_b32_e32 v189, 0, v171, vcc
	v_max3_u32 v171, v178, v182, v186
	v_max3_u32 v171, v171, v185, v184
	v_cndmask_b32_e64 v183, 0, v183, s[98:99]
	v_max3_u32 v171, v171, v179, v189
	v_cndmask_b32_e64 v188, 0, v188, s[100:101]
	v_cmp_ne_u32_e32 vcc, v187, v173
	v_max3_u32 v171, v171, v183, v188
	v_cmp_ne_u32_e64 s[98:99], v181, v173
	v_cndmask_b32_e32 v187, 0, v187, vcc
	v_cmp_ne_u32_e64 s[100:101], v180, v173
	v_cndmask_b32_e64 v181, 0, v181, s[98:99]
	v_max3_u32 v171, v171, v187, v181
	v_cndmask_b32_e64 v180, 0, v180, s[100:101]
	v_cmp_ne_u32_e32 vcc, v177, v173
	s_nop 0
	s_nop 0
	v_cndmask_b32_e32 v177, 0, v177, vcc
	v_max3_u32 v171, v171, v180, v177
	v_mov_b32_e32 v190, v171
	s_nop 1
	v_permlane16_swap_b32 v171, v190
	s_nop 1
	s_waitcnt lgkmcnt(0)
	v_max_u32_e32 v171, v171, v190
	v_mov_b32_e32 v190, v171
	s_nop 1
	v_permlane32_swap_b32 v171, v190
	s_nop 1
	s_waitcnt lgkmcnt(0)
	v_max_u32_e32 v171, v171, v190
	v_cmp_ne_u32_e32 vcc, v182, v171
	s_nop 1
	v_cndmask_b32_e32 v182, 0, v182, vcc
	v_max_u32_e32 v190, v178, v182
	v_cmp_eq_u32_e32 vcc, v178, v171
	s_nop 1
	v_cndmask_b32_e32 v178, v190, v182, vcc
	v_max_u32_e32 v182, v178, v186
	v_cmp_eq_u32_e32 vcc, v186, v171
	s_nop 1
	v_cndmask_b32_e32 v178, v182, v178, vcc
	v_max_u32_e32 v182, v178, v185
	v_cmp_eq_u32_e32 vcc, v185, v171
	s_nop 1
	v_cndmask_b32_e32 v178, v182, v178, vcc
	v_max_u32_e32 v182, v178, v184
	v_cmp_eq_u32_e32 vcc, v184, v171
	s_nop 1
	v_cndmask_b32_e32 v178, v182, v178, vcc
	v_max_u32_e32 v182, v178, v179
	v_cmp_eq_u32_e32 vcc, v179, v171
	s_nop 1
	v_cndmask_b32_e32 v178, v182, v178, vcc
	v_max_u32_e32 v179, v178, v189
	v_cmp_eq_u32_e32 vcc, v189, v171
	s_nop 1
	v_cndmask_b32_e32 v178, v179, v178, vcc
	v_max_u32_e32 v179, v178, v183
	v_cmp_eq_u32_e32 vcc, v183, v171
	s_nop 1
	v_cndmask_b32_e32 v178, v179, v178, vcc
	v_max_u32_e32 v179, v178, v188
	v_cmp_eq_u32_e32 vcc, v188, v171
	s_nop 1
	v_cndmask_b32_e32 v178, v179, v178, vcc
	v_max_u32_e32 v179, v178, v187
	v_cmp_eq_u32_e32 vcc, v187, v171
	s_nop 1
	v_cndmask_b32_e32 v178, v179, v178, vcc
	v_max_u32_e32 v179, v178, v181
	v_cmp_eq_u32_e32 vcc, v181, v171
	s_nop 1
	v_cndmask_b32_e32 v178, v179, v178, vcc
	v_max_u32_e32 v179, v178, v180
	v_cmp_eq_u32_e32 vcc, v180, v171
	s_nop 1
	v_cndmask_b32_e32 v178, v179, v178, vcc
	v_max_u32_e32 v179, v178, v177
	v_cmp_eq_u32_e32 vcc, v177, v171
	s_nop 1
	v_cndmask_b32_e32 v177, v179, v178, vcc
	v_mov_b32_e32 v178, v177
	s_nop 1
	v_permlane16_swap_b32 v177, v178
	s_nop 1
	s_waitcnt lgkmcnt(0)
	v_max_u32_e32 v177, v177, v178
	ds_bpermute_b32 v178, v112, v177
	s_and_saveexec_b64 s[0:1], s[6:7]
	s_cbranch_execz .LBB0_1281
	v_and_b32_e32 v181, 0x7f, v147
	v_and_b32_e32 v180, 0x7f, v16
	v_and_b32_e32 v1, 0x7f, v1
	v_and_b32_e32 v0, 0x7f, v0
	v_and_b32_e32 v183, 0x7f, v149
	v_and_b32_e32 v182, 0x7f, v148
	v_and_b32_e32 v3, 0x7f, v3
	v_and_b32_e32 v2, 0x7f, v2
	ds_write_b128 v110, v[180:183]
	ds_write_b128 v110, v[0:3] offset:64
	v_and_b32_e32 v1, 0x7f, v151
	v_and_b32_e32 v0, 0x7f, v150
	v_and_b32_e32 v3, 0x7f, v153
	v_and_b32_e32 v2, 0x7f, v152
	v_and_b32_e32 v5, 0x7f, v5
	v_and_b32_e32 v4, 0x7f, v4
	v_and_b32_e32 v7, 0x7f, v7
	v_and_b32_e32 v6, 0x7f, v6
	ds_write_b128 v110, v[0:3] offset:16
	ds_write_b128 v110, v[4:7] offset:80
	v_and_b32_e32 v1, 0x7f, v155
	v_and_b32_e32 v0, 0x7f, v154
	v_and_b32_e32 v3, 0x7f, v157
	v_and_b32_e32 v2, 0x7f, v156
	v_and_b32_e32 v5, 0x7f, v9
	v_and_b32_e32 v4, 0x7f, v8
	v_and_b32_e32 v7, 0x7f, v11
	v_and_b32_e32 v6, 0x7f, v10
	ds_write_b128 v110, v[0:3] offset:32
	ds_write_b128 v110, v[4:7] offset:96
	v_and_b32_e32 v1, 0x7f, v159
	v_and_b32_e32 v0, 0x7f, v158
	v_and_b32_e32 v3, 0x7f, v161
	v_and_b32_e32 v2, 0x7f, v160
	v_and_b32_e32 v5, 0x7f, v13
	v_and_b32_e32 v4, 0x7f, v12
	v_and_b32_e32 v7, 0x7f, v15
	v_and_b32_e32 v6, 0x7f, v14
	ds_write_b128 v110, v[0:3] offset:48
	ds_write_b128 v110, v[4:7] offset:112

; DI unsigned xb_ld(unsigned* q) { return __hip_atomic_load(q, __ATOMIC_RELAXED, __HIP_MEMORY_SCOPE_AGENT); }
; DI unsigned xb_add(unsigned* q, unsigned v) { return __hip_atomic_fetch_add(q, v, __ATOMIC_RELAXED, __HIP_MEMORY_SCOPE_AGENT); }
; #define XB_SPIN(cond, bar) do { unsigned _sp = 0; while (cond) { __builtin_amdgcn_s_sleep(1); \
;     if ((++_sp & 255u) == 0u) { if (xb_ld(&(bar)[XB_TMO])) break; if (_sp > XB_SPIN_CAP) { atomicAdd(&(bar)[XB_TMO], 1u); break; } } } } while (0)
; DI void xcd_barrier(const XcdBarrier& b) {
;     ...
;     const unsigned old = xb_add(&bar[XB_XSUB(b.x)], 1u);
;     const unsigned gen = old / nloc;
;     if (old + 1u == (gen + 1u) * nloc) {
;       __builtin_amdgcn_fence(__ATOMIC_RELEASE, "agent");
;       asm volatile("s_waitcnt vmcnt(0)" ::: "memory");
;       const unsigned og = xb_add(&bar[XB_TOP], 1u);
;       const unsigned tg = og / nx;
;       if (og + 1u == (tg + 1u) * nx) xb_add(&bar[XB_TOPGEN], 1u);
;       else XB_SPIN(xb_ld(&bar[XB_TOPGEN]) == tg, bar);
;       __builtin_amdgcn_fence(__ATOMIC_ACQUIRE, "agent");
;       xb_add(&bar[XB_XGEN(b.x)], 1u);
; __global__ void __launch_bounds__(256, 2) mega(Params pk) {
;     ...
;     for (int k = 0; gw + k * nw < MT && k < 17; ++k) peer_u_wave(p, gw + k * nw, wlw + k * 128);
;     __builtin_amdgcn_s_waitcnt(0xc07f);
;     __builtin_amdgcn_wave_barrier();
;     for (int g = 0; (g * 4) * nw + gw < MT && g < 5; ++g) peer_v_group(p, gw, nw, g, wlw);
.LBB0_1357:
	s_or_b64 exec, exec, s[14:15]
	s_waitcnt lgkmcnt(0)
	s_waitcnt vmcnt(0)
	s_barrier
	v_readlane_b32 s92, v255, 0
	v_readlane_b32 s93, v255, 1
	s_mov_b64 s[90:91], exec
	s_and_b64 exec, exec, s[92:93]
	s_cbranch_execz .Lgb_skip
	v_mov_b32_e32 v222, 0x101e8
	ds_read_b64 v[224:225], v222
	v_mov_b32_e32 v222, 0x10200
	ds_read_b64 v[226:227], v222
	s_getreg_b32 s92, hwreg(HW_REG_XCC_ID, 0, 4)
	s_lshl_b32 s92, s92, 8
	s_add_u32 s92, s92, 0x480
	s_mov_b32 s93, 0
	s_mov_b64 s[88:89], 0x3400
	v_mov_b32_e32 v222, 1
	s_waitcnt lgkmcnt(0)
	v_lshl_add_u64 v[228:229], v[224:225], 0, s[92:93]
	v_lshl_add_u64 v[230:231], v[224:225], 0, s[88:89]
	flat_atomic_add v223, v[228:229], v222 sc0
	s_waitcnt vmcnt(0) lgkmcnt(0)
	v_readfirstlane_b32 s92, v223
	v_readfirstlane_b32 s93, v226
	s_nop 3
	s_add_u32 s92, s92, 1
	s_cmp_lg_u32 s92, s93
	s_cbranch_scc1 .Lgb_spin
	buffer_wbl2 sc1
	s_waitcnt vmcnt(0)
	flat_atomic_add v223, v[230:231], v222 offset:128 sc0
	s_waitcnt vmcnt(0) lgkmcnt(0)
	v_readfirstlane_b32 s92, v223
	v_readfirstlane_b32 s93, v227
	s_nop 3
	s_add_u32 s92, s92, 1
	s_cmp_lg_u32 s92, s93
	s_cbranch_scc1 .Lgb_spin
	flat_atomic_add v[230:231], v222 offset:384
	s_waitcnt vmcnt(0) lgkmcnt(0)
.Lgb_spin:
	s_sleep 1
	flat_load_dword v223, v[230:231] offset:384 sc1
	s_waitcnt vmcnt(0) lgkmcnt(0)
	v_readfirstlane_b32 s92, v223
	s_nop 3
	s_cmp_eq_u32 s92, 0
	s_cbranch_scc1 .Lgb_spin
	buffer_inv sc1
